# v11 + pure 32-MFMA bursts in GEMM super-phases: removed s_setprio 1/0 bracket and the redundant lgkmcnt(0) after the barrier
# speedup vs baseline: 1.0050x; 1.0034x over previous
; #define PG8_STAGE(bufoff, gbase, voff) do { _Pragma("unroll") for (int _i = 0; _i < 2; ++_i) \
;         __builtin_amdgcn_global_load_lds((const unsigned*)((const char*)(gbase) + (voff)[_i]), (PG8_LAS unsigned*)(lds + (bufoff) + ldsw + _i * 8192), 16, 0, 0); } while (0)
; #define PG8_LDA(dst, b, h) do { _Pragma("unroll") for (int m = 0; m < 4; ++m) _Pragma("unroll") for (int k = 0; k < 2; ++k) dst[m][k] = *(const PG8_LAS bf16x8*)(lds + PG8_SA(b, h) + aoff + m * 2048 + k * 1024); } while (0)
; #define PG8_LDB(dst, b, h) do { _Pragma("unroll") for (int n = 0; n < 2; ++n) _Pragma("unroll") for (int k = 0; k < 2; ++k) dst[n][k] = *(const PG8_LAS bf16x8*)(lds + PG8_SB(b, h) + boff + n * 2048 + k * 1024); } while (0)
; #define PG8_MMA(ai, bj, At, Bt) do { __builtin_amdgcn_s_setprio(1); _Pragma("unroll") for (int m = 0; m < 4; ++m) _Pragma("unroll") for (int n = 0; n < 2; ++n) _Pragma("unroll") for (int k = 0; k < 2; ++k) \
;         acc[ai][bj][m][n] = __builtin_amdgcn_mfma_f32_16x16x32_bf16(Bt[n][k], At[m][k], acc[ai][bj][m][n], 0, 0, 0); __builtin_amdgcn_s_setprio(0); } while (0)
; #define PG8_WAIT_V(n) asm volatile("s_waitcnt vmcnt(" #n ")" ::: "memory")
; #define PG8_BAR __builtin_amdgcn_s_barrier()
; template <class Epi, class Sched, bool ALIGN_EPI = false, bool SP2 = false>
; __device__ __forceinline__ void gemm_phase(PG8_LAS unsigned char* lds, const Gemm g, const Sched& S, const Epi& E) {
;     ...
;             const bool last = (t == nt - 2);
;             const char* a1 = cA + (size_t)(t + 1) * kstep;
;             const char* a2 = last ? nA : cA + (size_t)(t + 2) * kstep; const char* b2 = last ? nB : cB + (size_t)(t + 2) * kstep;
;             const char* a3 = a2 + kstep; const char* b3 = b2 + kstep;
;             if (last && has_next) S.a_ready(nxt);
;             if (last) E.prefetch(lds + 139264, cur, wid, lane);
;             if constexpr (SP2) {
;             PG8_LDB(B0, 0, 0); PG8_LDB(B1, 0, 1); PG8_SCHED; PG8_LDA(At, 0, 0); PG8_STAGE(PG8_SA(1, 1), a1 + hstep, voffA);
;             PG8_WAIT_V(8); PG8_WAIT_L(0); PG8_BAR; PG8_MMA(0, 0, At, B0); PG8_MMA(0, 1, At, B1); PG8_BAR; PG8_SCHED;
;             PG8_LDA(At, 0, 1); PG8_STAGE(PG8_SB(0, 0), b2, voffB); PG8_STAGE(PG8_SB(0, 1), b2 + hstep, voffB); PG8_STAGE(PG8_SA(0, 0), a2, voffA);
;             PG8_WAIT_V(8); PG8_WAIT_L(0); PG8_BAR; PG8_MMA(1, 0, At, B0); PG8_MMA(1, 1, At, B1); PG8_BAR; PG8_SCHED;
.LBB0_510:
	ds_read_b128 v[128:131], v184
	ds_read_b128 v[148:151], v184 offset:1024
	ds_read_b128 v[152:155], v184 offset:2048
	ds_read_b128 v[158:161], v184 offset:3072
	ds_read_b128 v[190:193], v185
	ds_read_b128 v[194:197], v185 offset:1024
	ds_read_b128 v[198:201], v185 offset:2048
	ds_read_b128 v[202:205], v185 offset:3072
	s_add_u32 s34, s10, 0xfffc0080
	s_addc_u32 s35, s11, -1
	s_cmp_eq_u32 vcc_lo, 12
	s_cselect_b32 s69, s57, s35
	s_cselect_b32 s68, s63, s34
	s_cselect_b32 s67, s55, s97
	s_cselect_b32 s66, s95, s96
	s_add_i32 m0, s65, 0xc000
	ds_read_b128 v[206:209], v186
	ds_read_b128 v[210:213], v186 offset:1024
	ds_read_b128 v[214:217], v186 offset:2048
	ds_read_b128 v[218:221], v186 offset:3072
	ds_read_b128 v[222:225], v186 offset:4096
	ds_read_b128 v[226:229], v186 offset:5120
	ds_read_b128 v[230:233], v186 offset:6144
	ds_read_b128 v[234:237], v186 offset:7168
	global_load_lds_dwordx4 v142, s[10:11]
	s_add_i32 m0, s65, 0xe000
	s_nop 0
	global_load_lds_dwordx4 v140, s[10:11]
	s_waitcnt vmcnt(8)
	s_waitcnt lgkmcnt(0)
	s_barrier
	v_mfma_f32_16x16x32_bf16 v[124:127], v[128:131], v[206:209], v[124:127]
	v_mfma_f32_16x16x32_bf16 v[124:127], v[148:151], v[210:213], v[124:127]
	v_mfma_f32_16x16x32_bf16 v[120:123], v[152:155], v[206:209], v[120:123]
	v_mfma_f32_16x16x32_bf16 v[120:123], v[158:161], v[210:213], v[120:123]
	v_mfma_f32_16x16x32_bf16 v[104:107], v[152:155], v[214:217], v[104:107]
	v_mfma_f32_16x16x32_bf16 v[104:107], v[158:161], v[218:221], v[104:107]
	v_mfma_f32_16x16x32_bf16 v[108:111], v[128:131], v[214:217], v[108:111]
	v_mfma_f32_16x16x32_bf16 v[108:111], v[148:151], v[218:221], v[108:111]
	v_mfma_f32_16x16x32_bf16 v[92:95], v[128:131], v[222:225], v[92:95]
	v_mfma_f32_16x16x32_bf16 v[92:95], v[148:151], v[226:229], v[92:95]
	v_mfma_f32_16x16x32_bf16 v[88:91], v[152:155], v[222:225], v[88:91]
	v_mfma_f32_16x16x32_bf16 v[88:91], v[158:161], v[226:229], v[88:91]
	v_mfma_f32_16x16x32_bf16 v[72:75], v[152:155], v[230:233], v[72:75]
	v_mfma_f32_16x16x32_bf16 v[72:75], v[158:161], v[234:237], v[72:75]
	v_mfma_f32_16x16x32_bf16 v[76:79], v[128:131], v[230:233], v[76:79]
	v_mfma_f32_16x16x32_bf16 v[76:79], v[148:151], v[234:237], v[76:79]
	v_mfma_f32_16x16x32_bf16 v[116:119], v[190:193], v[206:209], v[116:119]
	v_mfma_f32_16x16x32_bf16 v[116:119], v[194:197], v[210:213], v[116:119]
	v_mfma_f32_16x16x32_bf16 v[112:115], v[198:201], v[206:209], v[112:115]
	v_mfma_f32_16x16x32_bf16 v[112:115], v[202:205], v[210:213], v[112:115]
	v_mfma_f32_16x16x32_bf16 v[96:99], v[198:201], v[214:217], v[96:99]
	v_mfma_f32_16x16x32_bf16 v[96:99], v[202:205], v[218:221], v[96:99]
	v_mfma_f32_16x16x32_bf16 v[100:103], v[190:193], v[214:217], v[100:103]
	v_mfma_f32_16x16x32_bf16 v[100:103], v[194:197], v[218:221], v[100:103]
	v_mfma_f32_16x16x32_bf16 v[84:87], v[190:193], v[222:225], v[84:87]
	v_mfma_f32_16x16x32_bf16 v[84:87], v[194:197], v[226:229], v[84:87]
	v_mfma_f32_16x16x32_bf16 v[80:83], v[198:201], v[222:225], v[80:83]
	v_mfma_f32_16x16x32_bf16 v[80:83], v[202:205], v[226:229], v[80:83]
	v_mfma_f32_16x16x32_bf16 v[64:67], v[198:201], v[230:233], v[64:67]
	v_mfma_f32_16x16x32_bf16 v[64:67], v[202:205], v[234:237], v[64:67]
	v_mfma_f32_16x16x32_bf16 v[68:71], v[190:193], v[230:233], v[68:71]
	v_mfma_f32_16x16x32_bf16 v[68:71], v[194:197], v[234:237], v[68:71]
	s_barrier
	s_add_i32 s34, s84, s71
	s_mov_b32 m0, s34
	ds_read_b128 v[206:209], v186 offset:16384
	ds_read_b128 v[210:213], v186 offset:17408
	ds_read_b128 v[214:217], v186 offset:18432
	ds_read_b128 v[218:221], v186 offset:19456
	ds_read_b128 v[222:225], v186 offset:20480
	ds_read_b128 v[226:229], v186 offset:21504
	ds_read_b128 v[230:233], v186 offset:22528
	ds_read_b128 v[234:237], v186 offset:23552
	global_load_lds_dwordx4 v134, s[66:67]
	s_add_i32 m0, s34, 0x2000
	s_add_u32 s34, s66, 0x40000
	s_addc_u32 s35, s67, 0
	s_add_i32 vcc_hi, s85, s71
	global_load_lds_dwordx4 v138, s[66:67]
	s_mov_b32 m0, vcc_hi
	s_nop 0
	global_load_lds_dwordx4 v134, s[34:35]
	s_add_i32 m0, vcc_hi, 0x2000
	s_nop 0
	global_load_lds_dwordx4 v138, s[34:35]
	s_mov_b32 m0, s65
	s_nop 0
	global_load_lds_dwordx4 v132, s[68:69]
	s_mov_b32 m0, s73
	s_nop 0
	global_load_lds_dwordx4 v136, s[68:69]
	s_waitcnt vmcnt(8)
	s_waitcnt lgkmcnt(0)
	s_barrier
	v_mfma_f32_16x16x32_bf16 v[60:63], v[128:131], v[206:209], v[60:63]
	v_mfma_f32_16x16x32_bf16 v[60:63], v[148:151], v[210:213], v[60:63]
	v_mfma_f32_16x16x32_bf16 v[56:59], v[152:155], v[206:209], v[56:59]
	v_mfma_f32_16x16x32_bf16 v[56:59], v[158:161], v[210:213], v[56:59]
	v_mfma_f32_16x16x32_bf16 v[40:43], v[152:155], v[214:217], v[40:43]
	v_mfma_f32_16x16x32_bf16 v[40:43], v[158:161], v[218:221], v[40:43]
	v_mfma_f32_16x16x32_bf16 v[44:47], v[128:131], v[214:217], v[44:47]
	v_mfma_f32_16x16x32_bf16 v[44:47], v[148:151], v[218:221], v[44:47]
	v_mfma_f32_16x16x32_bf16 v[28:31], v[128:131], v[222:225], v[28:31]
	v_mfma_f32_16x16x32_bf16 v[28:31], v[148:151], v[226:229], v[28:31]
	v_mfma_f32_16x16x32_bf16 v[24:27], v[152:155], v[222:225], v[24:27]
	v_mfma_f32_16x16x32_bf16 v[24:27], v[158:161], v[226:229], v[24:27]
	v_mfma_f32_16x16x32_bf16 v[8:11], v[152:155], v[230:233], v[8:11]
	v_mfma_f32_16x16x32_bf16 v[8:11], v[158:161], v[234:237], v[8:11]
	v_mfma_f32_16x16x32_bf16 v[12:15], v[128:131], v[230:233], v[12:15]
	v_mfma_f32_16x16x32_bf16 v[12:15], v[148:151], v[234:237], v[12:15]
	v_mfma_f32_16x16x32_bf16 v[52:55], v[190:193], v[206:209], v[52:55]
	v_mfma_f32_16x16x32_bf16 v[52:55], v[194:197], v[210:213], v[52:55]
	v_mfma_f32_16x16x32_bf16 v[48:51], v[198:201], v[206:209], v[48:51]
	v_mfma_f32_16x16x32_bf16 v[48:51], v[202:205], v[210:213], v[48:51]
	v_mfma_f32_16x16x32_bf16 v[32:35], v[198:201], v[214:217], v[32:35]
	v_mfma_f32_16x16x32_bf16 v[32:35], v[202:205], v[218:221], v[32:35]
	v_mfma_f32_16x16x32_bf16 v[36:39], v[190:193], v[214:217], v[36:39]
	v_mfma_f32_16x16x32_bf16 v[36:39], v[194:197], v[218:221], v[36:39]
	v_mfma_f32_16x16x32_bf16 v[20:23], v[190:193], v[222:225], v[20:23]
	v_mfma_f32_16x16x32_bf16 v[20:23], v[194:197], v[226:229], v[20:23]
	v_mfma_f32_16x16x32_bf16 v[16:19], v[198:201], v[222:225], v[16:19]
	v_mfma_f32_16x16x32_bf16 v[16:19], v[202:205], v[226:229], v[16:19]
	v_mfma_f32_16x16x32_bf16 v[0:3], v[198:201], v[230:233], v[0:3]
	v_mfma_f32_16x16x32_bf16 v[0:3], v[202:205], v[234:237], v[0:3]
	v_mfma_f32_16x16x32_bf16 v[4:7], v[190:193], v[230:233], v[4:7]
	v_mfma_f32_16x16x32_bf16 v[4:7], v[194:197], v[234:237], v[4:7]
	s_barrier
; #define PG8_STAGE(bufoff, gbase, voff) do { _Pragma("unroll") for (int _i = 0; _i < 2; ++_i) \
;         __builtin_amdgcn_global_load_lds((const unsigned*)((const char*)(gbase) + (voff)[_i]), (PG8_LAS unsigned*)(lds + (bufoff) + ldsw + _i * 8192), 16, 0, 0); } while (0)
; #define PG8_LDA(dst, b, h) do { _Pragma("unroll") for (int m = 0; m < 4; ++m) _Pragma("unroll") for (int k = 0; k < 2; ++k) dst[m][k] = *(const PG8_LAS bf16x8*)(lds + PG8_SA(b, h) + aoff + m * 2048 + k * 1024); } while (0)
; #define PG8_LDB(dst, b, h) do { _Pragma("unroll") for (int n = 0; n < 2; ++n) _Pragma("unroll") for (int k = 0; k < 2; ++k) dst[n][k] = *(const PG8_LAS bf16x8*)(lds + PG8_SB(b, h) + boff + n * 2048 + k * 1024); } while (0)
; #define PG8_MMA(ai, bj, At, Bt) do { __builtin_amdgcn_s_setprio(1); _Pragma("unroll") for (int m = 0; m < 4; ++m) _Pragma("unroll") for (int n = 0; n < 2; ++n) _Pragma("unroll") for (int k = 0; k < 2; ++k) \
;         acc[ai][bj][m][n] = __builtin_amdgcn_mfma_f32_16x16x32_bf16(Bt[n][k], At[m][k], acc[ai][bj][m][n], 0, 0, 0); __builtin_amdgcn_s_setprio(0); } while (0)
; #define PG8_WAIT_V(n) asm volatile("s_waitcnt vmcnt(" #n ")" ::: "memory")
; #define PG8_WAIT_L(n) asm volatile("s_waitcnt lgkmcnt(" #n ")" ::: "memory")
; #define PG8_BAR __builtin_amdgcn_s_barrier()
; #define PG8_SCHED __builtin_amdgcn_sched_barrier(0)
; template <class Epi, class Sched, bool ALIGN_EPI = false, bool SP2 = false>
; __device__ __forceinline__ void gemm_phase(PG8_LAS unsigned char* lds, const Gemm g, const Sched& S, const Epi& E) {
;     ...
;             PG8_LDB(B0, 1, 0); PG8_LDB(B1, 1, 1); PG8_SCHED; PG8_LDA(At, 1, 0); PG8_STAGE(PG8_SA(0, 1), a2 + hstep, voffA);
;             PG8_WAIT_V(8); PG8_WAIT_L(0); PG8_BAR; PG8_MMA(0, 0, At, B0); PG8_MMA(0, 1, At, B1); PG8_BAR; PG8_SCHED;
;             PG8_LDA(At, 1, 1); PG8_STAGE(PG8_SB(1, 0), b3, voffB); PG8_STAGE(PG8_SB(1, 1), b3 + hstep, voffB); PG8_STAGE(PG8_SA(1, 0), a3, voffA);
;             PG8_WAIT_V(8); PG8_WAIT_L(0); PG8_BAR; PG8_MMA(1, 0, At, B0); PG8_MMA(1, 1, At, B1); PG8_BAR; PG8_SCHED;
;     ...
;         if constexpr (ALIGN_EPI) { if (wr == 0) PG8_BAR; }
	s_add_i32 vcc_hi, 0, 0x18000
	s_add_i32 s14, 0, 0x1c000
	v_add_u32_e32 v158, vcc_hi, v163
	v_add_u32_e32 v202, s14, v163
	ds_read_b128 v[128:131], v158
	ds_read_b128 v[148:151], v158 offset:1024
	ds_read_b128 v[152:155], v158 offset:2048
	ds_read_b128 v[158:161], v158 offset:3072
	ds_read_b128 v[190:193], v202
	ds_read_b128 v[194:197], v202 offset:1024
	ds_read_b128 v[198:201], v202 offset:2048
	ds_read_b128 v[202:205], v202 offset:3072
	s_add_u32 s34, s68, 0x40000
	s_addc_u32 s35, s69, 0
	s_mov_b32 m0, s74
	ds_read_b128 v[206:209], v186 offset:32768
	ds_read_b128 v[210:213], v186 offset:33792
	ds_read_b128 v[214:217], v186 offset:34816
	ds_read_b128 v[218:221], v186 offset:35840
	ds_read_b128 v[222:225], v186 offset:36864
	ds_read_b128 v[226:229], v186 offset:37888
	ds_read_b128 v[230:233], v186 offset:38912
	ds_read_b128 v[234:237], v186 offset:39936
	global_load_lds_dwordx4 v132, s[34:35]
	s_mov_b32 m0, s75
	s_nop 0
	global_load_lds_dwordx4 v136, s[34:35]
	s_waitcnt vmcnt(8)
	s_waitcnt lgkmcnt(0)
	s_barrier
	v_mfma_f32_16x16x32_bf16 v[124:127], v[128:131], v[206:209], v[124:127]
	v_mfma_f32_16x16x32_bf16 v[124:127], v[148:151], v[210:213], v[124:127]
	v_mfma_f32_16x16x32_bf16 v[120:123], v[152:155], v[206:209], v[120:123]
	v_mfma_f32_16x16x32_bf16 v[120:123], v[158:161], v[210:213], v[120:123]
	v_mfma_f32_16x16x32_bf16 v[104:107], v[152:155], v[214:217], v[104:107]
	v_mfma_f32_16x16x32_bf16 v[104:107], v[158:161], v[218:221], v[104:107]
	v_mfma_f32_16x16x32_bf16 v[108:111], v[128:131], v[214:217], v[108:111]
	v_mfma_f32_16x16x32_bf16 v[108:111], v[148:151], v[218:221], v[108:111]
	v_mfma_f32_16x16x32_bf16 v[92:95], v[128:131], v[222:225], v[92:95]
	v_mfma_f32_16x16x32_bf16 v[92:95], v[148:151], v[226:229], v[92:95]
	v_mfma_f32_16x16x32_bf16 v[88:91], v[152:155], v[222:225], v[88:91]
	v_mfma_f32_16x16x32_bf16 v[88:91], v[158:161], v[226:229], v[88:91]
	v_mfma_f32_16x16x32_bf16 v[72:75], v[152:155], v[230:233], v[72:75]
	v_mfma_f32_16x16x32_bf16 v[72:75], v[158:161], v[234:237], v[72:75]
	v_mfma_f32_16x16x32_bf16 v[76:79], v[128:131], v[230:233], v[76:79]
	v_mfma_f32_16x16x32_bf16 v[76:79], v[148:151], v[234:237], v[76:79]
	v_mfma_f32_16x16x32_bf16 v[116:119], v[190:193], v[206:209], v[116:119]
	v_mfma_f32_16x16x32_bf16 v[116:119], v[194:197], v[210:213], v[116:119]
	v_mfma_f32_16x16x32_bf16 v[112:115], v[198:201], v[206:209], v[112:115]
	v_mfma_f32_16x16x32_bf16 v[112:115], v[202:205], v[210:213], v[112:115]
	v_mfma_f32_16x16x32_bf16 v[96:99], v[198:201], v[214:217], v[96:99]
	v_mfma_f32_16x16x32_bf16 v[96:99], v[202:205], v[218:221], v[96:99]
	v_mfma_f32_16x16x32_bf16 v[100:103], v[190:193], v[214:217], v[100:103]
	v_mfma_f32_16x16x32_bf16 v[100:103], v[194:197], v[218:221], v[100:103]
	v_mfma_f32_16x16x32_bf16 v[84:87], v[190:193], v[222:225], v[84:87]
	v_mfma_f32_16x16x32_bf16 v[84:87], v[194:197], v[226:229], v[84:87]
	v_mfma_f32_16x16x32_bf16 v[80:83], v[198:201], v[222:225], v[80:83]
	v_mfma_f32_16x16x32_bf16 v[80:83], v[202:205], v[226:229], v[80:83]
	v_mfma_f32_16x16x32_bf16 v[64:67], v[198:201], v[230:233], v[64:67]
	v_mfma_f32_16x16x32_bf16 v[64:67], v[202:205], v[234:237], v[64:67]
	v_mfma_f32_16x16x32_bf16 v[68:71], v[190:193], v[230:233], v[68:71]
	v_mfma_f32_16x16x32_bf16 v[68:71], v[194:197], v[234:237], v[68:71]
	s_barrier
	s_add_i32 s15, vcc_hi, s71
	s_add_u32 s98, s66, s42
	s_addc_u32 s99, s67, s43
	s_add_u32 s100, s68, s42
	s_addc_u32 s101, s69, s43
	s_mov_b32 m0, s15
	ds_read_b128 v[206:209], v186 offset:49152
	ds_read_b128 v[210:213], v186 offset:50176
	ds_read_b128 v[214:217], v186 offset:51200
	ds_read_b128 v[218:221], v186 offset:52224
	ds_read_b128 v[222:225], v186 offset:53248
	ds_read_b128 v[226:229], v186 offset:54272
	ds_read_b128 v[230:233], v186 offset:55296
	ds_read_b128 v[234:237], v186 offset:56320
	global_load_lds_dwordx4 v134, s[98:99]
	s_add_i32 m0, s15, 0x2000
	s_add_u32 s34, s66, 0x40080
	s_addc_u32 s35, s67, 0
	s_add_i32 s14, s14, s71
	global_load_lds_dwordx4 v138, s[98:99]
	s_mov_b32 m0, s14
	s_nop 0
	global_load_lds_dwordx4 v134, s[34:35]
	s_add_i32 m0, s14, 0x2000
	s_nop 0
	global_load_lds_dwordx4 v138, s[34:35]
	s_mov_b32 m0, s78
	s_nop 0
	global_load_lds_dwordx4 v132, s[100:101]
	s_mov_b32 m0, s79
	s_nop 0
	global_load_lds_dwordx4 v136, s[100:101]
	s_waitcnt vmcnt(8)
	s_waitcnt lgkmcnt(0)
	s_barrier
	v_mfma_f32_16x16x32_bf16 v[60:63], v[128:131], v[206:209], v[60:63]
	v_mfma_f32_16x16x32_bf16 v[60:63], v[148:151], v[210:213], v[60:63]
	v_mfma_f32_16x16x32_bf16 v[56:59], v[152:155], v[206:209], v[56:59]
	v_mfma_f32_16x16x32_bf16 v[56:59], v[158:161], v[210:213], v[56:59]
	v_mfma_f32_16x16x32_bf16 v[40:43], v[152:155], v[214:217], v[40:43]
	v_mfma_f32_16x16x32_bf16 v[40:43], v[158:161], v[218:221], v[40:43]
	v_mfma_f32_16x16x32_bf16 v[44:47], v[128:131], v[214:217], v[44:47]
	v_mfma_f32_16x16x32_bf16 v[44:47], v[148:151], v[218:221], v[44:47]
	v_mfma_f32_16x16x32_bf16 v[28:31], v[128:131], v[222:225], v[28:31]
	v_mfma_f32_16x16x32_bf16 v[28:31], v[148:151], v[226:229], v[28:31]
	v_mfma_f32_16x16x32_bf16 v[24:27], v[152:155], v[222:225], v[24:27]
	v_mfma_f32_16x16x32_bf16 v[24:27], v[158:161], v[226:229], v[24:27]
	v_mfma_f32_16x16x32_bf16 v[8:11], v[152:155], v[230:233], v[8:11]
	v_mfma_f32_16x16x32_bf16 v[8:11], v[158:161], v[234:237], v[8:11]
	v_mfma_f32_16x16x32_bf16 v[12:15], v[128:131], v[230:233], v[12:15]
	v_mfma_f32_16x16x32_bf16 v[12:15], v[148:151], v[234:237], v[12:15]
	v_mfma_f32_16x16x32_bf16 v[52:55], v[190:193], v[206:209], v[52:55]
	v_mfma_f32_16x16x32_bf16 v[52:55], v[194:197], v[210:213], v[52:55]
	v_mfma_f32_16x16x32_bf16 v[48:51], v[198:201], v[206:209], v[48:51]
	v_mfma_f32_16x16x32_bf16 v[48:51], v[202:205], v[210:213], v[48:51]
	v_mfma_f32_16x16x32_bf16 v[32:35], v[198:201], v[214:217], v[32:35]
	v_mfma_f32_16x16x32_bf16 v[32:35], v[202:205], v[218:221], v[32:35]
	v_mfma_f32_16x16x32_bf16 v[36:39], v[190:193], v[214:217], v[36:39]
	v_mfma_f32_16x16x32_bf16 v[36:39], v[194:197], v[218:221], v[36:39]
	v_mfma_f32_16x16x32_bf16 v[20:23], v[190:193], v[222:225], v[20:23]
	v_mfma_f32_16x16x32_bf16 v[20:23], v[194:197], v[226:229], v[20:23]
	v_mfma_f32_16x16x32_bf16 v[16:19], v[198:201], v[222:225], v[16:19]
	v_mfma_f32_16x16x32_bf16 v[16:19], v[202:205], v[226:229], v[16:19]
	v_mfma_f32_16x16x32_bf16 v[0:3], v[198:201], v[230:233], v[0:3]
	v_mfma_f32_16x16x32_bf16 v[0:3], v[202:205], v[234:237], v[0:3]
	v_mfma_f32_16x16x32_bf16 v[4:7], v[190:193], v[230:233], v[4:7]
	v_mfma_f32_16x16x32_bf16 v[4:7], v[194:197], v[234:237], v[4:7]
	s_barrier
	s_add_i32 vcc_lo, vcc_lo, 2
	s_add_u32 s96, s96, 0x100
	s_addc_u32 s97, s97, 0
	s_add_u32 s10, s10, 0x100
	s_addc_u32 s11, s11, 0
	s_cmp_gt_u32 vcc_lo, 13
	s_cbranch_scc0 .LBB0_510
	s_and_b64 vcc, exec, s[44:45]
	s_cbranch_vccz .LBB0_513
	s_barrier

; #define PG8_STAGE(bufoff, gbase, voff) do { _Pragma("unroll") for (int _i = 0; _i < 2; ++_i) \
;         __builtin_amdgcn_global_load_lds((const unsigned*)((const char*)(gbase) + (voff)[_i]), (PG8_LAS unsigned*)(lds + (bufoff) + ldsw + _i * 8192), 16, 0, 0); } while (0)
; #define PG8_LDA(dst, b, h) do { _Pragma("unroll") for (int m = 0; m < 4; ++m) _Pragma("unroll") for (int k = 0; k < 2; ++k) dst[m][k] = *(const PG8_LAS bf16x8*)(lds + PG8_SA(b, h) + aoff + m * 2048 + k * 1024); } while (0)
; #define PG8_LDB(dst, b, h) do { _Pragma("unroll") for (int n = 0; n < 2; ++n) _Pragma("unroll") for (int k = 0; k < 2; ++k) dst[n][k] = *(const PG8_LAS bf16x8*)(lds + PG8_SB(b, h) + boff + n * 2048 + k * 1024); } while (0)
; #define PG8_MMA(ai, bj, At, Bt) do { __builtin_amdgcn_s_setprio(1); _Pragma("unroll") for (int m = 0; m < 4; ++m) _Pragma("unroll") for (int n = 0; n < 2; ++n) _Pragma("unroll") for (int k = 0; k < 2; ++k) \
;         acc[ai][bj][m][n] = __builtin_amdgcn_mfma_f32_16x16x32_bf16(Bt[n][k], At[m][k], acc[ai][bj][m][n], 0, 0, 0); __builtin_amdgcn_s_setprio(0); } while (0)
; #define PG8_WAIT_V(n) asm volatile("s_waitcnt vmcnt(" #n ")" ::: "memory")
; #define PG8_BAR __builtin_amdgcn_s_barrier()
; template <class Epi, class Sched, bool ALIGN_EPI = false, bool SP2 = false>
; __device__ __forceinline__ void gemm_phase(PG8_LAS unsigned char* lds, const Gemm g, const Sched& S, const Epi& E) {
;     ...
;             const bool last = (t == nt - 2);
;             const char* a1 = cA + (size_t)(t + 1) * kstep;
;             const char* a2 = last ? nA : cA + (size_t)(t + 2) * kstep; const char* b2 = last ? nB : cB + (size_t)(t + 2) * kstep;
;             const char* a3 = a2 + kstep; const char* b3 = b2 + kstep;
;             if (last && has_next) S.a_ready(nxt);
;             if (last) E.prefetch(lds + 139264, cur, wid, lane);
;             if constexpr (SP2) {
;             PG8_LDB(B0, 0, 0); PG8_LDB(B1, 0, 1); PG8_SCHED; PG8_LDA(At, 0, 0); PG8_STAGE(PG8_SA(1, 1), a1 + hstep, voffA);
;             PG8_WAIT_V(8); PG8_WAIT_L(0); PG8_BAR; PG8_MMA(0, 0, At, B0); PG8_MMA(0, 1, At, B1); PG8_BAR; PG8_SCHED;
;             PG8_LDA(At, 0, 1); PG8_STAGE(PG8_SB(0, 0), b2, voffB); PG8_STAGE(PG8_SB(0, 1), b2 + hstep, voffB); PG8_STAGE(PG8_SA(0, 0), a2, voffA);
;             PG8_WAIT_V(8); PG8_WAIT_L(0); PG8_BAR; PG8_MMA(1, 0, At, B0); PG8_MMA(1, 1, At, B1); PG8_BAR; PG8_SCHED;
.LBB0_710:
	ds_read_b128 v[128:131], v169
	ds_read_b128 v[132:135], v169 offset:1024
	ds_read_b128 v[136:139], v169 offset:2048
	ds_read_b128 v[140:143], v169 offset:3072
	ds_read_b128 v[162:165], v170
	ds_read_b128 v[172:175], v170 offset:1024
	ds_read_b128 v[176:179], v170 offset:2048
	ds_read_b128 v[184:187], v170 offset:3072
	s_add_u32 s14, s54, 0xfffc0080
	s_addc_u32 s15, s55, -1
	s_cmp_eq_u32 s84, 12
	s_cselect_b32 s59, s45, s15
	s_cselect_b32 s58, s51, s14
	s_cselect_b32 s57, s43, s83
	s_cselect_b32 s56, s53, s82
	s_add_i32 m0, s64, 0xc000
	ds_read_b128 v[188:191], v171
	ds_read_b128 v[192:195], v171 offset:1024
	ds_read_b128 v[196:199], v171 offset:2048
	ds_read_b128 v[200:203], v171 offset:3072
	ds_read_b128 v[204:207], v171 offset:4096
	ds_read_b128 v[208:211], v171 offset:5120
	ds_read_b128 v[212:215], v171 offset:6144
	ds_read_b128 v[216:219], v171 offset:7168
	global_load_lds_dwordx4 v154, s[54:55]
	s_add_i32 m0, s64, 0xe000
	s_nop 0
	global_load_lds_dwordx4 v152, s[54:55]
	s_waitcnt vmcnt(8)
	s_waitcnt lgkmcnt(0)
	s_barrier
	v_mfma_f32_16x16x32_bf16 v[124:127], v[128:131], v[188:191], v[124:127]
	v_mfma_f32_16x16x32_bf16 v[124:127], v[132:135], v[192:195], v[124:127]
	v_mfma_f32_16x16x32_bf16 v[120:123], v[136:139], v[188:191], v[120:123]
	v_mfma_f32_16x16x32_bf16 v[120:123], v[140:143], v[192:195], v[120:123]
	v_mfma_f32_16x16x32_bf16 v[108:111], v[136:139], v[196:199], v[108:111]
	v_mfma_f32_16x16x32_bf16 v[108:111], v[140:143], v[200:203], v[108:111]
	v_mfma_f32_16x16x32_bf16 v[116:119], v[128:131], v[196:199], v[116:119]
	v_mfma_f32_16x16x32_bf16 v[116:119], v[132:135], v[200:203], v[116:119]
	v_mfma_f32_16x16x32_bf16 v[100:103], v[128:131], v[204:207], v[100:103]
	v_mfma_f32_16x16x32_bf16 v[100:103], v[132:135], v[208:211], v[100:103]
	v_mfma_f32_16x16x32_bf16 v[92:95], v[136:139], v[204:207], v[92:95]
	v_mfma_f32_16x16x32_bf16 v[92:95], v[140:143], v[208:211], v[92:95]
	v_mfma_f32_16x16x32_bf16 v[76:79], v[136:139], v[212:215], v[76:79]
	v_mfma_f32_16x16x32_bf16 v[76:79], v[140:143], v[216:219], v[76:79]
	v_mfma_f32_16x16x32_bf16 v[84:87], v[128:131], v[212:215], v[84:87]
	v_mfma_f32_16x16x32_bf16 v[84:87], v[132:135], v[216:219], v[84:87]
	v_mfma_f32_16x16x32_bf16 v[112:115], v[162:165], v[188:191], v[112:115]
	v_mfma_f32_16x16x32_bf16 v[112:115], v[172:175], v[192:195], v[112:115]
	v_mfma_f32_16x16x32_bf16 v[104:107], v[176:179], v[188:191], v[104:107]
	v_mfma_f32_16x16x32_bf16 v[104:107], v[184:187], v[192:195], v[104:107]
	v_mfma_f32_16x16x32_bf16 v[88:91], v[176:179], v[196:199], v[88:91]
	v_mfma_f32_16x16x32_bf16 v[88:91], v[184:187], v[200:203], v[88:91]
	v_mfma_f32_16x16x32_bf16 v[96:99], v[162:165], v[196:199], v[96:99]
	v_mfma_f32_16x16x32_bf16 v[96:99], v[172:175], v[200:203], v[96:99]
	v_mfma_f32_16x16x32_bf16 v[80:83], v[162:165], v[204:207], v[80:83]
	v_mfma_f32_16x16x32_bf16 v[80:83], v[172:175], v[208:211], v[80:83]
	v_mfma_f32_16x16x32_bf16 v[72:75], v[176:179], v[204:207], v[72:75]
	v_mfma_f32_16x16x32_bf16 v[72:75], v[184:187], v[208:211], v[72:75]
	v_mfma_f32_16x16x32_bf16 v[64:67], v[176:179], v[212:215], v[64:67]
	v_mfma_f32_16x16x32_bf16 v[64:67], v[184:187], v[216:219], v[64:67]
	v_mfma_f32_16x16x32_bf16 v[68:71], v[162:165], v[212:215], v[68:71]
	v_mfma_f32_16x16x32_bf16 v[68:71], v[172:175], v[216:219], v[68:71]
	s_barrier
	s_add_i32 s14, s80, s63
	s_mov_b32 m0, s14
	ds_read_b128 v[188:191], v171 offset:16384
	ds_read_b128 v[192:195], v171 offset:17408
	ds_read_b128 v[196:199], v171 offset:18432
	ds_read_b128 v[200:203], v171 offset:19456
	ds_read_b128 v[204:207], v171 offset:20480
	ds_read_b128 v[208:211], v171 offset:21504
	ds_read_b128 v[212:215], v171 offset:22528
	ds_read_b128 v[216:219], v171 offset:23552
	global_load_lds_dwordx4 v146, s[56:57]
	s_add_i32 m0, s14, 0x2000
	s_add_u32 s34, s56, 0x40000
	s_addc_u32 s35, s57, 0
	s_add_i32 s14, s81, s63
	global_load_lds_dwordx4 v150, s[56:57]
	s_mov_b32 m0, s14
	s_nop 0
	global_load_lds_dwordx4 v146, s[34:35]
	s_add_i32 m0, s14, 0x2000
	s_nop 0
	global_load_lds_dwordx4 v150, s[34:35]
	s_mov_b32 m0, s64
	s_nop 0
	global_load_lds_dwordx4 v144, s[58:59]
	s_mov_b32 m0, s65
	s_nop 0
	global_load_lds_dwordx4 v148, s[58:59]
	s_waitcnt vmcnt(8)
	s_waitcnt lgkmcnt(0)
	s_barrier
	v_mfma_f32_16x16x32_bf16 v[60:63], v[128:131], v[188:191], v[60:63]
	v_mfma_f32_16x16x32_bf16 v[60:63], v[132:135], v[192:195], v[60:63]
	v_mfma_f32_16x16x32_bf16 v[56:59], v[136:139], v[188:191], v[56:59]
	v_mfma_f32_16x16x32_bf16 v[56:59], v[140:143], v[192:195], v[56:59]
	v_mfma_f32_16x16x32_bf16 v[44:47], v[136:139], v[196:199], v[44:47]
	v_mfma_f32_16x16x32_bf16 v[44:47], v[140:143], v[200:203], v[44:47]
	v_mfma_f32_16x16x32_bf16 v[48:51], v[128:131], v[196:199], v[48:51]
	v_mfma_f32_16x16x32_bf16 v[48:51], v[132:135], v[200:203], v[48:51]
	v_mfma_f32_16x16x32_bf16 v[36:39], v[128:131], v[204:207], v[36:39]
	v_mfma_f32_16x16x32_bf16 v[36:39], v[132:135], v[208:211], v[36:39]
	v_mfma_f32_16x16x32_bf16 v[28:31], v[136:139], v[204:207], v[28:31]
	v_mfma_f32_16x16x32_bf16 v[28:31], v[140:143], v[208:211], v[28:31]
	v_mfma_f32_16x16x32_bf16 v[12:15], v[136:139], v[212:215], v[12:15]
	v_mfma_f32_16x16x32_bf16 v[12:15], v[140:143], v[216:219], v[12:15]
	v_mfma_f32_16x16x32_bf16 v[20:23], v[128:131], v[212:215], v[20:23]
	v_mfma_f32_16x16x32_bf16 v[20:23], v[132:135], v[216:219], v[20:23]
	v_mfma_f32_16x16x32_bf16 v[52:55], v[162:165], v[188:191], v[52:55]
	v_mfma_f32_16x16x32_bf16 v[52:55], v[172:175], v[192:195], v[52:55]
	v_mfma_f32_16x16x32_bf16 v[40:43], v[176:179], v[188:191], v[40:43]
	v_mfma_f32_16x16x32_bf16 v[40:43], v[184:187], v[192:195], v[40:43]
	v_mfma_f32_16x16x32_bf16 v[24:27], v[176:179], v[196:199], v[24:27]
	v_mfma_f32_16x16x32_bf16 v[24:27], v[184:187], v[200:203], v[24:27]
	v_mfma_f32_16x16x32_bf16 v[32:35], v[162:165], v[196:199], v[32:35]
	v_mfma_f32_16x16x32_bf16 v[32:35], v[172:175], v[200:203], v[32:35]
	v_mfma_f32_16x16x32_bf16 v[16:19], v[162:165], v[204:207], v[16:19]
	v_mfma_f32_16x16x32_bf16 v[16:19], v[172:175], v[208:211], v[16:19]
	v_mfma_f32_16x16x32_bf16 v[8:11], v[176:179], v[204:207], v[8:11]
	v_mfma_f32_16x16x32_bf16 v[8:11], v[184:187], v[208:211], v[8:11]
	v_mfma_f32_16x16x32_bf16 v[0:3], v[176:179], v[212:215], v[0:3]
	v_mfma_f32_16x16x32_bf16 v[0:3], v[184:187], v[216:219], v[0:3]
	v_mfma_f32_16x16x32_bf16 v[4:7], v[162:165], v[212:215], v[4:7]
	v_mfma_f32_16x16x32_bf16 v[4:7], v[172:175], v[216:219], v[4:7]
	s_barrier
; #define PG8_STAGE(bufoff, gbase, voff) do { _Pragma("unroll") for (int _i = 0; _i < 2; ++_i) \
;         __builtin_amdgcn_global_load_lds((const unsigned*)((const char*)(gbase) + (voff)[_i]), (PG8_LAS unsigned*)(lds + (bufoff) + ldsw + _i * 8192), 16, 0, 0); } while (0)
; #define PG8_LDA(dst, b, h) do { _Pragma("unroll") for (int m = 0; m < 4; ++m) _Pragma("unroll") for (int k = 0; k < 2; ++k) dst[m][k] = *(const PG8_LAS bf16x8*)(lds + PG8_SA(b, h) + aoff + m * 2048 + k * 1024); } while (0)
; #define PG8_LDB(dst, b, h) do { _Pragma("unroll") for (int n = 0; n < 2; ++n) _Pragma("unroll") for (int k = 0; k < 2; ++k) dst[n][k] = *(const PG8_LAS bf16x8*)(lds + PG8_SB(b, h) + boff + n * 2048 + k * 1024); } while (0)
; #define PG8_MMA(ai, bj, At, Bt) do { __builtin_amdgcn_s_setprio(1); _Pragma("unroll") for (int m = 0; m < 4; ++m) _Pragma("unroll") for (int n = 0; n < 2; ++n) _Pragma("unroll") for (int k = 0; k < 2; ++k) \
;         acc[ai][bj][m][n] = __builtin_amdgcn_mfma_f32_16x16x32_bf16(Bt[n][k], At[m][k], acc[ai][bj][m][n], 0, 0, 0); __builtin_amdgcn_s_setprio(0); } while (0)
; #define PG8_WAIT_V(n) asm volatile("s_waitcnt vmcnt(" #n ")" ::: "memory")
; #define PG8_WAIT_L(n) asm volatile("s_waitcnt lgkmcnt(" #n ")" ::: "memory")
; #define PG8_BAR __builtin_amdgcn_s_barrier()
; #define PG8_SCHED __builtin_amdgcn_sched_barrier(0)
; template <class Epi, class Sched, bool ALIGN_EPI = false, bool SP2 = false>
; __device__ __forceinline__ void gemm_phase(PG8_LAS unsigned char* lds, const Gemm g, const Sched& S, const Epi& E) {
;     ...
;             PG8_LDB(B0, 1, 0); PG8_LDB(B1, 1, 1); PG8_SCHED; PG8_LDA(At, 1, 0); PG8_STAGE(PG8_SA(0, 1), a2 + hstep, voffA);
;             PG8_WAIT_V(8); PG8_WAIT_L(0); PG8_BAR; PG8_MMA(0, 0, At, B0); PG8_MMA(0, 1, At, B1); PG8_BAR; PG8_SCHED;
;             PG8_LDA(At, 1, 1); PG8_STAGE(PG8_SB(1, 0), b3, voffB); PG8_STAGE(PG8_SB(1, 1), b3 + hstep, voffB); PG8_STAGE(PG8_SA(1, 0), a3, voffA);
;             PG8_WAIT_V(8); PG8_WAIT_L(0); PG8_BAR; PG8_MMA(1, 0, At, B0); PG8_MMA(1, 1, At, B1); PG8_BAR; PG8_SCHED;
;     ...
;         if constexpr (ALIGN_EPI) { if (wr == 0) PG8_BAR; }
	s_add_i32 s14, 0, 0x18000
	s_add_i32 s15, 0, 0x1c000
	v_add_u32_e32 v140, s14, v167
	v_add_u32_e32 v183, s15, v167
	ds_read_b128 v[128:131], v140
	ds_read_b128 v[132:135], v140 offset:1024
	ds_read_b128 v[136:139], v140 offset:2048
	ds_read_b128 v[140:143], v140 offset:3072
	ds_read_b128 v[162:165], v183
	ds_read_b128 v[172:175], v183 offset:1024
	ds_read_b128 v[176:179], v183 offset:2048
	ds_read_b128 v[184:187], v183 offset:3072
	s_add_u32 s34, s58, 0x40000
	s_addc_u32 s35, s59, 0
	s_mov_b32 m0, s66
	ds_read_b128 v[188:191], v171 offset:32768
	ds_read_b128 v[192:195], v171 offset:33792
	ds_read_b128 v[196:199], v171 offset:34816
	ds_read_b128 v[200:203], v171 offset:35840
	ds_read_b128 v[204:207], v171 offset:36864
	ds_read_b128 v[208:211], v171 offset:37888
	ds_read_b128 v[212:215], v171 offset:38912
	ds_read_b128 v[216:219], v171 offset:39936
	global_load_lds_dwordx4 v144, s[34:35]
	s_mov_b32 m0, s67
	s_nop 0
	global_load_lds_dwordx4 v148, s[34:35]
	s_waitcnt vmcnt(8)
	s_waitcnt lgkmcnt(0)
	s_barrier
	v_mfma_f32_16x16x32_bf16 v[124:127], v[128:131], v[188:191], v[124:127]
	v_mfma_f32_16x16x32_bf16 v[124:127], v[132:135], v[192:195], v[124:127]
	v_mfma_f32_16x16x32_bf16 v[120:123], v[136:139], v[188:191], v[120:123]
	v_mfma_f32_16x16x32_bf16 v[120:123], v[140:143], v[192:195], v[120:123]
	v_mfma_f32_16x16x32_bf16 v[108:111], v[136:139], v[196:199], v[108:111]
	v_mfma_f32_16x16x32_bf16 v[108:111], v[140:143], v[200:203], v[108:111]
	v_mfma_f32_16x16x32_bf16 v[116:119], v[128:131], v[196:199], v[116:119]
	v_mfma_f32_16x16x32_bf16 v[116:119], v[132:135], v[200:203], v[116:119]
	v_mfma_f32_16x16x32_bf16 v[100:103], v[128:131], v[204:207], v[100:103]
	v_mfma_f32_16x16x32_bf16 v[100:103], v[132:135], v[208:211], v[100:103]
	v_mfma_f32_16x16x32_bf16 v[92:95], v[136:139], v[204:207], v[92:95]
	v_mfma_f32_16x16x32_bf16 v[92:95], v[140:143], v[208:211], v[92:95]
	v_mfma_f32_16x16x32_bf16 v[76:79], v[136:139], v[212:215], v[76:79]
	v_mfma_f32_16x16x32_bf16 v[76:79], v[140:143], v[216:219], v[76:79]
	v_mfma_f32_16x16x32_bf16 v[84:87], v[128:131], v[212:215], v[84:87]
	v_mfma_f32_16x16x32_bf16 v[84:87], v[132:135], v[216:219], v[84:87]
	v_mfma_f32_16x16x32_bf16 v[112:115], v[162:165], v[188:191], v[112:115]
	v_mfma_f32_16x16x32_bf16 v[112:115], v[172:175], v[192:195], v[112:115]
	v_mfma_f32_16x16x32_bf16 v[104:107], v[176:179], v[188:191], v[104:107]
	v_mfma_f32_16x16x32_bf16 v[104:107], v[184:187], v[192:195], v[104:107]
	v_mfma_f32_16x16x32_bf16 v[88:91], v[176:179], v[196:199], v[88:91]
	v_mfma_f32_16x16x32_bf16 v[88:91], v[184:187], v[200:203], v[88:91]
	v_mfma_f32_16x16x32_bf16 v[96:99], v[162:165], v[196:199], v[96:99]
	v_mfma_f32_16x16x32_bf16 v[96:99], v[172:175], v[200:203], v[96:99]
	v_mfma_f32_16x16x32_bf16 v[80:83], v[162:165], v[204:207], v[80:83]
	v_mfma_f32_16x16x32_bf16 v[80:83], v[172:175], v[208:211], v[80:83]
	v_mfma_f32_16x16x32_bf16 v[72:75], v[176:179], v[204:207], v[72:75]
	v_mfma_f32_16x16x32_bf16 v[72:75], v[184:187], v[208:211], v[72:75]
	v_mfma_f32_16x16x32_bf16 v[64:67], v[176:179], v[212:215], v[64:67]
	v_mfma_f32_16x16x32_bf16 v[64:67], v[184:187], v[216:219], v[64:67]
	v_mfma_f32_16x16x32_bf16 v[68:71], v[162:165], v[212:215], v[68:71]
	v_mfma_f32_16x16x32_bf16 v[68:71], v[172:175], v[216:219], v[68:71]
	s_barrier
	s_add_i32 s14, s14, s63
	s_add_u32 s98, s56, s36
	s_addc_u32 s99, s57, s37
	s_add_u32 s100, s58, s36
	s_addc_u32 s101, s59, s37
	s_mov_b32 m0, s14
	ds_read_b128 v[188:191], v171 offset:49152
	ds_read_b128 v[192:195], v171 offset:50176
	ds_read_b128 v[196:199], v171 offset:51200
	ds_read_b128 v[200:203], v171 offset:52224
	ds_read_b128 v[204:207], v171 offset:53248
	ds_read_b128 v[208:211], v171 offset:54272
	ds_read_b128 v[212:215], v171 offset:55296
	ds_read_b128 v[216:219], v171 offset:56320
	global_load_lds_dwordx4 v146, s[98:99]
	s_add_i32 m0, s14, 0x2000
	s_add_u32 s34, s56, 0x40080
	s_addc_u32 s35, s57, 0
	s_add_i32 s14, s15, s63
	global_load_lds_dwordx4 v150, s[98:99]
	s_mov_b32 m0, s14
	s_nop 0
	global_load_lds_dwordx4 v146, s[34:35]
	s_add_i32 m0, s14, 0x2000
	s_nop 0
	global_load_lds_dwordx4 v150, s[34:35]
	s_mov_b32 m0, s74
	s_nop 0
	global_load_lds_dwordx4 v144, s[100:101]
	s_mov_b32 m0, s75
	s_nop 0
	global_load_lds_dwordx4 v148, s[100:101]
	s_waitcnt vmcnt(8)
	s_waitcnt lgkmcnt(0)
	s_barrier
	v_mfma_f32_16x16x32_bf16 v[60:63], v[128:131], v[188:191], v[60:63]
	v_mfma_f32_16x16x32_bf16 v[60:63], v[132:135], v[192:195], v[60:63]
	v_mfma_f32_16x16x32_bf16 v[56:59], v[136:139], v[188:191], v[56:59]
	v_mfma_f32_16x16x32_bf16 v[56:59], v[140:143], v[192:195], v[56:59]
	v_mfma_f32_16x16x32_bf16 v[44:47], v[136:139], v[196:199], v[44:47]
	v_mfma_f32_16x16x32_bf16 v[44:47], v[140:143], v[200:203], v[44:47]
	v_mfma_f32_16x16x32_bf16 v[48:51], v[128:131], v[196:199], v[48:51]
	v_mfma_f32_16x16x32_bf16 v[48:51], v[132:135], v[200:203], v[48:51]
	v_mfma_f32_16x16x32_bf16 v[36:39], v[128:131], v[204:207], v[36:39]
	v_mfma_f32_16x16x32_bf16 v[36:39], v[132:135], v[208:211], v[36:39]
	v_mfma_f32_16x16x32_bf16 v[28:31], v[136:139], v[204:207], v[28:31]
	v_mfma_f32_16x16x32_bf16 v[28:31], v[140:143], v[208:211], v[28:31]
	v_mfma_f32_16x16x32_bf16 v[12:15], v[136:139], v[212:215], v[12:15]
	v_mfma_f32_16x16x32_bf16 v[12:15], v[140:143], v[216:219], v[12:15]
	v_mfma_f32_16x16x32_bf16 v[20:23], v[128:131], v[212:215], v[20:23]
	v_mfma_f32_16x16x32_bf16 v[20:23], v[132:135], v[216:219], v[20:23]
	v_mfma_f32_16x16x32_bf16 v[52:55], v[162:165], v[188:191], v[52:55]
	v_mfma_f32_16x16x32_bf16 v[52:55], v[172:175], v[192:195], v[52:55]
	v_mfma_f32_16x16x32_bf16 v[40:43], v[176:179], v[188:191], v[40:43]
	v_mfma_f32_16x16x32_bf16 v[40:43], v[184:187], v[192:195], v[40:43]
	v_mfma_f32_16x16x32_bf16 v[24:27], v[176:179], v[196:199], v[24:27]
	v_mfma_f32_16x16x32_bf16 v[24:27], v[184:187], v[200:203], v[24:27]
	v_mfma_f32_16x16x32_bf16 v[32:35], v[162:165], v[196:199], v[32:35]
	v_mfma_f32_16x16x32_bf16 v[32:35], v[172:175], v[200:203], v[32:35]
	v_mfma_f32_16x16x32_bf16 v[16:19], v[162:165], v[204:207], v[16:19]
	v_mfma_f32_16x16x32_bf16 v[16:19], v[172:175], v[208:211], v[16:19]
	v_mfma_f32_16x16x32_bf16 v[8:11], v[176:179], v[204:207], v[8:11]
	v_mfma_f32_16x16x32_bf16 v[8:11], v[184:187], v[208:211], v[8:11]
	v_mfma_f32_16x16x32_bf16 v[0:3], v[176:179], v[212:215], v[0:3]
	v_mfma_f32_16x16x32_bf16 v[0:3], v[184:187], v[216:219], v[0:3]
	v_mfma_f32_16x16x32_bf16 v[4:7], v[162:165], v[212:215], v[4:7]
	v_mfma_f32_16x16x32_bf16 v[4:7], v[172:175], v[216:219], v[4:7]
	s_barrier
	s_add_i32 s84, s84, 2
	s_add_u32 s82, s82, 0x100
	s_addc_u32 s83, s83, 0
	s_add_u32 s54, s54, 0x100
	s_addc_u32 s55, s55, 0
	s_cmp_gt_u32 s84, 13
	s_cbranch_scc0 .LBB0_710
	s_and_b64 vcc, exec, s[40:41]
	s_cbranch_vccz .LBB0_713
	s_barrier

; #define PG8_STAGE(bufoff, gbase, voff) do { _Pragma("unroll") for (int _i = 0; _i < 2; ++_i) \
;         __builtin_amdgcn_global_load_lds((const unsigned*)((const char*)(gbase) + (voff)[_i]), (PG8_LAS unsigned*)(lds + (bufoff) + ldsw + _i * 8192), 16, 0, 0); } while (0)
; #define PG8_LDA(dst, b, h) do { _Pragma("unroll") for (int m = 0; m < 4; ++m) _Pragma("unroll") for (int k = 0; k < 2; ++k) dst[m][k] = *(const PG8_LAS bf16x8*)(lds + PG8_SA(b, h) + aoff + m * 2048 + k * 1024); } while (0)
; #define PG8_LDB(dst, b, h) do { _Pragma("unroll") for (int n = 0; n < 2; ++n) _Pragma("unroll") for (int k = 0; k < 2; ++k) dst[n][k] = *(const PG8_LAS bf16x8*)(lds + PG8_SB(b, h) + boff + n * 2048 + k * 1024); } while (0)
; #define PG8_MMA(ai, bj, At, Bt) do { __builtin_amdgcn_s_setprio(1); _Pragma("unroll") for (int m = 0; m < 4; ++m) _Pragma("unroll") for (int n = 0; n < 2; ++n) _Pragma("unroll") for (int k = 0; k < 2; ++k) \
;         acc[ai][bj][m][n] = __builtin_amdgcn_mfma_f32_16x16x32_bf16(Bt[n][k], At[m][k], acc[ai][bj][m][n], 0, 0, 0); __builtin_amdgcn_s_setprio(0); } while (0)
; #define PG8_WAIT_V(n) asm volatile("s_waitcnt vmcnt(" #n ")" ::: "memory")
; #define PG8_BAR __builtin_amdgcn_s_barrier()
; template <class Epi, class Sched, bool ALIGN_EPI = false, bool SP2 = false>
; __device__ __forceinline__ void gemm_phase(PG8_LAS unsigned char* lds, const Gemm g, const Sched& S, const Epi& E) {
;     ...
;             const bool last = (t == nt - 2);
;             const char* a1 = cA + (size_t)(t + 1) * kstep;
;             const char* a2 = last ? nA : cA + (size_t)(t + 2) * kstep; const char* b2 = last ? nB : cB + (size_t)(t + 2) * kstep;
;             const char* a3 = a2 + kstep; const char* b3 = b2 + kstep;
;             if (last && has_next) S.a_ready(nxt);
;             if (last) E.prefetch(lds + 139264, cur, wid, lane);
;             if constexpr (SP2) {
;             PG8_LDB(B0, 0, 0); PG8_LDB(B1, 0, 1); PG8_SCHED; PG8_LDA(At, 0, 0); PG8_STAGE(PG8_SA(1, 1), a1 + hstep, voffA);
;             PG8_WAIT_V(8); PG8_WAIT_L(0); PG8_BAR; PG8_MMA(0, 0, At, B0); PG8_MMA(0, 1, At, B1); PG8_BAR; PG8_SCHED;
;             PG8_LDA(At, 0, 1); PG8_STAGE(PG8_SB(0, 0), b2, voffB); PG8_STAGE(PG8_SB(0, 1), b2 + hstep, voffB); PG8_STAGE(PG8_SA(0, 0), a2, voffA);
;             PG8_WAIT_V(8); PG8_WAIT_L(0); PG8_BAR; PG8_MMA(1, 0, At, B0); PG8_MMA(1, 1, At, B1); PG8_BAR; PG8_SCHED;
.LBB0_796:
	v_add_u32_e32 v130, s76, v165
	ds_read_b128 v[118:121], v130
	ds_read_b128 v[122:125], v130 offset:1024
	ds_read_b128 v[126:129], v130 offset:2048
	ds_read_b128 v[172:175], v130 offset:3072
	v_add_u32_e32 v130, s77, v165
	ds_read_b128 v[176:179], v130
	ds_read_b128 v[184:187], v130 offset:1024
	ds_read_b128 v[188:191], v130 offset:2048
	ds_read_b128 v[192:195], v130 offset:3072
	s_add_u32 s12, s52, 0xfffc0080
	s_addc_u32 s13, s53, -1
	s_and_b64 s[34:35], s[54:55], exec
	s_cselect_b32 s57, s43, s13
	s_cselect_b32 s56, s78, s12
	s_cselect_b32 s55, s41, s51
	s_cselect_b32 s54, s79, s49
	s_add_i32 m0, s62, 0xc000
	ds_read_b128 v[196:199], v170
	ds_read_b128 v[200:203], v170 offset:1024
	ds_read_b128 v[204:207], v170 offset:2048
	ds_read_b128 v[208:211], v170 offset:3072
	ds_read_b128 v[212:215], v170 offset:4096
	ds_read_b128 v[216:219], v170 offset:5120
	ds_read_b128 v[220:223], v170 offset:6144
	ds_read_b128 v[224:227], v170 offset:7168
	global_load_lds_dwordx4 v154, s[52:53]
	s_add_i32 m0, s62, 0xe000
	s_nop 0
	global_load_lds_dwordx4 v152, s[52:53]
	s_waitcnt vmcnt(8)
	s_waitcnt lgkmcnt(0)
	s_barrier
	v_mfma_f32_16x16x32_bf16 v[140:143], v[118:121], v[196:199], v[140:143]
	v_mfma_f32_16x16x32_bf16 v[140:143], v[122:125], v[200:203], v[140:143]
	v_mfma_f32_16x16x32_bf16 v[136:139], v[126:129], v[196:199], v[136:139]
	v_mfma_f32_16x16x32_bf16 v[136:139], v[172:175], v[200:203], v[136:139]
	v_mfma_f32_16x16x32_bf16 v[104:107], v[126:129], v[204:207], v[104:107]
	v_mfma_f32_16x16x32_bf16 v[104:107], v[172:175], v[208:211], v[104:107]
	v_mfma_f32_16x16x32_bf16 v[108:111], v[118:121], v[204:207], v[108:111]
	v_mfma_f32_16x16x32_bf16 v[108:111], v[122:125], v[208:211], v[108:111]
	v_mfma_f32_16x16x32_bf16 v[92:95], v[118:121], v[212:215], v[92:95]
	v_mfma_f32_16x16x32_bf16 v[92:95], v[122:125], v[216:219], v[92:95]
	v_mfma_f32_16x16x32_bf16 v[88:91], v[126:129], v[212:215], v[88:91]
	v_mfma_f32_16x16x32_bf16 v[88:91], v[172:175], v[216:219], v[88:91]
	v_mfma_f32_16x16x32_bf16 v[72:75], v[126:129], v[220:223], v[72:75]
	v_mfma_f32_16x16x32_bf16 v[72:75], v[172:175], v[224:227], v[72:75]
	v_mfma_f32_16x16x32_bf16 v[76:79], v[118:121], v[220:223], v[76:79]
	v_mfma_f32_16x16x32_bf16 v[76:79], v[122:125], v[224:227], v[76:79]
	v_mfma_f32_16x16x32_bf16 v[130:133], v[176:179], v[196:199], v[132:135]
	v_mfma_f32_16x16x32_bf16 v[130:133], v[184:187], v[200:203], v[130:133]
	v_mfma_f32_16x16x32_bf16 v[112:115], v[188:191], v[196:199], v[112:115]
	v_mfma_f32_16x16x32_bf16 v[112:115], v[192:195], v[200:203], v[112:115]
	v_mfma_f32_16x16x32_bf16 v[96:99], v[188:191], v[204:207], v[96:99]
	v_mfma_f32_16x16x32_bf16 v[96:99], v[192:195], v[208:211], v[96:99]
	v_mfma_f32_16x16x32_bf16 v[100:103], v[176:179], v[204:207], v[100:103]
	v_mfma_f32_16x16x32_bf16 v[100:103], v[184:187], v[208:211], v[100:103]
	v_mfma_f32_16x16x32_bf16 v[84:87], v[176:179], v[212:215], v[84:87]
	v_mfma_f32_16x16x32_bf16 v[84:87], v[184:187], v[216:219], v[84:87]
	v_mfma_f32_16x16x32_bf16 v[80:83], v[188:191], v[212:215], v[80:83]
	v_mfma_f32_16x16x32_bf16 v[80:83], v[192:195], v[216:219], v[80:83]
	v_mfma_f32_16x16x32_bf16 v[64:67], v[188:191], v[220:223], v[64:67]
	v_mfma_f32_16x16x32_bf16 v[64:67], v[192:195], v[224:227], v[64:67]
	v_mfma_f32_16x16x32_bf16 v[68:71], v[176:179], v[220:223], v[68:71]
	v_mfma_f32_16x16x32_bf16 v[68:71], v[184:187], v[224:227], v[68:71]
	s_barrier
	s_add_i32 s12, s76, s59
	s_mov_b32 m0, s12
	ds_read_b128 v[196:199], v170 offset:16384
	ds_read_b128 v[200:203], v170 offset:17408
	ds_read_b128 v[204:207], v170 offset:18432
	ds_read_b128 v[208:211], v170 offset:19456
	ds_read_b128 v[212:215], v170 offset:20480
	ds_read_b128 v[216:219], v170 offset:21504
	ds_read_b128 v[220:223], v170 offset:22528
	ds_read_b128 v[224:227], v170 offset:23552
	global_load_lds_dwordx4 v148, s[54:55]
	s_add_i32 m0, s12, 0x2000
	s_add_u32 s34, s54, 0x40000
	s_addc_u32 s35, s55, 0
	s_add_i32 s12, s77, s59
	global_load_lds_dwordx4 v144, s[54:55]
	s_mov_b32 m0, s12
	s_nop 0
	global_load_lds_dwordx4 v148, s[34:35]
	s_add_i32 m0, s12, 0x2000
	s_nop 0
	global_load_lds_dwordx4 v144, s[34:35]
	s_mov_b32 m0, s62
	s_nop 0
	global_load_lds_dwordx4 v150, s[56:57]
	s_mov_b32 m0, s63
	s_nop 0
	global_load_lds_dwordx4 v146, s[56:57]
	s_waitcnt vmcnt(8)
	s_waitcnt lgkmcnt(0)
	s_barrier
	v_mfma_f32_16x16x32_bf16 v[60:63], v[118:121], v[196:199], v[60:63]
	v_mfma_f32_16x16x32_bf16 v[60:63], v[122:125], v[200:203], v[60:63]
	v_mfma_f32_16x16x32_bf16 v[56:59], v[126:129], v[196:199], v[56:59]
	v_mfma_f32_16x16x32_bf16 v[56:59], v[172:175], v[200:203], v[56:59]
	v_mfma_f32_16x16x32_bf16 v[40:43], v[126:129], v[204:207], v[40:43]
	v_mfma_f32_16x16x32_bf16 v[40:43], v[172:175], v[208:211], v[40:43]
	v_mfma_f32_16x16x32_bf16 v[44:47], v[118:121], v[204:207], v[44:47]
	v_mfma_f32_16x16x32_bf16 v[44:47], v[122:125], v[208:211], v[44:47]
	v_mfma_f32_16x16x32_bf16 v[28:31], v[118:121], v[212:215], v[28:31]
	v_mfma_f32_16x16x32_bf16 v[28:31], v[122:125], v[216:219], v[28:31]
	v_mfma_f32_16x16x32_bf16 v[24:27], v[126:129], v[212:215], v[24:27]
	v_mfma_f32_16x16x32_bf16 v[24:27], v[172:175], v[216:219], v[24:27]
	v_mfma_f32_16x16x32_bf16 v[8:11], v[126:129], v[220:223], v[8:11]
	v_mfma_f32_16x16x32_bf16 v[8:11], v[172:175], v[224:227], v[8:11]
	v_mfma_f32_16x16x32_bf16 v[12:15], v[118:121], v[220:223], v[12:15]
	v_mfma_f32_16x16x32_bf16 v[12:15], v[122:125], v[224:227], v[12:15]
	v_mfma_f32_16x16x32_bf16 v[52:55], v[176:179], v[196:199], v[52:55]
	v_mfma_f32_16x16x32_bf16 v[52:55], v[184:187], v[200:203], v[52:55]
	v_mfma_f32_16x16x32_bf16 v[48:51], v[188:191], v[196:199], v[48:51]
	v_mfma_f32_16x16x32_bf16 v[48:51], v[192:195], v[200:203], v[48:51]
	v_mfma_f32_16x16x32_bf16 v[32:35], v[188:191], v[204:207], v[32:35]
	v_mfma_f32_16x16x32_bf16 v[32:35], v[192:195], v[208:211], v[32:35]
	v_mfma_f32_16x16x32_bf16 v[36:39], v[176:179], v[204:207], v[36:39]
	v_mfma_f32_16x16x32_bf16 v[36:39], v[184:187], v[208:211], v[36:39]
	v_mfma_f32_16x16x32_bf16 v[20:23], v[176:179], v[212:215], v[20:23]
	v_mfma_f32_16x16x32_bf16 v[20:23], v[184:187], v[216:219], v[20:23]
	v_mfma_f32_16x16x32_bf16 v[16:19], v[188:191], v[212:215], v[16:19]
	v_mfma_f32_16x16x32_bf16 v[16:19], v[192:195], v[216:219], v[16:19]
	v_mfma_f32_16x16x32_bf16 v[0:3], v[188:191], v[220:223], v[0:3]
	v_mfma_f32_16x16x32_bf16 v[0:3], v[192:195], v[224:227], v[0:3]
	v_mfma_f32_16x16x32_bf16 v[4:7], v[176:179], v[220:223], v[4:7]
	v_mfma_f32_16x16x32_bf16 v[4:7], v[184:187], v[224:227], v[4:7]
	s_barrier
; #define PG8_STAGE(bufoff, gbase, voff) do { _Pragma("unroll") for (int _i = 0; _i < 2; ++_i) \
;         __builtin_amdgcn_global_load_lds((const unsigned*)((const char*)(gbase) + (voff)[_i]), (PG8_LAS unsigned*)(lds + (bufoff) + ldsw + _i * 8192), 16, 0, 0); } while (0)
; #define PG8_LDA(dst, b, h) do { _Pragma("unroll") for (int m = 0; m < 4; ++m) _Pragma("unroll") for (int k = 0; k < 2; ++k) dst[m][k] = *(const PG8_LAS bf16x8*)(lds + PG8_SA(b, h) + aoff + m * 2048 + k * 1024); } while (0)
; #define PG8_LDB(dst, b, h) do { _Pragma("unroll") for (int n = 0; n < 2; ++n) _Pragma("unroll") for (int k = 0; k < 2; ++k) dst[n][k] = *(const PG8_LAS bf16x8*)(lds + PG8_SB(b, h) + boff + n * 2048 + k * 1024); } while (0)
; #define PG8_MMA(ai, bj, At, Bt) do { __builtin_amdgcn_s_setprio(1); _Pragma("unroll") for (int m = 0; m < 4; ++m) _Pragma("unroll") for (int n = 0; n < 2; ++n) _Pragma("unroll") for (int k = 0; k < 2; ++k) \
;         acc[ai][bj][m][n] = __builtin_amdgcn_mfma_f32_16x16x32_bf16(Bt[n][k], At[m][k], acc[ai][bj][m][n], 0, 0, 0); __builtin_amdgcn_s_setprio(0); } while (0)
; #define PG8_WAIT_V(n) asm volatile("s_waitcnt vmcnt(" #n ")" ::: "memory")
; #define PG8_WAIT_L(n) asm volatile("s_waitcnt lgkmcnt(" #n ")" ::: "memory")
; #define PG8_BAR __builtin_amdgcn_s_barrier()
; #define PG8_SCHED __builtin_amdgcn_sched_barrier(0)
; template <class Epi, class Sched, bool ALIGN_EPI = false, bool SP2 = false>
; __device__ __forceinline__ void gemm_phase(PG8_LAS unsigned char* lds, const Gemm g, const Sched& S, const Epi& E) {
;     ...
;             PG8_LDB(B0, 1, 0); PG8_LDB(B1, 1, 1); PG8_SCHED; PG8_LDA(At, 1, 0); PG8_STAGE(PG8_SA(0, 1), a2 + hstep, voffA);
;             PG8_WAIT_V(8); PG8_WAIT_L(0); PG8_BAR; PG8_MMA(0, 0, At, B0); PG8_MMA(0, 1, At, B1); PG8_BAR; PG8_SCHED;
;             PG8_LDA(At, 1, 1); PG8_STAGE(PG8_SB(1, 0), b3, voffB); PG8_STAGE(PG8_SB(1, 1), b3 + hstep, voffB); PG8_STAGE(PG8_SA(1, 0), a3, voffA);
;             PG8_WAIT_V(8); PG8_WAIT_L(0); PG8_BAR; PG8_MMA(1, 0, At, B0); PG8_MMA(1, 1, At, B1); PG8_BAR; PG8_SCHED;
	s_add_i32 s12, 0, 0x18000
	v_add_u32_e32 v134, s12, v165
	s_add_i32 s13, 0, 0x1c000
	ds_read_b128 v[118:121], v134
	ds_read_b128 v[122:125], v134 offset:1024
	ds_read_b128 v[126:129], v134 offset:2048
	ds_read_b128 v[172:175], v134 offset:3072
	v_add_u32_e32 v134, s13, v165
	ds_read_b128 v[176:179], v134
	ds_read_b128 v[184:187], v134 offset:1024
	ds_read_b128 v[188:191], v134 offset:2048
	ds_read_b128 v[192:195], v134 offset:3072
	s_add_u32 s34, s56, 0x40000
	s_addc_u32 s35, s57, 0
	s_mov_b32 m0, s64
	ds_read_b128 v[196:199], v170 offset:32768
	ds_read_b128 v[200:203], v170 offset:33792
	ds_read_b128 v[204:207], v170 offset:34816
	ds_read_b128 v[208:211], v170 offset:35840
	ds_read_b128 v[212:215], v170 offset:36864
	ds_read_b128 v[216:219], v170 offset:37888
	ds_read_b128 v[220:223], v170 offset:38912
	ds_read_b128 v[224:227], v170 offset:39936
	global_load_lds_dwordx4 v150, s[34:35]
	s_mov_b32 m0, s65
	s_nop 0
	global_load_lds_dwordx4 v146, s[34:35]
	s_waitcnt vmcnt(8)
	s_waitcnt lgkmcnt(0)
	s_barrier
	v_mfma_f32_16x16x32_bf16 v[140:143], v[118:121], v[196:199], v[140:143]
	v_mfma_f32_16x16x32_bf16 v[140:143], v[122:125], v[200:203], v[140:143]
	v_mfma_f32_16x16x32_bf16 v[134:137], v[126:129], v[196:199], v[136:139]
	v_mfma_f32_16x16x32_bf16 v[136:139], v[172:175], v[200:203], v[134:137]
	v_mfma_f32_16x16x32_bf16 v[104:107], v[126:129], v[204:207], v[104:107]
	v_mfma_f32_16x16x32_bf16 v[104:107], v[172:175], v[208:211], v[104:107]
	v_mfma_f32_16x16x32_bf16 v[108:111], v[118:121], v[204:207], v[108:111]
	v_mfma_f32_16x16x32_bf16 v[108:111], v[122:125], v[208:211], v[108:111]
	v_mfma_f32_16x16x32_bf16 v[92:95], v[118:121], v[212:215], v[92:95]
	v_mfma_f32_16x16x32_bf16 v[92:95], v[122:125], v[216:219], v[92:95]
	v_mfma_f32_16x16x32_bf16 v[88:91], v[126:129], v[212:215], v[88:91]
	v_mfma_f32_16x16x32_bf16 v[88:91], v[172:175], v[216:219], v[88:91]
	v_mfma_f32_16x16x32_bf16 v[72:75], v[126:129], v[220:223], v[72:75]
	v_mfma_f32_16x16x32_bf16 v[72:75], v[172:175], v[224:227], v[72:75]
	v_mfma_f32_16x16x32_bf16 v[76:79], v[118:121], v[220:223], v[76:79]
	v_mfma_f32_16x16x32_bf16 v[76:79], v[122:125], v[224:227], v[76:79]
	v_mfma_f32_16x16x32_bf16 v[130:133], v[176:179], v[196:199], v[130:133]
	v_mfma_f32_16x16x32_bf16 v[132:135], v[184:187], v[200:203], v[130:133]
	v_mfma_f32_16x16x32_bf16 v[112:115], v[188:191], v[196:199], v[112:115]
	v_mfma_f32_16x16x32_bf16 v[112:115], v[192:195], v[200:203], v[112:115]
	v_mfma_f32_16x16x32_bf16 v[96:99], v[188:191], v[204:207], v[96:99]
	v_mfma_f32_16x16x32_bf16 v[96:99], v[192:195], v[208:211], v[96:99]
	v_mfma_f32_16x16x32_bf16 v[100:103], v[176:179], v[204:207], v[100:103]
	v_mfma_f32_16x16x32_bf16 v[100:103], v[184:187], v[208:211], v[100:103]
	v_mfma_f32_16x16x32_bf16 v[84:87], v[176:179], v[212:215], v[84:87]
	v_mfma_f32_16x16x32_bf16 v[84:87], v[184:187], v[216:219], v[84:87]
	v_mfma_f32_16x16x32_bf16 v[80:83], v[188:191], v[212:215], v[80:83]
	v_mfma_f32_16x16x32_bf16 v[80:83], v[192:195], v[216:219], v[80:83]
	v_mfma_f32_16x16x32_bf16 v[64:67], v[188:191], v[220:223], v[64:67]
	v_mfma_f32_16x16x32_bf16 v[64:67], v[192:195], v[224:227], v[64:67]
	v_mfma_f32_16x16x32_bf16 v[68:71], v[176:179], v[220:223], v[68:71]
	v_mfma_f32_16x16x32_bf16 v[68:71], v[184:187], v[224:227], v[68:71]
	s_barrier
	s_add_i32 s12, s12, s59
	s_add_u32 s98, s54, s18
	s_addc_u32 s99, s55, s19
	s_add_u32 s100, s56, s18
	s_addc_u32 s101, s57, s19
	s_mov_b32 m0, s12
	ds_read_b128 v[196:199], v170 offset:49152
	ds_read_b128 v[200:203], v170 offset:50176
	ds_read_b128 v[204:207], v170 offset:51200
	ds_read_b128 v[208:211], v170 offset:52224
	ds_read_b128 v[212:215], v170 offset:53248
	ds_read_b128 v[216:219], v170 offset:54272
	ds_read_b128 v[220:223], v170 offset:55296
	ds_read_b128 v[224:227], v170 offset:56320
	global_load_lds_dwordx4 v148, s[98:99]
	s_add_i32 m0, s12, 0x2000
	s_add_u32 s34, s54, 0x40080
	s_addc_u32 s35, s55, 0
	s_add_i32 s12, s13, s59
	global_load_lds_dwordx4 v144, s[98:99]
	s_mov_b32 m0, s12
	s_nop 0
	global_load_lds_dwordx4 v148, s[34:35]
	s_add_i32 m0, s12, 0x2000
	s_nop 0
	global_load_lds_dwordx4 v144, s[34:35]
	s_mov_b32 m0, s68
	s_nop 0
	global_load_lds_dwordx4 v150, s[100:101]
	s_mov_b32 m0, s69
	s_nop 0
	global_load_lds_dwordx4 v146, s[100:101]
	s_waitcnt vmcnt(8)
	s_waitcnt lgkmcnt(0)
	s_barrier
	v_mfma_f32_16x16x32_bf16 v[60:63], v[118:121], v[196:199], v[60:63]
	v_mfma_f32_16x16x32_bf16 v[60:63], v[122:125], v[200:203], v[60:63]
	v_mfma_f32_16x16x32_bf16 v[56:59], v[126:129], v[196:199], v[56:59]
	v_mfma_f32_16x16x32_bf16 v[56:59], v[172:175], v[200:203], v[56:59]
	v_mfma_f32_16x16x32_bf16 v[40:43], v[126:129], v[204:207], v[40:43]
	v_mfma_f32_16x16x32_bf16 v[40:43], v[172:175], v[208:211], v[40:43]
	v_mfma_f32_16x16x32_bf16 v[44:47], v[118:121], v[204:207], v[44:47]
	v_mfma_f32_16x16x32_bf16 v[44:47], v[122:125], v[208:211], v[44:47]
	v_mfma_f32_16x16x32_bf16 v[28:31], v[118:121], v[212:215], v[28:31]
	v_mfma_f32_16x16x32_bf16 v[28:31], v[122:125], v[216:219], v[28:31]
	v_mfma_f32_16x16x32_bf16 v[24:27], v[126:129], v[212:215], v[24:27]
	v_mfma_f32_16x16x32_bf16 v[24:27], v[172:175], v[216:219], v[24:27]
	v_mfma_f32_16x16x32_bf16 v[8:11], v[126:129], v[220:223], v[8:11]
	v_mfma_f32_16x16x32_bf16 v[8:11], v[172:175], v[224:227], v[8:11]
	v_mfma_f32_16x16x32_bf16 v[12:15], v[118:121], v[220:223], v[12:15]
	v_mfma_f32_16x16x32_bf16 v[12:15], v[122:125], v[224:227], v[12:15]
	v_mfma_f32_16x16x32_bf16 v[52:55], v[176:179], v[196:199], v[52:55]
	v_mfma_f32_16x16x32_bf16 v[52:55], v[184:187], v[200:203], v[52:55]
	v_mfma_f32_16x16x32_bf16 v[48:51], v[188:191], v[196:199], v[48:51]
	v_mfma_f32_16x16x32_bf16 v[48:51], v[192:195], v[200:203], v[48:51]
	v_mfma_f32_16x16x32_bf16 v[32:35], v[188:191], v[204:207], v[32:35]
	v_mfma_f32_16x16x32_bf16 v[32:35], v[192:195], v[208:211], v[32:35]
	v_mfma_f32_16x16x32_bf16 v[36:39], v[176:179], v[204:207], v[36:39]
	v_mfma_f32_16x16x32_bf16 v[36:39], v[184:187], v[208:211], v[36:39]
	v_mfma_f32_16x16x32_bf16 v[20:23], v[176:179], v[212:215], v[20:23]
	v_mfma_f32_16x16x32_bf16 v[20:23], v[184:187], v[216:219], v[20:23]
	v_mfma_f32_16x16x32_bf16 v[16:19], v[188:191], v[212:215], v[16:19]
	v_mfma_f32_16x16x32_bf16 v[16:19], v[192:195], v[216:219], v[16:19]
	v_mfma_f32_16x16x32_bf16 v[0:3], v[188:191], v[220:223], v[0:3]
	v_mfma_f32_16x16x32_bf16 v[0:3], v[192:195], v[224:227], v[0:3]
	v_mfma_f32_16x16x32_bf16 v[4:7], v[176:179], v[220:223], v[4:7]
	v_mfma_f32_16x16x32_bf16 v[4:7], v[184:187], v[224:227], v[4:7]
	s_barrier
	s_add_i32 s80, s80, 2
	s_add_u32 s49, s49, 0x100
	s_addc_u32 s51, s51, 0
	s_add_u32 s52, s52, 0x100
	s_addc_u32 s53, s53, 0
	s_cmp_gt_u32 s80, 13
	s_cbranch_scc1 .LBB0_799

; #define PG8_STAGE(bufoff, gbase, voff) do { _Pragma("unroll") for (int _i = 0; _i < 2; ++_i) \
;         __builtin_amdgcn_global_load_lds((const unsigned*)((const char*)(gbase) + (voff)[_i]), (PG8_LAS unsigned*)(lds + (bufoff) + ldsw + _i * 8192), 16, 0, 0); } while (0)
; #define PG8_LDA(dst, b, h) do { _Pragma("unroll") for (int m = 0; m < 4; ++m) _Pragma("unroll") for (int k = 0; k < 2; ++k) dst[m][k] = *(const PG8_LAS bf16x8*)(lds + PG8_SA(b, h) + aoff + m * 2048 + k * 1024); } while (0)
; #define PG8_LDB(dst, b, h) do { _Pragma("unroll") for (int n = 0; n < 2; ++n) _Pragma("unroll") for (int k = 0; k < 2; ++k) dst[n][k] = *(const PG8_LAS bf16x8*)(lds + PG8_SB(b, h) + boff + n * 2048 + k * 1024); } while (0)
; #define PG8_MMA(ai, bj, At, Bt) do { __builtin_amdgcn_s_setprio(1); _Pragma("unroll") for (int m = 0; m < 4; ++m) _Pragma("unroll") for (int n = 0; n < 2; ++n) _Pragma("unroll") for (int k = 0; k < 2; ++k) \
;         acc[ai][bj][m][n] = __builtin_amdgcn_mfma_f32_16x16x32_bf16(Bt[n][k], At[m][k], acc[ai][bj][m][n], 0, 0, 0); __builtin_amdgcn_s_setprio(0); } while (0)
; #define PG8_WAIT_V(n) asm volatile("s_waitcnt vmcnt(" #n ")" ::: "memory")
; #define PG8_BAR __builtin_amdgcn_s_barrier()
; template <class Epi, class Sched, bool ALIGN_EPI = false, bool SP2 = false>
; __device__ __forceinline__ void gemm_phase(PG8_LAS unsigned char* lds, const Gemm g, const Sched& S, const Epi& E) {
;     ...
;             const bool last = (t == nt - 2);
;             const char* a1 = cA + (size_t)(t + 1) * kstep;
;             const char* a2 = last ? nA : cA + (size_t)(t + 2) * kstep; const char* b2 = last ? nB : cB + (size_t)(t + 2) * kstep;
;             const char* a3 = a2 + kstep; const char* b3 = b2 + kstep;
;             if (last && has_next) S.a_ready(nxt);
;             if (last) E.prefetch(lds + 139264, cur, wid, lane);
;             if constexpr (SP2) {
;             PG8_LDB(B0, 0, 0); PG8_LDB(B1, 0, 1); PG8_SCHED; PG8_LDA(At, 0, 0); PG8_STAGE(PG8_SA(1, 1), a1 + hstep, voffA);
;             PG8_WAIT_V(8); PG8_WAIT_L(0); PG8_BAR; PG8_MMA(0, 0, At, B0); PG8_MMA(0, 1, At, B1); PG8_BAR; PG8_SCHED;
;             PG8_LDA(At, 0, 1); PG8_STAGE(PG8_SB(0, 0), b2, voffB); PG8_STAGE(PG8_SB(0, 1), b2 + hstep, voffB); PG8_STAGE(PG8_SA(0, 0), a2, voffA);
;             PG8_WAIT_V(8); PG8_WAIT_L(0); PG8_BAR; PG8_MMA(1, 0, At, B0); PG8_MMA(1, 1, At, B1); PG8_BAR; PG8_SCHED;
.LBB0_872:
	ds_read_b128 v[128:131], v169
	ds_read_b128 v[132:135], v169 offset:1024
	ds_read_b128 v[136:139], v169 offset:2048
	ds_read_b128 v[140:143], v169 offset:3072
	ds_read_b128 v[162:165], v170
	ds_read_b128 v[172:175], v170 offset:1024
	ds_read_b128 v[176:179], v170 offset:2048
	ds_read_b128 v[184:187], v170 offset:3072
	s_add_u32 s42, s40, 0x100
	s_addc_u32 s43, s41, 0
	s_cmp_eq_u32 s74, 40
	s_cselect_b32 s47, s11, s43
	s_cselect_b32 s46, s10, s42
	s_cselect_b32 s45, s37, s73
	s_cselect_b32 s44, s36, s71
	v_lshl_add_u64 v[180:181], s[40:41], 0, v[154:155]
	s_add_i32 m0, s50, 0xc000
	ds_read_b128 v[188:191], v171
	ds_read_b128 v[192:195], v171 offset:1024
	ds_read_b128 v[196:199], v171 offset:2048
	ds_read_b128 v[200:203], v171 offset:3072
	ds_read_b128 v[204:207], v171 offset:4096
	ds_read_b128 v[208:211], v171 offset:5120
	ds_read_b128 v[212:215], v171 offset:6144
	ds_read_b128 v[216:219], v171 offset:7168
	global_load_lds_dwordx4 v[180:181], off
	v_lshl_add_u64 v[180:181], s[40:41], 0, v[152:153]
	s_add_i32 m0, s50, 0xe000
	s_nop 0
	global_load_lds_dwordx4 v[180:181], off
	s_waitcnt vmcnt(8)
	s_waitcnt lgkmcnt(0)
	s_barrier
	v_mfma_f32_16x16x32_bf16 v[124:127], v[128:131], v[188:191], v[124:127]
	v_mfma_f32_16x16x32_bf16 v[124:127], v[132:135], v[192:195], v[124:127]
	v_mfma_f32_16x16x32_bf16 v[120:123], v[136:139], v[188:191], v[120:123]
	v_mfma_f32_16x16x32_bf16 v[120:123], v[140:143], v[192:195], v[120:123]
	v_mfma_f32_16x16x32_bf16 v[108:111], v[136:139], v[196:199], v[108:111]
	v_mfma_f32_16x16x32_bf16 v[108:111], v[140:143], v[200:203], v[108:111]
	v_mfma_f32_16x16x32_bf16 v[116:119], v[128:131], v[196:199], v[116:119]
	v_mfma_f32_16x16x32_bf16 v[116:119], v[132:135], v[200:203], v[116:119]
	v_mfma_f32_16x16x32_bf16 v[100:103], v[128:131], v[204:207], v[100:103]
	v_mfma_f32_16x16x32_bf16 v[100:103], v[132:135], v[208:211], v[100:103]
	v_mfma_f32_16x16x32_bf16 v[92:95], v[136:139], v[204:207], v[92:95]
	v_mfma_f32_16x16x32_bf16 v[92:95], v[140:143], v[208:211], v[92:95]
	v_mfma_f32_16x16x32_bf16 v[76:79], v[136:139], v[212:215], v[76:79]
	v_mfma_f32_16x16x32_bf16 v[76:79], v[140:143], v[216:219], v[76:79]
	v_mfma_f32_16x16x32_bf16 v[84:87], v[128:131], v[212:215], v[84:87]
	v_mfma_f32_16x16x32_bf16 v[84:87], v[132:135], v[216:219], v[84:87]
	v_mfma_f32_16x16x32_bf16 v[112:115], v[162:165], v[188:191], v[112:115]
	v_mfma_f32_16x16x32_bf16 v[112:115], v[172:175], v[192:195], v[112:115]
	v_mfma_f32_16x16x32_bf16 v[104:107], v[176:179], v[188:191], v[104:107]
	v_mfma_f32_16x16x32_bf16 v[104:107], v[184:187], v[192:195], v[104:107]
	v_mfma_f32_16x16x32_bf16 v[88:91], v[176:179], v[196:199], v[88:91]
	v_mfma_f32_16x16x32_bf16 v[88:91], v[184:187], v[200:203], v[88:91]
	v_mfma_f32_16x16x32_bf16 v[96:99], v[162:165], v[196:199], v[96:99]
	v_mfma_f32_16x16x32_bf16 v[96:99], v[172:175], v[200:203], v[96:99]
	v_mfma_f32_16x16x32_bf16 v[80:83], v[162:165], v[204:207], v[80:83]
	v_mfma_f32_16x16x32_bf16 v[80:83], v[172:175], v[208:211], v[80:83]
	v_mfma_f32_16x16x32_bf16 v[72:75], v[176:179], v[204:207], v[72:75]
	v_mfma_f32_16x16x32_bf16 v[72:75], v[184:187], v[208:211], v[72:75]
	v_mfma_f32_16x16x32_bf16 v[64:67], v[176:179], v[212:215], v[64:67]
	v_mfma_f32_16x16x32_bf16 v[64:67], v[184:187], v[216:219], v[64:67]
	v_mfma_f32_16x16x32_bf16 v[68:71], v[162:165], v[212:215], v[68:71]
	v_mfma_f32_16x16x32_bf16 v[68:71], v[172:175], v[216:219], v[68:71]
	s_barrier
	s_add_i32 s12, s65, s49
	s_mov_b32 m0, s12
	ds_read_b128 v[188:191], v171 offset:16384
	ds_read_b128 v[192:195], v171 offset:17408
	ds_read_b128 v[196:199], v171 offset:18432
	ds_read_b128 v[200:203], v171 offset:19456
	ds_read_b128 v[204:207], v171 offset:20480
	ds_read_b128 v[208:211], v171 offset:21504
	ds_read_b128 v[212:215], v171 offset:22528
	ds_read_b128 v[216:219], v171 offset:23552
	global_load_lds_dwordx4 v146, s[44:45]
	s_add_i32 m0, s12, 0x2000
	s_add_u32 s40, s44, 0xb0000
	s_addc_u32 s41, s45, 0
	s_add_i32 s12, s66, s49
	global_load_lds_dwordx4 v150, s[44:45]
	s_mov_b32 m0, s12
	s_nop 0
	global_load_lds_dwordx4 v146, s[40:41]
	s_add_i32 m0, s12, 0x2000
	s_nop 0
	global_load_lds_dwordx4 v150, s[40:41]
	s_mov_b32 m0, s50
	s_nop 0
	global_load_lds_dwordx4 v144, s[46:47]
	s_mov_b32 m0, s51
	s_nop 0
	global_load_lds_dwordx4 v148, s[46:47]
	s_waitcnt vmcnt(8)
	s_waitcnt lgkmcnt(0)
	s_barrier
	v_mfma_f32_16x16x32_bf16 v[60:63], v[128:131], v[188:191], v[60:63]
	v_mfma_f32_16x16x32_bf16 v[60:63], v[132:135], v[192:195], v[60:63]
	v_mfma_f32_16x16x32_bf16 v[56:59], v[136:139], v[188:191], v[56:59]
	v_mfma_f32_16x16x32_bf16 v[56:59], v[140:143], v[192:195], v[56:59]
	v_mfma_f32_16x16x32_bf16 v[44:47], v[136:139], v[196:199], v[44:47]
	v_mfma_f32_16x16x32_bf16 v[44:47], v[140:143], v[200:203], v[44:47]
	v_mfma_f32_16x16x32_bf16 v[48:51], v[128:131], v[196:199], v[48:51]
	v_mfma_f32_16x16x32_bf16 v[48:51], v[132:135], v[200:203], v[48:51]
	v_mfma_f32_16x16x32_bf16 v[36:39], v[128:131], v[204:207], v[36:39]
	v_mfma_f32_16x16x32_bf16 v[36:39], v[132:135], v[208:211], v[36:39]
	v_mfma_f32_16x16x32_bf16 v[28:31], v[136:139], v[204:207], v[28:31]
	v_mfma_f32_16x16x32_bf16 v[28:31], v[140:143], v[208:211], v[28:31]
	v_mfma_f32_16x16x32_bf16 v[12:15], v[136:139], v[212:215], v[12:15]
	v_mfma_f32_16x16x32_bf16 v[12:15], v[140:143], v[216:219], v[12:15]
	v_mfma_f32_16x16x32_bf16 v[20:23], v[128:131], v[212:215], v[20:23]
	v_mfma_f32_16x16x32_bf16 v[20:23], v[132:135], v[216:219], v[20:23]
	v_mfma_f32_16x16x32_bf16 v[52:55], v[162:165], v[188:191], v[52:55]
	v_mfma_f32_16x16x32_bf16 v[52:55], v[172:175], v[192:195], v[52:55]
	v_mfma_f32_16x16x32_bf16 v[40:43], v[176:179], v[188:191], v[40:43]
	v_mfma_f32_16x16x32_bf16 v[40:43], v[184:187], v[192:195], v[40:43]
	v_mfma_f32_16x16x32_bf16 v[24:27], v[176:179], v[196:199], v[24:27]
	v_mfma_f32_16x16x32_bf16 v[24:27], v[184:187], v[200:203], v[24:27]
	v_mfma_f32_16x16x32_bf16 v[32:35], v[162:165], v[196:199], v[32:35]
	v_mfma_f32_16x16x32_bf16 v[32:35], v[172:175], v[200:203], v[32:35]
	v_mfma_f32_16x16x32_bf16 v[16:19], v[162:165], v[204:207], v[16:19]
	v_mfma_f32_16x16x32_bf16 v[16:19], v[172:175], v[208:211], v[16:19]
	v_mfma_f32_16x16x32_bf16 v[8:11], v[176:179], v[204:207], v[8:11]
	v_mfma_f32_16x16x32_bf16 v[8:11], v[184:187], v[208:211], v[8:11]
	v_mfma_f32_16x16x32_bf16 v[0:3], v[176:179], v[212:215], v[0:3]
	v_mfma_f32_16x16x32_bf16 v[0:3], v[184:187], v[216:219], v[0:3]
	v_mfma_f32_16x16x32_bf16 v[4:7], v[162:165], v[212:215], v[4:7]
	v_mfma_f32_16x16x32_bf16 v[4:7], v[172:175], v[216:219], v[4:7]
	s_barrier
; #define PG8_STAGE(bufoff, gbase, voff) do { _Pragma("unroll") for (int _i = 0; _i < 2; ++_i) \
;         __builtin_amdgcn_global_load_lds((const unsigned*)((const char*)(gbase) + (voff)[_i]), (PG8_LAS unsigned*)(lds + (bufoff) + ldsw + _i * 8192), 16, 0, 0); } while (0)
; #define PG8_LDA(dst, b, h) do { _Pragma("unroll") for (int m = 0; m < 4; ++m) _Pragma("unroll") for (int k = 0; k < 2; ++k) dst[m][k] = *(const PG8_LAS bf16x8*)(lds + PG8_SA(b, h) + aoff + m * 2048 + k * 1024); } while (0)
; #define PG8_LDB(dst, b, h) do { _Pragma("unroll") for (int n = 0; n < 2; ++n) _Pragma("unroll") for (int k = 0; k < 2; ++k) dst[n][k] = *(const PG8_LAS bf16x8*)(lds + PG8_SB(b, h) + boff + n * 2048 + k * 1024); } while (0)
; #define PG8_MMA(ai, bj, At, Bt) do { __builtin_amdgcn_s_setprio(1); _Pragma("unroll") for (int m = 0; m < 4; ++m) _Pragma("unroll") for (int n = 0; n < 2; ++n) _Pragma("unroll") for (int k = 0; k < 2; ++k) \
;         acc[ai][bj][m][n] = __builtin_amdgcn_mfma_f32_16x16x32_bf16(Bt[n][k], At[m][k], acc[ai][bj][m][n], 0, 0, 0); __builtin_amdgcn_s_setprio(0); } while (0)
; #define PG8_WAIT_V(n) asm volatile("s_waitcnt vmcnt(" #n ")" ::: "memory")
; #define PG8_WAIT_L(n) asm volatile("s_waitcnt lgkmcnt(" #n ")" ::: "memory")
; #define PG8_BAR __builtin_amdgcn_s_barrier()
; #define PG8_SCHED __builtin_amdgcn_sched_barrier(0)
; template <class Epi, class Sched, bool ALIGN_EPI = false, bool SP2 = false>
; __device__ __forceinline__ void gemm_phase(PG8_LAS unsigned char* lds, const Gemm g, const Sched& S, const Epi& E) {
;     ...
;             PG8_LDB(B0, 1, 0); PG8_LDB(B1, 1, 1); PG8_SCHED; PG8_LDA(At, 1, 0); PG8_STAGE(PG8_SA(0, 1), a2 + hstep, voffA);
;             PG8_WAIT_V(8); PG8_WAIT_L(0); PG8_BAR; PG8_MMA(0, 0, At, B0); PG8_MMA(0, 1, At, B1); PG8_BAR; PG8_SCHED;
;             PG8_LDA(At, 1, 1); PG8_STAGE(PG8_SB(1, 0), b3, voffB); PG8_STAGE(PG8_SB(1, 1), b3 + hstep, voffB); PG8_STAGE(PG8_SA(1, 0), a3, voffA);
;             PG8_WAIT_V(8); PG8_WAIT_L(0); PG8_BAR; PG8_MMA(1, 0, At, B0); PG8_MMA(1, 1, At, B1); PG8_BAR; PG8_SCHED;
;     ...
;         if constexpr (ALIGN_EPI) { if (wr == 0) PG8_BAR; }
	s_add_i32 s12, 0, 0x18000
	s_add_i32 s13, 0, 0x1c000
	v_add_u32_e32 v140, s12, v167
	v_add_u32_e32 v183, s13, v167
	ds_read_b128 v[128:131], v140
	ds_read_b128 v[132:135], v140 offset:1024
	ds_read_b128 v[136:139], v140 offset:2048
	ds_read_b128 v[140:143], v140 offset:3072
	ds_read_b128 v[162:165], v183
	ds_read_b128 v[172:175], v183 offset:1024
	ds_read_b128 v[176:179], v183 offset:2048
	ds_read_b128 v[184:187], v183 offset:3072
	s_add_u32 s40, s46, 0xb0000
	s_addc_u32 s41, s47, 0
	s_mov_b32 m0, s52
	ds_read_b128 v[188:191], v171 offset:32768
	ds_read_b128 v[192:195], v171 offset:33792
	ds_read_b128 v[196:199], v171 offset:34816
	ds_read_b128 v[200:203], v171 offset:35840
	ds_read_b128 v[204:207], v171 offset:36864
	ds_read_b128 v[208:211], v171 offset:37888
	ds_read_b128 v[212:215], v171 offset:38912
	ds_read_b128 v[216:219], v171 offset:39936
	global_load_lds_dwordx4 v144, s[40:41]
	s_mov_b32 m0, s53
	s_nop 0
	global_load_lds_dwordx4 v148, s[40:41]
	s_waitcnt vmcnt(8)
	s_waitcnt lgkmcnt(0)
	s_barrier
	v_mfma_f32_16x16x32_bf16 v[124:127], v[128:131], v[188:191], v[124:127]
	v_mfma_f32_16x16x32_bf16 v[124:127], v[132:135], v[192:195], v[124:127]
	v_mfma_f32_16x16x32_bf16 v[120:123], v[136:139], v[188:191], v[120:123]
	v_mfma_f32_16x16x32_bf16 v[120:123], v[140:143], v[192:195], v[120:123]
	v_mfma_f32_16x16x32_bf16 v[108:111], v[136:139], v[196:199], v[108:111]
	v_mfma_f32_16x16x32_bf16 v[108:111], v[140:143], v[200:203], v[108:111]
	v_mfma_f32_16x16x32_bf16 v[116:119], v[128:131], v[196:199], v[116:119]
	v_mfma_f32_16x16x32_bf16 v[116:119], v[132:135], v[200:203], v[116:119]
	v_mfma_f32_16x16x32_bf16 v[100:103], v[128:131], v[204:207], v[100:103]
	v_mfma_f32_16x16x32_bf16 v[100:103], v[132:135], v[208:211], v[100:103]
	v_mfma_f32_16x16x32_bf16 v[92:95], v[136:139], v[204:207], v[92:95]
	v_mfma_f32_16x16x32_bf16 v[92:95], v[140:143], v[208:211], v[92:95]
	v_mfma_f32_16x16x32_bf16 v[76:79], v[136:139], v[212:215], v[76:79]
	v_mfma_f32_16x16x32_bf16 v[76:79], v[140:143], v[216:219], v[76:79]
	v_mfma_f32_16x16x32_bf16 v[84:87], v[128:131], v[212:215], v[84:87]
	v_mfma_f32_16x16x32_bf16 v[84:87], v[132:135], v[216:219], v[84:87]
	v_mfma_f32_16x16x32_bf16 v[112:115], v[162:165], v[188:191], v[112:115]
	v_mfma_f32_16x16x32_bf16 v[112:115], v[172:175], v[192:195], v[112:115]
	v_mfma_f32_16x16x32_bf16 v[104:107], v[176:179], v[188:191], v[104:107]
	v_mfma_f32_16x16x32_bf16 v[104:107], v[184:187], v[192:195], v[104:107]
	v_mfma_f32_16x16x32_bf16 v[88:91], v[176:179], v[196:199], v[88:91]
	v_mfma_f32_16x16x32_bf16 v[88:91], v[184:187], v[200:203], v[88:91]
	v_mfma_f32_16x16x32_bf16 v[96:99], v[162:165], v[196:199], v[96:99]
	v_mfma_f32_16x16x32_bf16 v[96:99], v[172:175], v[200:203], v[96:99]
	v_mfma_f32_16x16x32_bf16 v[80:83], v[162:165], v[204:207], v[80:83]
	v_mfma_f32_16x16x32_bf16 v[80:83], v[172:175], v[208:211], v[80:83]
	v_mfma_f32_16x16x32_bf16 v[72:75], v[176:179], v[204:207], v[72:75]
	v_mfma_f32_16x16x32_bf16 v[72:75], v[184:187], v[208:211], v[72:75]
	v_mfma_f32_16x16x32_bf16 v[64:67], v[176:179], v[212:215], v[64:67]
	v_mfma_f32_16x16x32_bf16 v[64:67], v[184:187], v[216:219], v[64:67]
	v_mfma_f32_16x16x32_bf16 v[68:71], v[162:165], v[212:215], v[68:71]
	v_mfma_f32_16x16x32_bf16 v[68:71], v[172:175], v[216:219], v[68:71]
	s_barrier
	s_add_i32 s12, s12, s49
	s_add_u32 s98, s44, s30
	s_addc_u32 s99, s45, s31
	s_add_u32 s100, s46, s30
	s_addc_u32 s101, s47, s31
	s_mov_b32 m0, s12
	ds_read_b128 v[188:191], v171 offset:49152
	ds_read_b128 v[192:195], v171 offset:50176
	ds_read_b128 v[196:199], v171 offset:51200
	ds_read_b128 v[200:203], v171 offset:52224
	ds_read_b128 v[204:207], v171 offset:53248
	ds_read_b128 v[208:211], v171 offset:54272
	ds_read_b128 v[212:215], v171 offset:55296
	ds_read_b128 v[216:219], v171 offset:56320
	global_load_lds_dwordx4 v146, s[98:99]
	s_add_i32 m0, s12, 0x2000
	s_add_u32 s40, s44, 0xb0080
	s_addc_u32 s41, s45, 0
	s_add_i32 s12, s13, s49
	global_load_lds_dwordx4 v150, s[98:99]
	s_mov_b32 m0, s12
	s_nop 0
	global_load_lds_dwordx4 v146, s[40:41]
	s_add_i32 m0, s12, 0x2000
	s_nop 0
	global_load_lds_dwordx4 v150, s[40:41]
	s_mov_b32 m0, s59
	s_nop 0
	global_load_lds_dwordx4 v144, s[100:101]
	s_mov_b32 m0, s60
	s_nop 0
	global_load_lds_dwordx4 v148, s[100:101]
	s_waitcnt vmcnt(8)
	s_waitcnt lgkmcnt(0)
	s_barrier
	v_mfma_f32_16x16x32_bf16 v[60:63], v[128:131], v[188:191], v[60:63]
	v_mfma_f32_16x16x32_bf16 v[60:63], v[132:135], v[192:195], v[60:63]
	v_mfma_f32_16x16x32_bf16 v[56:59], v[136:139], v[188:191], v[56:59]
	v_mfma_f32_16x16x32_bf16 v[56:59], v[140:143], v[192:195], v[56:59]
	v_mfma_f32_16x16x32_bf16 v[44:47], v[136:139], v[196:199], v[44:47]
	v_mfma_f32_16x16x32_bf16 v[44:47], v[140:143], v[200:203], v[44:47]
	v_mfma_f32_16x16x32_bf16 v[48:51], v[128:131], v[196:199], v[48:51]
	v_mfma_f32_16x16x32_bf16 v[48:51], v[132:135], v[200:203], v[48:51]
	v_mfma_f32_16x16x32_bf16 v[36:39], v[128:131], v[204:207], v[36:39]
	v_mfma_f32_16x16x32_bf16 v[36:39], v[132:135], v[208:211], v[36:39]
	v_mfma_f32_16x16x32_bf16 v[28:31], v[136:139], v[204:207], v[28:31]
	v_mfma_f32_16x16x32_bf16 v[28:31], v[140:143], v[208:211], v[28:31]
	v_mfma_f32_16x16x32_bf16 v[12:15], v[136:139], v[212:215], v[12:15]
	v_mfma_f32_16x16x32_bf16 v[12:15], v[140:143], v[216:219], v[12:15]
	v_mfma_f32_16x16x32_bf16 v[20:23], v[128:131], v[212:215], v[20:23]
	v_mfma_f32_16x16x32_bf16 v[20:23], v[132:135], v[216:219], v[20:23]
	v_mfma_f32_16x16x32_bf16 v[52:55], v[162:165], v[188:191], v[52:55]
	v_mfma_f32_16x16x32_bf16 v[52:55], v[172:175], v[192:195], v[52:55]
	v_mfma_f32_16x16x32_bf16 v[40:43], v[176:179], v[188:191], v[40:43]
	v_mfma_f32_16x16x32_bf16 v[40:43], v[184:187], v[192:195], v[40:43]
	v_mfma_f32_16x16x32_bf16 v[24:27], v[176:179], v[196:199], v[24:27]
	v_mfma_f32_16x16x32_bf16 v[24:27], v[184:187], v[200:203], v[24:27]
	v_mfma_f32_16x16x32_bf16 v[32:35], v[162:165], v[196:199], v[32:35]
	v_mfma_f32_16x16x32_bf16 v[32:35], v[172:175], v[200:203], v[32:35]
	v_mfma_f32_16x16x32_bf16 v[16:19], v[162:165], v[204:207], v[16:19]
	v_mfma_f32_16x16x32_bf16 v[16:19], v[172:175], v[208:211], v[16:19]
	v_mfma_f32_16x16x32_bf16 v[8:11], v[176:179], v[204:207], v[8:11]
	v_mfma_f32_16x16x32_bf16 v[8:11], v[184:187], v[208:211], v[8:11]
	v_mfma_f32_16x16x32_bf16 v[0:3], v[176:179], v[212:215], v[0:3]
	v_mfma_f32_16x16x32_bf16 v[0:3], v[184:187], v[216:219], v[0:3]
	v_mfma_f32_16x16x32_bf16 v[4:7], v[162:165], v[212:215], v[4:7]
	v_mfma_f32_16x16x32_bf16 v[4:7], v[172:175], v[216:219], v[4:7]
	s_barrier
	s_add_i32 s74, s74, 2
	s_add_u32 s71, s71, 0x100
	s_addc_u32 s73, s73, 0
	s_cmp_gt_u32 s74, 41
	s_mov_b64 s[40:41], s[42:43]
	s_cbranch_scc0 .LBB0_872
	s_and_b64 vcc, exec, s[34:35]
	s_cbranch_vccz .LBB0_875
	s_barrier

; #define PG8_STAGE(bufoff, gbase, voff) do { _Pragma("unroll") for (int _i = 0; _i < 2; ++_i) \
;         __builtin_amdgcn_global_load_lds((const unsigned*)((const char*)(gbase) + (voff)[_i]), (PG8_LAS unsigned*)(lds + (bufoff) + ldsw + _i * 8192), 16, 0, 0); } while (0)
; #define PG8_LDA(dst, b, h) do { _Pragma("unroll") for (int m = 0; m < 4; ++m) _Pragma("unroll") for (int k = 0; k < 2; ++k) dst[m][k] = *(const PG8_LAS bf16x8*)(lds + PG8_SA(b, h) + aoff + m * 2048 + k * 1024); } while (0)
; #define PG8_LDB(dst, b, h) do { _Pragma("unroll") for (int n = 0; n < 2; ++n) _Pragma("unroll") for (int k = 0; k < 2; ++k) dst[n][k] = *(const PG8_LAS bf16x8*)(lds + PG8_SB(b, h) + boff + n * 2048 + k * 1024); } while (0)
; #define PG8_MMA(ai, bj, At, Bt) do { __builtin_amdgcn_s_setprio(1); _Pragma("unroll") for (int m = 0; m < 4; ++m) _Pragma("unroll") for (int n = 0; n < 2; ++n) _Pragma("unroll") for (int k = 0; k < 2; ++k) \
;         acc[ai][bj][m][n] = __builtin_amdgcn_mfma_f32_16x16x32_bf16(Bt[n][k], At[m][k], acc[ai][bj][m][n], 0, 0, 0); __builtin_amdgcn_s_setprio(0); } while (0)
; #define PG8_WAIT_V(n) asm volatile("s_waitcnt vmcnt(" #n ")" ::: "memory")
; #define PG8_WAIT_L(n) asm volatile("s_waitcnt lgkmcnt(" #n ")" ::: "memory")
; #define PG8_BAR __builtin_amdgcn_s_barrier()
; template <class Epi, class Sched, bool ALIGN_EPI = false, bool SP2 = false>
; __device__ __forceinline__ void gemm_phase(PG8_LAS unsigned char* lds, const Gemm g, const Sched& S, const Epi& E) {
;     ...
;             const bool last = (t == nt - 2);
;             const char* a1 = cA + (size_t)(t + 1) * kstep;
;             const char* a2 = last ? nA : cA + (size_t)(t + 2) * kstep; const char* b2 = last ? nB : cB + (size_t)(t + 2) * kstep;
;             const char* a3 = a2 + kstep; const char* b3 = b2 + kstep;
;             if (last && has_next) S.a_ready(nxt);
;             if (last) E.prefetch(lds + 139264, cur, wid, lane);
;             if constexpr (SP2) {
;             PG8_LDB(B0, 0, 0); PG8_LDB(B1, 0, 1); PG8_SCHED; PG8_LDA(At, 0, 0); PG8_STAGE(PG8_SA(1, 1), a1 + hstep, voffA);
;             PG8_WAIT_V(8); PG8_WAIT_L(0); PG8_BAR; PG8_MMA(0, 0, At, B0); PG8_MMA(0, 1, At, B1); PG8_BAR; PG8_SCHED;
;             PG8_LDA(At, 0, 1); PG8_STAGE(PG8_SB(0, 0), b2, voffB); PG8_STAGE(PG8_SB(0, 1), b2 + hstep, voffB); PG8_STAGE(PG8_SA(0, 0), a2, voffA);
.LBB0_960:
	v_add_u32_e32 v130, s89, v169
	ds_read_b128 v[150:153], v130
	ds_read_b128 v[158:161], v130 offset:1024
	ds_read_b128 v[162:165], v130 offset:2048
	ds_read_b128 v[196:199], v130 offset:3072
	v_add_u32_e32 v130, s90, v169
	ds_read_b128 v[200:203], v130
	ds_read_b128 v[204:207], v130 offset:1024
	ds_read_b128 v[208:211], v130 offset:2048
	ds_read_b128 v[212:215], v130 offset:3072
	s_add_u32 s12, s10, 0xfffc0080
	s_addc_u32 s13, s11, -1
	s_and_b64 s[66:67], s[66:67], exec
	s_cselect_b32 s69, s57, s13
	s_cselect_b32 s68, s63, s12
	s_cselect_b32 s67, s55, s71
	s_cselect_b32 s66, s70, s65
	s_add_i32 m0, s75, 0xc000
	ds_read_b128 v[216:219], v191
	ds_read_b128 v[220:223], v191 offset:1024
	ds_read_b128 v[224:227], v191 offset:2048
	ds_read_b128 v[228:231], v191 offset:3072
	ds_read_b128 v[232:235], v191 offset:4096
	ds_read_b128 v[236:239], v191 offset:5120
	ds_read_b128 v[240:243], v191 offset:6144
	ds_read_b128 v[244:247], v191 offset:7168
	global_load_lds_dwordx4 v142, s[10:11]
	s_add_i32 m0, s75, 0xe000
	s_nop 0
	global_load_lds_dwordx4 v140, s[10:11]
	s_waitcnt vmcnt(8)
	s_waitcnt lgkmcnt(0)
	s_barrier
	v_mfma_f32_16x16x32_bf16 v[124:127], v[150:153], v[216:219], v[124:127]
	v_mfma_f32_16x16x32_bf16 v[124:127], v[158:161], v[220:223], v[124:127]
	v_mfma_f32_16x16x32_bf16 v[120:123], v[162:165], v[216:219], v[120:123]
	v_mfma_f32_16x16x32_bf16 v[120:123], v[196:199], v[220:223], v[120:123]
	v_mfma_f32_16x16x32_bf16 v[104:107], v[162:165], v[224:227], v[104:107]
	v_mfma_f32_16x16x32_bf16 v[104:107], v[196:199], v[228:231], v[104:107]
	v_mfma_f32_16x16x32_bf16 v[112:115], v[150:153], v[224:227], v[112:115]
	v_mfma_f32_16x16x32_bf16 v[112:115], v[158:161], v[228:231], v[112:115]
	v_mfma_f32_16x16x32_bf16 v[100:103], v[150:153], v[232:235], v[100:103]
	v_mfma_f32_16x16x32_bf16 v[100:103], v[158:161], v[236:239], v[100:103]
	v_mfma_f32_16x16x32_bf16 v[96:99], v[162:165], v[232:235], v[96:99]
	v_mfma_f32_16x16x32_bf16 v[96:99], v[196:199], v[236:239], v[96:99]
	v_mfma_f32_16x16x32_bf16 v[72:75], v[162:165], v[240:243], v[72:75]
	v_mfma_f32_16x16x32_bf16 v[72:75], v[196:199], v[244:247], v[72:75]
	v_mfma_f32_16x16x32_bf16 v[80:83], v[150:153], v[240:243], v[80:83]
	v_mfma_f32_16x16x32_bf16 v[80:83], v[158:161], v[244:247], v[80:83]
	v_mfma_f32_16x16x32_bf16 v[116:119], v[200:203], v[216:219], v[116:119]
	v_mfma_f32_16x16x32_bf16 v[116:119], v[204:207], v[220:223], v[116:119]
	v_mfma_f32_16x16x32_bf16 v[108:111], v[208:211], v[216:219], v[108:111]
	v_mfma_f32_16x16x32_bf16 v[108:111], v[212:215], v[220:223], v[108:111]
	v_mfma_f32_16x16x32_bf16 v[88:91], v[208:211], v[224:227], v[88:91]
	v_mfma_f32_16x16x32_bf16 v[88:91], v[212:215], v[228:231], v[88:91]
	v_mfma_f32_16x16x32_bf16 v[92:95], v[200:203], v[224:227], v[92:95]
	v_mfma_f32_16x16x32_bf16 v[92:95], v[204:207], v[228:231], v[92:95]
	v_mfma_f32_16x16x32_bf16 v[84:87], v[200:203], v[232:235], v[84:87]
	v_mfma_f32_16x16x32_bf16 v[84:87], v[204:207], v[236:239], v[84:87]
	v_mfma_f32_16x16x32_bf16 v[76:79], v[208:211], v[232:235], v[76:79]
	v_mfma_f32_16x16x32_bf16 v[76:79], v[212:215], v[236:239], v[76:79]
	v_mfma_f32_16x16x32_bf16 v[64:67], v[208:211], v[240:243], v[64:67]
	v_mfma_f32_16x16x32_bf16 v[64:67], v[212:215], v[244:247], v[64:67]
	v_mfma_f32_16x16x32_bf16 v[68:71], v[200:203], v[240:243], v[68:71]
	v_mfma_f32_16x16x32_bf16 v[68:71], v[204:207], v[244:247], v[68:71]
	s_barrier
	s_add_i32 s12, s89, s74
	s_mov_b32 m0, s12
	ds_read_b128 v[216:219], v191 offset:16384
	ds_read_b128 v[220:223], v191 offset:17408
	ds_read_b128 v[224:227], v191 offset:18432
	ds_read_b128 v[228:231], v191 offset:19456
	ds_read_b128 v[232:235], v191 offset:20480
	ds_read_b128 v[236:239], v191 offset:21504
	ds_read_b128 v[240:243], v191 offset:22528
	ds_read_b128 v[244:247], v191 offset:23552
	global_load_lds_dwordx4 v134, s[66:67]
	s_add_i32 m0, s12, 0x2000
	s_add_u32 vcc_lo, s66, 0x40000
	v_lshl_add_u64 v[154:155], s[66:67], 0, v[138:139]
	s_addc_u32 vcc_hi, s67, 0
	s_add_i32 s12, s90, s74
	global_load_lds_dwordx4 v138, s[66:67]
	v_lshl_add_u64 v[166:167], vcc, 0, v[134:135]
	s_mov_b32 m0, s12
	v_lshl_add_u64 v[248:249], s[68:69], 0, v[136:137]
	global_load_lds_dwordx4 v[166:167], off
	v_lshl_add_u64 v[166:167], vcc, 0, v[138:139]
	s_add_i32 m0, s12, 0x2000
	s_nop 0
	global_load_lds_dwordx4 v[166:167], off
	v_lshl_add_u64 v[166:167], s[68:69], 0, v[132:133]
	s_mov_b32 m0, s75
	s_nop 0
	global_load_lds_dwordx4 v132, s[68:69]
	s_mov_b32 m0, s76
	s_nop 0
	global_load_lds_dwordx4 v136, s[68:69]
	s_waitcnt vmcnt(8)
	s_waitcnt lgkmcnt(0)
	s_barrier
; #define PG8_STAGE(bufoff, gbase, voff) do { _Pragma("unroll") for (int _i = 0; _i < 2; ++_i) \
;         __builtin_amdgcn_global_load_lds((const unsigned*)((const char*)(gbase) + (voff)[_i]), (PG8_LAS unsigned*)(lds + (bufoff) + ldsw + _i * 8192), 16, 0, 0); } while (0)
; #define PG8_LDA(dst, b, h) do { _Pragma("unroll") for (int m = 0; m < 4; ++m) _Pragma("unroll") for (int k = 0; k < 2; ++k) dst[m][k] = *(const PG8_LAS bf16x8*)(lds + PG8_SA(b, h) + aoff + m * 2048 + k * 1024); } while (0)
; #define PG8_LDB(dst, b, h) do { _Pragma("unroll") for (int n = 0; n < 2; ++n) _Pragma("unroll") for (int k = 0; k < 2; ++k) dst[n][k] = *(const PG8_LAS bf16x8*)(lds + PG8_SB(b, h) + boff + n * 2048 + k * 1024); } while (0)
; #define PG8_MMA(ai, bj, At, Bt) do { __builtin_amdgcn_s_setprio(1); _Pragma("unroll") for (int m = 0; m < 4; ++m) _Pragma("unroll") for (int n = 0; n < 2; ++n) _Pragma("unroll") for (int k = 0; k < 2; ++k) \
;         acc[ai][bj][m][n] = __builtin_amdgcn_mfma_f32_16x16x32_bf16(Bt[n][k], At[m][k], acc[ai][bj][m][n], 0, 0, 0); __builtin_amdgcn_s_setprio(0); } while (0)
; #define PG8_WAIT_V(n) asm volatile("s_waitcnt vmcnt(" #n ")" ::: "memory")
; #define PG8_WAIT_L(n) asm volatile("s_waitcnt lgkmcnt(" #n ")" ::: "memory")
; #define PG8_BAR __builtin_amdgcn_s_barrier()
; #define PG8_SCHED __builtin_amdgcn_sched_barrier(0)
; template <class Epi, class Sched, bool ALIGN_EPI = false, bool SP2 = false>
; __device__ __forceinline__ void gemm_phase(PG8_LAS unsigned char* lds, const Gemm g, const Sched& S, const Epi& E) {
;     ...
;             PG8_WAIT_V(8); PG8_WAIT_L(0); PG8_BAR; PG8_MMA(0, 0, At, B0); PG8_MMA(0, 1, At, B1); PG8_BAR; PG8_SCHED;
;             PG8_LDA(At, 0, 1); PG8_STAGE(PG8_SB(0, 0), b2, voffB); PG8_STAGE(PG8_SB(0, 1), b2 + hstep, voffB); PG8_STAGE(PG8_SA(0, 0), a2, voffA);
;             PG8_WAIT_V(8); PG8_WAIT_L(0); PG8_BAR; PG8_MMA(1, 0, At, B0); PG8_MMA(1, 1, At, B1); PG8_BAR; PG8_SCHED;
;             PG8_LDB(B0, 1, 0); PG8_LDB(B1, 1, 1); PG8_SCHED; PG8_LDA(At, 1, 0); PG8_STAGE(PG8_SA(0, 1), a2 + hstep, voffA);
;             PG8_WAIT_V(8); PG8_WAIT_L(0); PG8_BAR; PG8_MMA(0, 0, At, B0); PG8_MMA(0, 1, At, B1); PG8_BAR; PG8_SCHED;
	v_mfma_f32_16x16x32_bf16 v[60:63], v[150:153], v[216:219], v[60:63]
	v_mfma_f32_16x16x32_bf16 v[60:63], v[158:161], v[220:223], v[60:63]
	v_mfma_f32_16x16x32_bf16 v[56:59], v[162:165], v[216:219], v[56:59]
	v_mfma_f32_16x16x32_bf16 v[56:59], v[196:199], v[220:223], v[56:59]
	v_mfma_f32_16x16x32_bf16 v[40:43], v[162:165], v[224:227], v[40:43]
	v_mfma_f32_16x16x32_bf16 v[40:43], v[196:199], v[228:231], v[40:43]
	v_mfma_f32_16x16x32_bf16 v[48:51], v[150:153], v[224:227], v[48:51]
	v_mfma_f32_16x16x32_bf16 v[48:51], v[158:161], v[228:231], v[48:51]
	v_mfma_f32_16x16x32_bf16 v[36:39], v[150:153], v[232:235], v[36:39]
	v_mfma_f32_16x16x32_bf16 v[36:39], v[158:161], v[236:239], v[36:39]
	v_mfma_f32_16x16x32_bf16 v[32:35], v[162:165], v[232:235], v[32:35]
	v_mfma_f32_16x16x32_bf16 v[32:35], v[196:199], v[236:239], v[32:35]
	v_mfma_f32_16x16x32_bf16 v[16:19], v[162:165], v[240:243], v[16:19]
	v_mfma_f32_16x16x32_bf16 v[16:19], v[196:199], v[244:247], v[16:19]
	v_mfma_f32_16x16x32_bf16 v[20:23], v[150:153], v[240:243], v[20:23]
	v_mfma_f32_16x16x32_bf16 v[20:23], v[158:161], v[244:247], v[20:23]
	v_mfma_f32_16x16x32_bf16 v[52:55], v[200:203], v[216:219], v[52:55]
	v_mfma_f32_16x16x32_bf16 v[52:55], v[204:207], v[220:223], v[52:55]
	v_mfma_f32_16x16x32_bf16 v[44:47], v[208:211], v[216:219], v[44:47]
	v_mfma_f32_16x16x32_bf16 v[44:47], v[212:215], v[220:223], v[44:47]
	v_mfma_f32_16x16x32_bf16 v[24:27], v[208:211], v[224:227], v[24:27]
	v_mfma_f32_16x16x32_bf16 v[24:27], v[212:215], v[228:231], v[24:27]
	v_mfma_f32_16x16x32_bf16 v[28:31], v[200:203], v[224:227], v[28:31]
	v_mfma_f32_16x16x32_bf16 v[28:31], v[204:207], v[228:231], v[28:31]
	v_mfma_f32_16x16x32_bf16 v[12:15], v[200:203], v[232:235], v[12:15]
	v_mfma_f32_16x16x32_bf16 v[12:15], v[204:207], v[236:239], v[12:15]
	v_mfma_f32_16x16x32_bf16 v[8:11], v[208:211], v[232:235], v[8:11]
	v_mfma_f32_16x16x32_bf16 v[8:11], v[212:215], v[236:239], v[8:11]
	v_mfma_f32_16x16x32_bf16 v[0:3], v[208:211], v[240:243], v[0:3]
	v_mfma_f32_16x16x32_bf16 v[0:3], v[212:215], v[244:247], v[0:3]
	v_mfma_f32_16x16x32_bf16 v[4:7], v[200:203], v[240:243], v[4:7]
	v_mfma_f32_16x16x32_bf16 v[4:7], v[204:207], v[244:247], v[4:7]
	s_barrier
	s_add_i32 s12, 0, 0x18000
	v_add_u32_e32 v195, s12, v169
	s_add_i32 s13, 0, 0x1c000
	ds_read_b128 v[150:153], v195
	ds_read_b128 v[158:161], v195 offset:1024
	ds_read_b128 v[162:165], v195 offset:2048
	ds_read_b128 v[196:199], v195 offset:3072
	v_add_u32_e32 v195, s13, v169
	ds_read_b128 v[200:203], v195
	ds_read_b128 v[204:207], v195 offset:1024
	ds_read_b128 v[208:211], v195 offset:2048
	ds_read_b128 v[212:215], v195 offset:3072
	s_add_u32 s68, s68, 0x40000
	s_addc_u32 s69, s69, 0
	s_mov_b32 m0, s77
	ds_read_b128 v[216:219], v191 offset:32768
	ds_read_b128 v[220:223], v191 offset:33792
	ds_read_b128 v[224:227], v191 offset:34816
	ds_read_b128 v[228:231], v191 offset:35840
	ds_read_b128 v[232:235], v191 offset:36864
	ds_read_b128 v[236:239], v191 offset:37888
	ds_read_b128 v[240:243], v191 offset:38912
	ds_read_b128 v[244:247], v191 offset:39936
	global_load_lds_dwordx4 v132, s[68:69]
	s_mov_b32 m0, s78
	s_nop 0
	global_load_lds_dwordx4 v136, s[68:69]
	s_waitcnt vmcnt(8)
	s_waitcnt lgkmcnt(0)
	s_barrier
	v_mfma_f32_16x16x32_bf16 v[124:127], v[150:153], v[216:219], v[124:127]
	v_mfma_f32_16x16x32_bf16 v[124:127], v[158:161], v[220:223], v[124:127]
	v_mfma_f32_16x16x32_bf16 v[120:123], v[162:165], v[216:219], v[120:123]
	v_mfma_f32_16x16x32_bf16 v[120:123], v[196:199], v[220:223], v[120:123]
	v_mfma_f32_16x16x32_bf16 v[104:107], v[162:165], v[224:227], v[104:107]
	v_mfma_f32_16x16x32_bf16 v[104:107], v[196:199], v[228:231], v[104:107]
	v_mfma_f32_16x16x32_bf16 v[112:115], v[150:153], v[224:227], v[112:115]
	v_mfma_f32_16x16x32_bf16 v[112:115], v[158:161], v[228:231], v[112:115]
	v_mfma_f32_16x16x32_bf16 v[100:103], v[150:153], v[232:235], v[100:103]
	v_mfma_f32_16x16x32_bf16 v[100:103], v[158:161], v[236:239], v[100:103]
	v_mfma_f32_16x16x32_bf16 v[96:99], v[162:165], v[232:235], v[96:99]
	v_mfma_f32_16x16x32_bf16 v[96:99], v[196:199], v[236:239], v[96:99]
	v_mfma_f32_16x16x32_bf16 v[72:75], v[162:165], v[240:243], v[72:75]
	v_mfma_f32_16x16x32_bf16 v[72:75], v[196:199], v[244:247], v[72:75]
	v_mfma_f32_16x16x32_bf16 v[80:83], v[150:153], v[240:243], v[80:83]
	v_mfma_f32_16x16x32_bf16 v[80:83], v[158:161], v[244:247], v[80:83]
	v_mfma_f32_16x16x32_bf16 v[116:119], v[200:203], v[216:219], v[116:119]
	v_mfma_f32_16x16x32_bf16 v[116:119], v[204:207], v[220:223], v[116:119]
	v_mfma_f32_16x16x32_bf16 v[108:111], v[208:211], v[216:219], v[108:111]
	v_mfma_f32_16x16x32_bf16 v[108:111], v[212:215], v[220:223], v[108:111]
	v_mfma_f32_16x16x32_bf16 v[88:91], v[208:211], v[224:227], v[88:91]
	v_mfma_f32_16x16x32_bf16 v[88:91], v[212:215], v[228:231], v[88:91]
	v_mfma_f32_16x16x32_bf16 v[92:95], v[200:203], v[224:227], v[92:95]
	v_mfma_f32_16x16x32_bf16 v[92:95], v[204:207], v[228:231], v[92:95]
	v_mfma_f32_16x16x32_bf16 v[84:87], v[200:203], v[232:235], v[84:87]
	v_mfma_f32_16x16x32_bf16 v[84:87], v[204:207], v[236:239], v[84:87]
	v_mfma_f32_16x16x32_bf16 v[76:79], v[208:211], v[232:235], v[76:79]
	v_mfma_f32_16x16x32_bf16 v[76:79], v[212:215], v[236:239], v[76:79]
	v_mfma_f32_16x16x32_bf16 v[64:67], v[208:211], v[240:243], v[64:67]
	v_mfma_f32_16x16x32_bf16 v[64:67], v[212:215], v[244:247], v[64:67]
	v_mfma_f32_16x16x32_bf16 v[68:71], v[200:203], v[240:243], v[68:71]
	v_mfma_f32_16x16x32_bf16 v[68:71], v[204:207], v[244:247], v[68:71]
	s_barrier
; #define PG8_STAGE(bufoff, gbase, voff) do { _Pragma("unroll") for (int _i = 0; _i < 2; ++_i) \
;         __builtin_amdgcn_global_load_lds((const unsigned*)((const char*)(gbase) + (voff)[_i]), (PG8_LAS unsigned*)(lds + (bufoff) + ldsw + _i * 8192), 16, 0, 0); } while (0)
; #define PG8_LDA(dst, b, h) do { _Pragma("unroll") for (int m = 0; m < 4; ++m) _Pragma("unroll") for (int k = 0; k < 2; ++k) dst[m][k] = *(const PG8_LAS bf16x8*)(lds + PG8_SA(b, h) + aoff + m * 2048 + k * 1024); } while (0)
; #define PG8_MMA(ai, bj, At, Bt) do { __builtin_amdgcn_s_setprio(1); _Pragma("unroll") for (int m = 0; m < 4; ++m) _Pragma("unroll") for (int n = 0; n < 2; ++n) _Pragma("unroll") for (int k = 0; k < 2; ++k) \
;         acc[ai][bj][m][n] = __builtin_amdgcn_mfma_f32_16x16x32_bf16(Bt[n][k], At[m][k], acc[ai][bj][m][n], 0, 0, 0); __builtin_amdgcn_s_setprio(0); } while (0)
; #define PG8_WAIT_V(n) asm volatile("s_waitcnt vmcnt(" #n ")" ::: "memory")
; #define PG8_WAIT_L(n) asm volatile("s_waitcnt lgkmcnt(" #n ")" ::: "memory")
; #define PG8_BAR __builtin_amdgcn_s_barrier()
; #define PG8_SCHED __builtin_amdgcn_sched_barrier(0)
; template <class Epi, class Sched, bool ALIGN_EPI = false, bool SP2 = false>
; __device__ __forceinline__ void gemm_phase(PG8_LAS unsigned char* lds, const Gemm g, const Sched& S, const Epi& E) {
;     ...
;             PG8_LDA(At, 1, 1); PG8_STAGE(PG8_SB(1, 0), b3, voffB); PG8_STAGE(PG8_SB(1, 1), b3 + hstep, voffB); PG8_STAGE(PG8_SA(1, 0), a3, voffA);
;             PG8_WAIT_V(8); PG8_WAIT_L(0); PG8_BAR; PG8_MMA(1, 0, At, B0); PG8_MMA(1, 1, At, B1); PG8_BAR; PG8_SCHED;
	s_add_i32 s12, s12, s74
	s_add_u32 s98, s66, s42
	s_addc_u32 s99, s67, s43
	s_mov_b32 m0, s12
	ds_read_b128 v[216:219], v191 offset:49152
	ds_read_b128 v[220:223], v191 offset:50176
	ds_read_b128 v[224:227], v191 offset:51200
	ds_read_b128 v[228:231], v191 offset:52224
	ds_read_b128 v[232:235], v191 offset:53248
	ds_read_b128 v[236:239], v191 offset:54272
	ds_read_b128 v[240:243], v191 offset:55296
	ds_read_b128 v[244:247], v191 offset:56320
	global_load_lds_dwordx4 v134, s[98:99]
	s_add_i32 m0, s12, 0x2000
	s_add_u32 s66, s66, 0x40080
	v_lshl_add_u64 v[130:131], v[154:155], 0, s[42:43]
	s_addc_u32 s67, s67, 0
	s_add_i32 s12, s13, s74
	global_load_lds_dwordx4 v[130:131], off
	s_mov_b32 m0, s12
	s_nop 0
	global_load_lds_dwordx4 v134, s[66:67]
	s_add_i32 m0, s12, 0x2000
	s_nop 0
	global_load_lds_dwordx4 v138, s[66:67]
	v_lshl_add_u64 v[130:131], v[166:167], 0, s[42:43]
	s_mov_b32 m0, s79
	s_nop 0
	global_load_lds_dwordx4 v[130:131], off
	v_lshl_add_u64 v[130:131], v[248:249], 0, s[42:43]
	s_mov_b32 m0, s80
	s_nop 0
	global_load_lds_dwordx4 v[130:131], off
	s_waitcnt vmcnt(8)
	s_waitcnt lgkmcnt(0)
	s_barrier
	v_mfma_f32_16x16x32_bf16 v[60:63], v[150:153], v[216:219], v[60:63]
	v_mfma_f32_16x16x32_bf16 v[60:63], v[158:161], v[220:223], v[60:63]
	v_mfma_f32_16x16x32_bf16 v[56:59], v[162:165], v[216:219], v[56:59]
	v_mfma_f32_16x16x32_bf16 v[56:59], v[196:199], v[220:223], v[56:59]
	v_mfma_f32_16x16x32_bf16 v[40:43], v[162:165], v[224:227], v[40:43]
	v_mfma_f32_16x16x32_bf16 v[40:43], v[196:199], v[228:231], v[40:43]
	v_mfma_f32_16x16x32_bf16 v[48:51], v[150:153], v[224:227], v[48:51]
	v_mfma_f32_16x16x32_bf16 v[48:51], v[158:161], v[228:231], v[48:51]
	v_mfma_f32_16x16x32_bf16 v[36:39], v[150:153], v[232:235], v[36:39]
	v_mfma_f32_16x16x32_bf16 v[36:39], v[158:161], v[236:239], v[36:39]
	v_mfma_f32_16x16x32_bf16 v[32:35], v[162:165], v[232:235], v[32:35]
	v_mfma_f32_16x16x32_bf16 v[32:35], v[196:199], v[236:239], v[32:35]
	v_mfma_f32_16x16x32_bf16 v[16:19], v[162:165], v[240:243], v[16:19]
	v_mfma_f32_16x16x32_bf16 v[16:19], v[196:199], v[244:247], v[16:19]
	v_mfma_f32_16x16x32_bf16 v[20:23], v[150:153], v[240:243], v[20:23]
	v_mfma_f32_16x16x32_bf16 v[20:23], v[158:161], v[244:247], v[20:23]
	v_mfma_f32_16x16x32_bf16 v[52:55], v[200:203], v[216:219], v[52:55]
	v_mfma_f32_16x16x32_bf16 v[52:55], v[204:207], v[220:223], v[52:55]
	v_mfma_f32_16x16x32_bf16 v[44:47], v[208:211], v[216:219], v[44:47]
	v_mfma_f32_16x16x32_bf16 v[44:47], v[212:215], v[220:223], v[44:47]
	v_mfma_f32_16x16x32_bf16 v[24:27], v[208:211], v[224:227], v[24:27]
	v_mfma_f32_16x16x32_bf16 v[24:27], v[212:215], v[228:231], v[24:27]
	v_mfma_f32_16x16x32_bf16 v[28:31], v[200:203], v[224:227], v[28:31]
	v_mfma_f32_16x16x32_bf16 v[28:31], v[204:207], v[228:231], v[28:31]
	v_mfma_f32_16x16x32_bf16 v[12:15], v[200:203], v[232:235], v[12:15]
	v_mfma_f32_16x16x32_bf16 v[12:15], v[204:207], v[236:239], v[12:15]
	v_mfma_f32_16x16x32_bf16 v[8:11], v[208:211], v[232:235], v[8:11]
	v_mfma_f32_16x16x32_bf16 v[8:11], v[212:215], v[236:239], v[8:11]
	v_mfma_f32_16x16x32_bf16 v[0:3], v[208:211], v[240:243], v[0:3]
	v_mfma_f32_16x16x32_bf16 v[0:3], v[212:215], v[244:247], v[0:3]
	v_mfma_f32_16x16x32_bf16 v[4:7], v[200:203], v[240:243], v[4:7]
	v_mfma_f32_16x16x32_bf16 v[4:7], v[204:207], v[244:247], v[4:7]
	s_barrier
	s_add_i32 s96, s96, 2
	s_add_u32 s65, s65, 0x100
	s_addc_u32 s71, s71, 0
	s_add_u32 s10, s10, 0x100
	s_addc_u32 s11, s11, 0
	s_cmp_gt_u32 s96, 13
	s_cbranch_scc1 .LBB0_963

; #define PG8_STAGE(bufoff, gbase, voff) do { _Pragma("unroll") for (int _i = 0; _i < 2; ++_i) \
;         __builtin_amdgcn_global_load_lds((const unsigned*)((const char*)(gbase) + (voff)[_i]), (PG8_LAS unsigned*)(lds + (bufoff) + ldsw + _i * 8192), 16, 0, 0); } while (0)
; #define PG8_LDA(dst, b, h) do { _Pragma("unroll") for (int m = 0; m < 4; ++m) _Pragma("unroll") for (int k = 0; k < 2; ++k) dst[m][k] = *(const PG8_LAS bf16x8*)(lds + PG8_SA(b, h) + aoff + m * 2048 + k * 1024); } while (0)
; #define PG8_LDB(dst, b, h) do { _Pragma("unroll") for (int n = 0; n < 2; ++n) _Pragma("unroll") for (int k = 0; k < 2; ++k) dst[n][k] = *(const PG8_LAS bf16x8*)(lds + PG8_SB(b, h) + boff + n * 2048 + k * 1024); } while (0)
; #define PG8_MMA(ai, bj, At, Bt) do { __builtin_amdgcn_s_setprio(1); _Pragma("unroll") for (int m = 0; m < 4; ++m) _Pragma("unroll") for (int n = 0; n < 2; ++n) _Pragma("unroll") for (int k = 0; k < 2; ++k) \
;         acc[ai][bj][m][n] = __builtin_amdgcn_mfma_f32_16x16x32_bf16(Bt[n][k], At[m][k], acc[ai][bj][m][n], 0, 0, 0); __builtin_amdgcn_s_setprio(0); } while (0)
; #define PG8_WAIT_V(n) asm volatile("s_waitcnt vmcnt(" #n ")" ::: "memory")
; #define PG8_BAR __builtin_amdgcn_s_barrier()
; template <class Epi, class Sched, bool ALIGN_EPI = false, bool SP2 = false>
; __device__ __forceinline__ void gemm_phase(PG8_LAS unsigned char* lds, const Gemm g, const Sched& S, const Epi& E) {
;     ...
;             const bool last = (t == nt - 2);
;             const char* a1 = cA + (size_t)(t + 1) * kstep;
;             const char* a2 = last ? nA : cA + (size_t)(t + 2) * kstep; const char* b2 = last ? nB : cB + (size_t)(t + 2) * kstep;
;             const char* a3 = a2 + kstep; const char* b3 = b2 + kstep;
;             if (last && has_next) S.a_ready(nxt);
;             if (last) E.prefetch(lds + 139264, cur, wid, lane);
;             if constexpr (SP2) {
;             PG8_LDB(B0, 0, 0); PG8_LDB(B1, 0, 1); PG8_SCHED; PG8_LDA(At, 0, 0); PG8_STAGE(PG8_SA(1, 1), a1 + hstep, voffA);
;             PG8_WAIT_V(8); PG8_WAIT_L(0); PG8_BAR; PG8_MMA(0, 0, At, B0); PG8_MMA(0, 1, At, B1); PG8_BAR; PG8_SCHED;
;             PG8_LDA(At, 0, 1); PG8_STAGE(PG8_SB(0, 0), b2, voffB); PG8_STAGE(PG8_SB(0, 1), b2 + hstep, voffB); PG8_STAGE(PG8_SA(0, 0), a2, voffA);
;             PG8_WAIT_V(8); PG8_WAIT_L(0); PG8_BAR; PG8_MMA(1, 0, At, B0); PG8_MMA(1, 1, At, B1); PG8_BAR; PG8_SCHED;
.LBB0_1272:
	ds_read_b128 v[128:131], v167
	ds_read_b128 v[132:135], v167 offset:1024
	ds_read_b128 v[136:139], v167 offset:2048
	ds_read_b128 v[140:143], v167 offset:3072
	ds_read_b128 v[160:163], v168
	ds_read_b128 v[170:173], v168 offset:1024
	ds_read_b128 v[174:177], v168 offset:2048
	ds_read_b128 v[178:181], v168 offset:3072
	s_add_u32 s12, s50, 0xfffc0080
	s_addc_u32 s13, s51, -1
	s_cmp_eq_u32 s79, 12
	s_cselect_b32 s55, s41, s13
	s_cselect_b32 s54, s47, s12
	s_cselect_b32 s53, s39, s78
	s_cselect_b32 s52, s49, s77
	s_add_i32 m0, s60, 0xc000
	ds_read_b128 v[188:191], v169
	ds_read_b128 v[192:195], v169 offset:1024
	ds_read_b128 v[196:199], v169 offset:2048
	ds_read_b128 v[200:203], v169 offset:3072
	ds_read_b128 v[204:207], v169 offset:4096
	ds_read_b128 v[208:211], v169 offset:5120
	ds_read_b128 v[212:215], v169 offset:6144
	ds_read_b128 v[216:219], v169 offset:7168
	global_load_lds_dwordx4 v154, s[50:51]
	s_add_i32 m0, s60, 0xe000
	s_nop 0
	global_load_lds_dwordx4 v152, s[50:51]
	s_waitcnt vmcnt(8)
	s_waitcnt lgkmcnt(0)
	s_barrier
	v_mfma_f32_16x16x32_bf16 v[124:127], v[128:131], v[188:191], v[124:127]
	v_mfma_f32_16x16x32_bf16 v[124:127], v[132:135], v[192:195], v[124:127]
	v_mfma_f32_16x16x32_bf16 v[120:123], v[136:139], v[188:191], v[120:123]
	v_mfma_f32_16x16x32_bf16 v[120:123], v[140:143], v[192:195], v[120:123]
	v_mfma_f32_16x16x32_bf16 v[108:111], v[136:139], v[196:199], v[108:111]
	v_mfma_f32_16x16x32_bf16 v[108:111], v[140:143], v[200:203], v[108:111]
	v_mfma_f32_16x16x32_bf16 v[116:119], v[128:131], v[196:199], v[116:119]
	v_mfma_f32_16x16x32_bf16 v[116:119], v[132:135], v[200:203], v[116:119]
	v_mfma_f32_16x16x32_bf16 v[100:103], v[128:131], v[204:207], v[100:103]
	v_mfma_f32_16x16x32_bf16 v[100:103], v[132:135], v[208:211], v[100:103]
	v_mfma_f32_16x16x32_bf16 v[92:95], v[136:139], v[204:207], v[92:95]
	v_mfma_f32_16x16x32_bf16 v[92:95], v[140:143], v[208:211], v[92:95]
	v_mfma_f32_16x16x32_bf16 v[76:79], v[136:139], v[212:215], v[76:79]
	v_mfma_f32_16x16x32_bf16 v[76:79], v[140:143], v[216:219], v[76:79]
	v_mfma_f32_16x16x32_bf16 v[84:87], v[128:131], v[212:215], v[84:87]
	v_mfma_f32_16x16x32_bf16 v[84:87], v[132:135], v[216:219], v[84:87]
	v_mfma_f32_16x16x32_bf16 v[112:115], v[160:163], v[188:191], v[112:115]
	v_mfma_f32_16x16x32_bf16 v[112:115], v[170:173], v[192:195], v[112:115]
	v_mfma_f32_16x16x32_bf16 v[104:107], v[174:177], v[188:191], v[104:107]
	v_mfma_f32_16x16x32_bf16 v[104:107], v[178:181], v[192:195], v[104:107]
	v_mfma_f32_16x16x32_bf16 v[88:91], v[174:177], v[196:199], v[88:91]
	v_mfma_f32_16x16x32_bf16 v[88:91], v[178:181], v[200:203], v[88:91]
	v_mfma_f32_16x16x32_bf16 v[96:99], v[160:163], v[196:199], v[96:99]
	v_mfma_f32_16x16x32_bf16 v[96:99], v[170:173], v[200:203], v[96:99]
	v_mfma_f32_16x16x32_bf16 v[80:83], v[160:163], v[204:207], v[80:83]
	v_mfma_f32_16x16x32_bf16 v[80:83], v[170:173], v[208:211], v[80:83]
	v_mfma_f32_16x16x32_bf16 v[72:75], v[174:177], v[204:207], v[72:75]
	v_mfma_f32_16x16x32_bf16 v[72:75], v[178:181], v[208:211], v[72:75]
	v_mfma_f32_16x16x32_bf16 v[64:67], v[174:177], v[212:215], v[64:67]
	v_mfma_f32_16x16x32_bf16 v[64:67], v[178:181], v[216:219], v[64:67]
	v_mfma_f32_16x16x32_bf16 v[68:71], v[160:163], v[212:215], v[68:71]
	v_mfma_f32_16x16x32_bf16 v[68:71], v[170:173], v[216:219], v[68:71]
	s_barrier
	s_add_i32 s12, s75, s59
	s_mov_b32 m0, s12
	ds_read_b128 v[188:191], v169 offset:16384
	ds_read_b128 v[192:195], v169 offset:17408
	ds_read_b128 v[196:199], v169 offset:18432
	ds_read_b128 v[200:203], v169 offset:19456
	ds_read_b128 v[204:207], v169 offset:20480
	ds_read_b128 v[208:211], v169 offset:21504
	ds_read_b128 v[212:215], v169 offset:22528
	ds_read_b128 v[216:219], v169 offset:23552
	global_load_lds_dwordx4 v146, s[52:53]
	s_add_i32 m0, s12, 0x2000
	s_add_u32 s80, s52, 0x40000
	v_lshl_add_u64 v[220:221], s[52:53], 0, v[150:151]
	s_addc_u32 s81, s53, 0
	s_add_i32 s12, s76, s59
	global_load_lds_dwordx4 v150, s[52:53]
	s_mov_b32 m0, s12
	v_lshl_add_u64 v[224:225], s[54:55], 0, v[148:149]
	global_load_lds_dwordx4 v146, s[80:81]
	s_add_i32 m0, s12, 0x2000
	s_nop 0
	global_load_lds_dwordx4 v150, s[80:81]
	v_lshl_add_u64 v[222:223], s[54:55], 0, v[144:145]
	s_mov_b32 m0, s60
	s_nop 0
	global_load_lds_dwordx4 v144, s[54:55]
	s_mov_b32 m0, s61
	s_nop 0
	global_load_lds_dwordx4 v148, s[54:55]
	s_waitcnt vmcnt(8)
	s_waitcnt lgkmcnt(0)
	s_barrier
	v_mfma_f32_16x16x32_bf16 v[60:63], v[128:131], v[188:191], v[60:63]
	v_mfma_f32_16x16x32_bf16 v[60:63], v[132:135], v[192:195], v[60:63]
	v_mfma_f32_16x16x32_bf16 v[56:59], v[136:139], v[188:191], v[56:59]
	v_mfma_f32_16x16x32_bf16 v[56:59], v[140:143], v[192:195], v[56:59]
	v_mfma_f32_16x16x32_bf16 v[44:47], v[136:139], v[196:199], v[44:47]
	v_mfma_f32_16x16x32_bf16 v[44:47], v[140:143], v[200:203], v[44:47]
	v_mfma_f32_16x16x32_bf16 v[48:51], v[128:131], v[196:199], v[48:51]
	v_mfma_f32_16x16x32_bf16 v[48:51], v[132:135], v[200:203], v[48:51]
	v_mfma_f32_16x16x32_bf16 v[36:39], v[128:131], v[204:207], v[36:39]
	v_mfma_f32_16x16x32_bf16 v[36:39], v[132:135], v[208:211], v[36:39]
	v_mfma_f32_16x16x32_bf16 v[28:31], v[136:139], v[204:207], v[28:31]
	v_mfma_f32_16x16x32_bf16 v[28:31], v[140:143], v[208:211], v[28:31]
	v_mfma_f32_16x16x32_bf16 v[12:15], v[136:139], v[212:215], v[12:15]
	v_mfma_f32_16x16x32_bf16 v[12:15], v[140:143], v[216:219], v[12:15]
	v_mfma_f32_16x16x32_bf16 v[20:23], v[128:131], v[212:215], v[20:23]
	v_mfma_f32_16x16x32_bf16 v[20:23], v[132:135], v[216:219], v[20:23]
	v_mfma_f32_16x16x32_bf16 v[52:55], v[160:163], v[188:191], v[52:55]
	v_mfma_f32_16x16x32_bf16 v[52:55], v[170:173], v[192:195], v[52:55]
	v_mfma_f32_16x16x32_bf16 v[40:43], v[174:177], v[188:191], v[40:43]
	v_mfma_f32_16x16x32_bf16 v[40:43], v[178:181], v[192:195], v[40:43]
	v_mfma_f32_16x16x32_bf16 v[24:27], v[174:177], v[196:199], v[24:27]
	v_mfma_f32_16x16x32_bf16 v[24:27], v[178:181], v[200:203], v[24:27]
	v_mfma_f32_16x16x32_bf16 v[32:35], v[160:163], v[196:199], v[32:35]
	v_mfma_f32_16x16x32_bf16 v[32:35], v[170:173], v[200:203], v[32:35]
	v_mfma_f32_16x16x32_bf16 v[16:19], v[160:163], v[204:207], v[16:19]
	v_mfma_f32_16x16x32_bf16 v[16:19], v[170:173], v[208:211], v[16:19]
	v_mfma_f32_16x16x32_bf16 v[8:11], v[174:177], v[204:207], v[8:11]
	v_mfma_f32_16x16x32_bf16 v[8:11], v[178:181], v[208:211], v[8:11]
	v_mfma_f32_16x16x32_bf16 v[0:3], v[174:177], v[212:215], v[0:3]
	v_mfma_f32_16x16x32_bf16 v[0:3], v[178:181], v[216:219], v[0:3]
	v_mfma_f32_16x16x32_bf16 v[4:7], v[160:163], v[212:215], v[4:7]
	v_mfma_f32_16x16x32_bf16 v[4:7], v[170:173], v[216:219], v[4:7]
	s_barrier
; #define PG8_STAGE(bufoff, gbase, voff) do { _Pragma("unroll") for (int _i = 0; _i < 2; ++_i) \
;         __builtin_amdgcn_global_load_lds((const unsigned*)((const char*)(gbase) + (voff)[_i]), (PG8_LAS unsigned*)(lds + (bufoff) + ldsw + _i * 8192), 16, 0, 0); } while (0)
; #define PG8_LDA(dst, b, h) do { _Pragma("unroll") for (int m = 0; m < 4; ++m) _Pragma("unroll") for (int k = 0; k < 2; ++k) dst[m][k] = *(const PG8_LAS bf16x8*)(lds + PG8_SA(b, h) + aoff + m * 2048 + k * 1024); } while (0)
; #define PG8_LDB(dst, b, h) do { _Pragma("unroll") for (int n = 0; n < 2; ++n) _Pragma("unroll") for (int k = 0; k < 2; ++k) dst[n][k] = *(const PG8_LAS bf16x8*)(lds + PG8_SB(b, h) + boff + n * 2048 + k * 1024); } while (0)
; #define PG8_MMA(ai, bj, At, Bt) do { __builtin_amdgcn_s_setprio(1); _Pragma("unroll") for (int m = 0; m < 4; ++m) _Pragma("unroll") for (int n = 0; n < 2; ++n) _Pragma("unroll") for (int k = 0; k < 2; ++k) \
;         acc[ai][bj][m][n] = __builtin_amdgcn_mfma_f32_16x16x32_bf16(Bt[n][k], At[m][k], acc[ai][bj][m][n], 0, 0, 0); __builtin_amdgcn_s_setprio(0); } while (0)
; #define PG8_WAIT_V(n) asm volatile("s_waitcnt vmcnt(" #n ")" ::: "memory")
; #define PG8_WAIT_L(n) asm volatile("s_waitcnt lgkmcnt(" #n ")" ::: "memory")
; #define PG8_BAR __builtin_amdgcn_s_barrier()
; #define PG8_SCHED __builtin_amdgcn_sched_barrier(0)
; template <class Epi, class Sched, bool ALIGN_EPI = false, bool SP2 = false>
; __device__ __forceinline__ void gemm_phase(PG8_LAS unsigned char* lds, const Gemm g, const Sched& S, const Epi& E) {
;     ...
;             PG8_LDB(B0, 1, 0); PG8_LDB(B1, 1, 1); PG8_SCHED; PG8_LDA(At, 1, 0); PG8_STAGE(PG8_SA(0, 1), a2 + hstep, voffA);
;             PG8_WAIT_V(8); PG8_WAIT_L(0); PG8_BAR; PG8_MMA(0, 0, At, B0); PG8_MMA(0, 1, At, B1); PG8_BAR; PG8_SCHED;
;             PG8_LDA(At, 1, 1); PG8_STAGE(PG8_SB(1, 0), b3, voffB); PG8_STAGE(PG8_SB(1, 1), b3 + hstep, voffB); PG8_STAGE(PG8_SA(1, 0), a3, voffA);
;             PG8_WAIT_V(8); PG8_WAIT_L(0); PG8_BAR; PG8_MMA(1, 0, At, B0); PG8_MMA(1, 1, At, B1); PG8_BAR; PG8_SCHED;
;     ...
;         if constexpr (ALIGN_EPI) { if (wr == 0) PG8_BAR; }
	s_add_i32 s12, 0, 0x18000
	s_add_i32 s13, 0, 0x1c000
	v_add_u32_e32 v140, s12, v165
	v_add_u32_e32 v178, s13, v165
	ds_read_b128 v[128:131], v140
	ds_read_b128 v[132:135], v140 offset:1024
	ds_read_b128 v[136:139], v140 offset:2048
	ds_read_b128 v[140:143], v140 offset:3072
	ds_read_b128 v[160:163], v178
	ds_read_b128 v[170:173], v178 offset:1024
	ds_read_b128 v[174:177], v178 offset:2048
	ds_read_b128 v[178:181], v178 offset:3072
	s_add_u32 s54, s54, 0x40000
	s_addc_u32 s55, s55, 0
	s_mov_b32 m0, s62
	ds_read_b128 v[188:191], v169 offset:32768
	ds_read_b128 v[192:195], v169 offset:33792
	ds_read_b128 v[196:199], v169 offset:34816
	ds_read_b128 v[200:203], v169 offset:35840
	ds_read_b128 v[204:207], v169 offset:36864
	ds_read_b128 v[208:211], v169 offset:37888
	ds_read_b128 v[212:215], v169 offset:38912
	ds_read_b128 v[216:219], v169 offset:39936
	global_load_lds_dwordx4 v144, s[54:55]
	s_mov_b32 m0, s63
	s_nop 0
	global_load_lds_dwordx4 v148, s[54:55]
	s_waitcnt vmcnt(8)
	s_waitcnt lgkmcnt(0)
	s_barrier
	v_mfma_f32_16x16x32_bf16 v[124:127], v[128:131], v[188:191], v[124:127]
	v_mfma_f32_16x16x32_bf16 v[124:127], v[132:135], v[192:195], v[124:127]
	v_mfma_f32_16x16x32_bf16 v[120:123], v[136:139], v[188:191], v[120:123]
	v_mfma_f32_16x16x32_bf16 v[120:123], v[140:143], v[192:195], v[120:123]
	v_mfma_f32_16x16x32_bf16 v[108:111], v[136:139], v[196:199], v[108:111]
	v_mfma_f32_16x16x32_bf16 v[108:111], v[140:143], v[200:203], v[108:111]
	v_mfma_f32_16x16x32_bf16 v[116:119], v[128:131], v[196:199], v[116:119]
	v_mfma_f32_16x16x32_bf16 v[116:119], v[132:135], v[200:203], v[116:119]
	v_mfma_f32_16x16x32_bf16 v[100:103], v[128:131], v[204:207], v[100:103]
	v_mfma_f32_16x16x32_bf16 v[100:103], v[132:135], v[208:211], v[100:103]
	v_mfma_f32_16x16x32_bf16 v[92:95], v[136:139], v[204:207], v[92:95]
	v_mfma_f32_16x16x32_bf16 v[92:95], v[140:143], v[208:211], v[92:95]
	v_mfma_f32_16x16x32_bf16 v[76:79], v[136:139], v[212:215], v[76:79]
	v_mfma_f32_16x16x32_bf16 v[76:79], v[140:143], v[216:219], v[76:79]
	v_mfma_f32_16x16x32_bf16 v[84:87], v[128:131], v[212:215], v[84:87]
	v_mfma_f32_16x16x32_bf16 v[84:87], v[132:135], v[216:219], v[84:87]
	v_mfma_f32_16x16x32_bf16 v[112:115], v[160:163], v[188:191], v[112:115]
	v_mfma_f32_16x16x32_bf16 v[112:115], v[170:173], v[192:195], v[112:115]
	v_mfma_f32_16x16x32_bf16 v[104:107], v[174:177], v[188:191], v[104:107]
	v_mfma_f32_16x16x32_bf16 v[104:107], v[178:181], v[192:195], v[104:107]
	v_mfma_f32_16x16x32_bf16 v[88:91], v[174:177], v[196:199], v[88:91]
	v_mfma_f32_16x16x32_bf16 v[88:91], v[178:181], v[200:203], v[88:91]
	v_mfma_f32_16x16x32_bf16 v[96:99], v[160:163], v[196:199], v[96:99]
	v_mfma_f32_16x16x32_bf16 v[96:99], v[170:173], v[200:203], v[96:99]
	v_mfma_f32_16x16x32_bf16 v[80:83], v[160:163], v[204:207], v[80:83]
	v_mfma_f32_16x16x32_bf16 v[80:83], v[170:173], v[208:211], v[80:83]
	v_mfma_f32_16x16x32_bf16 v[72:75], v[174:177], v[204:207], v[72:75]
	v_mfma_f32_16x16x32_bf16 v[72:75], v[178:181], v[208:211], v[72:75]
	v_mfma_f32_16x16x32_bf16 v[64:67], v[174:177], v[212:215], v[64:67]
	v_mfma_f32_16x16x32_bf16 v[64:67], v[178:181], v[216:219], v[64:67]
	v_mfma_f32_16x16x32_bf16 v[68:71], v[160:163], v[212:215], v[68:71]
	v_mfma_f32_16x16x32_bf16 v[68:71], v[170:173], v[216:219], v[68:71]
	s_barrier
	s_add_i32 s12, s12, s59
	s_add_u32 s98, s52, s22
	s_addc_u32 s99, s53, s23
	s_mov_b32 m0, s12
	ds_read_b128 v[188:191], v169 offset:49152
	ds_read_b128 v[192:195], v169 offset:50176
	ds_read_b128 v[196:199], v169 offset:51200
	ds_read_b128 v[200:203], v169 offset:52224
	ds_read_b128 v[204:207], v169 offset:53248
	ds_read_b128 v[208:211], v169 offset:54272
	ds_read_b128 v[212:215], v169 offset:55296
	ds_read_b128 v[216:219], v169 offset:56320
	global_load_lds_dwordx4 v146, s[98:99]
	s_add_i32 m0, s12, 0x2000
	s_add_u32 s52, s52, 0x40080
	v_lshl_add_u64 v[184:185], v[220:221], 0, s[22:23]
	s_addc_u32 s53, s53, 0
	s_add_i32 s12, s13, s59
	global_load_lds_dwordx4 v[184:185], off
	s_mov_b32 m0, s12
	s_nop 0
	global_load_lds_dwordx4 v146, s[52:53]
	s_add_i32 m0, s12, 0x2000
	s_nop 0
	global_load_lds_dwordx4 v150, s[52:53]
	v_lshl_add_u64 v[184:185], v[222:223], 0, s[22:23]
	s_mov_b32 m0, s69
	s_nop 0
	global_load_lds_dwordx4 v[184:185], off
	v_lshl_add_u64 v[184:185], v[224:225], 0, s[22:23]
	s_mov_b32 m0, s70
	s_nop 0
	global_load_lds_dwordx4 v[184:185], off
	s_waitcnt vmcnt(8)
	s_waitcnt lgkmcnt(0)
	s_barrier
	v_mfma_f32_16x16x32_bf16 v[60:63], v[128:131], v[188:191], v[60:63]
	v_mfma_f32_16x16x32_bf16 v[60:63], v[132:135], v[192:195], v[60:63]
	v_mfma_f32_16x16x32_bf16 v[56:59], v[136:139], v[188:191], v[56:59]
	v_mfma_f32_16x16x32_bf16 v[56:59], v[140:143], v[192:195], v[56:59]
	v_mfma_f32_16x16x32_bf16 v[44:47], v[136:139], v[196:199], v[44:47]
	v_mfma_f32_16x16x32_bf16 v[44:47], v[140:143], v[200:203], v[44:47]
	v_mfma_f32_16x16x32_bf16 v[48:51], v[128:131], v[196:199], v[48:51]
	v_mfma_f32_16x16x32_bf16 v[48:51], v[132:135], v[200:203], v[48:51]
	v_mfma_f32_16x16x32_bf16 v[36:39], v[128:131], v[204:207], v[36:39]
	v_mfma_f32_16x16x32_bf16 v[36:39], v[132:135], v[208:211], v[36:39]
	v_mfma_f32_16x16x32_bf16 v[28:31], v[136:139], v[204:207], v[28:31]
	v_mfma_f32_16x16x32_bf16 v[28:31], v[140:143], v[208:211], v[28:31]
	v_mfma_f32_16x16x32_bf16 v[12:15], v[136:139], v[212:215], v[12:15]
	v_mfma_f32_16x16x32_bf16 v[12:15], v[140:143], v[216:219], v[12:15]
	v_mfma_f32_16x16x32_bf16 v[20:23], v[128:131], v[212:215], v[20:23]
	v_mfma_f32_16x16x32_bf16 v[20:23], v[132:135], v[216:219], v[20:23]
	v_mfma_f32_16x16x32_bf16 v[52:55], v[160:163], v[188:191], v[52:55]
	v_mfma_f32_16x16x32_bf16 v[52:55], v[170:173], v[192:195], v[52:55]
	v_mfma_f32_16x16x32_bf16 v[40:43], v[174:177], v[188:191], v[40:43]
	v_mfma_f32_16x16x32_bf16 v[40:43], v[178:181], v[192:195], v[40:43]
	v_mfma_f32_16x16x32_bf16 v[24:27], v[174:177], v[196:199], v[24:27]
	v_mfma_f32_16x16x32_bf16 v[24:27], v[178:181], v[200:203], v[24:27]
	v_mfma_f32_16x16x32_bf16 v[32:35], v[160:163], v[196:199], v[32:35]
	v_mfma_f32_16x16x32_bf16 v[32:35], v[170:173], v[200:203], v[32:35]
	v_mfma_f32_16x16x32_bf16 v[16:19], v[160:163], v[204:207], v[16:19]
	v_mfma_f32_16x16x32_bf16 v[16:19], v[170:173], v[208:211], v[16:19]
	v_mfma_f32_16x16x32_bf16 v[8:11], v[174:177], v[204:207], v[8:11]
	v_mfma_f32_16x16x32_bf16 v[8:11], v[178:181], v[208:211], v[8:11]
	v_mfma_f32_16x16x32_bf16 v[0:3], v[174:177], v[212:215], v[0:3]
	v_mfma_f32_16x16x32_bf16 v[0:3], v[178:181], v[216:219], v[0:3]
	v_mfma_f32_16x16x32_bf16 v[4:7], v[160:163], v[212:215], v[4:7]
	v_mfma_f32_16x16x32_bf16 v[4:7], v[170:173], v[216:219], v[4:7]
	s_barrier
	s_add_i32 s79, s79, 2
	s_add_u32 s77, s77, 0x100
	s_addc_u32 s78, s78, 0
	s_add_u32 s50, s50, 0x100
	s_addc_u32 s51, s51, 0
	s_cmp_gt_u32 s79, 13
	s_cbranch_scc0 .LBB0_1272
	s_and_b64 vcc, exec, s[36:37]
	s_cbranch_vccz .LBB0_1275
	s_barrier

; #define PG8_STAGE(bufoff, gbase, voff) do { _Pragma("unroll") for (int _i = 0; _i < 2; ++_i) \
;         __builtin_amdgcn_global_load_lds((const unsigned*)((const char*)(gbase) + (voff)[_i]), (PG8_LAS unsigned*)(lds + (bufoff) + ldsw + _i * 8192), 16, 0, 0); } while (0)
; #define PG8_LDA(dst, b, h) do { _Pragma("unroll") for (int m = 0; m < 4; ++m) _Pragma("unroll") for (int k = 0; k < 2; ++k) dst[m][k] = *(const PG8_LAS bf16x8*)(lds + PG8_SA(b, h) + aoff + m * 2048 + k * 1024); } while (0)
; #define PG8_LDB(dst, b, h) do { _Pragma("unroll") for (int n = 0; n < 2; ++n) _Pragma("unroll") for (int k = 0; k < 2; ++k) dst[n][k] = *(const PG8_LAS bf16x8*)(lds + PG8_SB(b, h) + boff + n * 2048 + k * 1024); } while (0)
; #define PG8_MMA(ai, bj, At, Bt) do { __builtin_amdgcn_s_setprio(1); _Pragma("unroll") for (int m = 0; m < 4; ++m) _Pragma("unroll") for (int n = 0; n < 2; ++n) _Pragma("unroll") for (int k = 0; k < 2; ++k) \
;         acc[ai][bj][m][n] = __builtin_amdgcn_mfma_f32_16x16x32_bf16(Bt[n][k], At[m][k], acc[ai][bj][m][n], 0, 0, 0); __builtin_amdgcn_s_setprio(0); } while (0)
; #define PG8_WAIT_V(n) asm volatile("s_waitcnt vmcnt(" #n ")" ::: "memory")
; #define PG8_BAR __builtin_amdgcn_s_barrier()
; template <class Epi, class Sched, bool ALIGN_EPI = false, bool SP2 = false>
; __device__ __forceinline__ void gemm_phase(PG8_LAS unsigned char* lds, const Gemm g, const Sched& S, const Epi& E) {
;     ...
;             const bool last = (t == nt - 2);
;             const char* a1 = cA + (size_t)(t + 1) * kstep;
;             const char* a2 = last ? nA : cA + (size_t)(t + 2) * kstep; const char* b2 = last ? nB : cB + (size_t)(t + 2) * kstep;
;             const char* a3 = a2 + kstep; const char* b3 = b2 + kstep;
;             if (last && has_next) S.a_ready(nxt);
;             if (last) E.prefetch(lds + 139264, cur, wid, lane);
;             if constexpr (SP2) {
;             PG8_LDB(B0, 0, 0); PG8_LDB(B1, 0, 1); PG8_SCHED; PG8_LDA(At, 0, 0); PG8_STAGE(PG8_SA(1, 1), a1 + hstep, voffA);
;             PG8_WAIT_V(8); PG8_WAIT_L(0); PG8_BAR; PG8_MMA(0, 0, At, B0); PG8_MMA(0, 1, At, B1); PG8_BAR; PG8_SCHED;
;             PG8_LDA(At, 0, 1); PG8_STAGE(PG8_SB(0, 0), b2, voffB); PG8_STAGE(PG8_SB(0, 1), b2 + hstep, voffB); PG8_STAGE(PG8_SA(0, 0), a2, voffA);
;             PG8_WAIT_V(8); PG8_WAIT_L(0); PG8_BAR; PG8_MMA(1, 0, At, B0); PG8_MMA(1, 1, At, B1); PG8_BAR; PG8_SCHED;
.LBB0_1358:
	v_add_u32_e32 v130, s71, v163
	ds_read_b128 v[118:121], v130
	ds_read_b128 v[122:125], v130 offset:1024
	ds_read_b128 v[126:129], v130 offset:2048
	ds_read_b128 v[170:173], v130 offset:3072
	v_add_u32_e32 v130, s72, v163
	ds_read_b128 v[174:177], v130
	ds_read_b128 v[178:181], v130 offset:1024
	ds_read_b128 v[184:187], v130 offset:2048
	ds_read_b128 v[188:191], v130 offset:3072
	s_add_u32 s14, s48, 0xfffc0080
	s_addc_u32 s15, s49, -1
	s_and_b64 s[50:51], s[50:51], exec
	s_cselect_b32 s53, s39, s15
	s_cselect_b32 s52, s73, s14
	s_cselect_b32 s51, s37, s47
	s_cselect_b32 s50, s74, s45
	s_add_i32 m0, s58, 0xc000
	ds_read_b128 v[192:195], v168
	ds_read_b128 v[196:199], v168 offset:1024
	ds_read_b128 v[200:203], v168 offset:2048
	ds_read_b128 v[204:207], v168 offset:3072
	ds_read_b128 v[208:211], v168 offset:4096
	ds_read_b128 v[212:215], v168 offset:5120
	ds_read_b128 v[216:219], v168 offset:6144
	ds_read_b128 v[220:223], v168 offset:7168
	global_load_lds_dwordx4 v154, s[48:49]
	s_add_i32 m0, s58, 0xe000
	s_nop 0
	global_load_lds_dwordx4 v152, s[48:49]
	s_waitcnt vmcnt(8)
	s_waitcnt lgkmcnt(0)
	s_barrier
	v_mfma_f32_16x16x32_bf16 v[140:143], v[118:121], v[192:195], v[140:143]
	v_mfma_f32_16x16x32_bf16 v[140:143], v[122:125], v[196:199], v[140:143]
	v_mfma_f32_16x16x32_bf16 v[136:139], v[126:129], v[192:195], v[136:139]
	v_mfma_f32_16x16x32_bf16 v[136:139], v[170:173], v[196:199], v[136:139]
	v_mfma_f32_16x16x32_bf16 v[104:107], v[126:129], v[200:203], v[104:107]
	v_mfma_f32_16x16x32_bf16 v[104:107], v[170:173], v[204:207], v[104:107]
	v_mfma_f32_16x16x32_bf16 v[108:111], v[118:121], v[200:203], v[108:111]
	v_mfma_f32_16x16x32_bf16 v[108:111], v[122:125], v[204:207], v[108:111]
	v_mfma_f32_16x16x32_bf16 v[92:95], v[118:121], v[208:211], v[92:95]
	v_mfma_f32_16x16x32_bf16 v[92:95], v[122:125], v[212:215], v[92:95]
	v_mfma_f32_16x16x32_bf16 v[88:91], v[126:129], v[208:211], v[88:91]
	v_mfma_f32_16x16x32_bf16 v[88:91], v[170:173], v[212:215], v[88:91]
	v_mfma_f32_16x16x32_bf16 v[72:75], v[126:129], v[216:219], v[72:75]
	v_mfma_f32_16x16x32_bf16 v[72:75], v[170:173], v[220:223], v[72:75]
	v_mfma_f32_16x16x32_bf16 v[76:79], v[118:121], v[216:219], v[76:79]
	v_mfma_f32_16x16x32_bf16 v[76:79], v[122:125], v[220:223], v[76:79]
	v_mfma_f32_16x16x32_bf16 v[130:133], v[174:177], v[192:195], v[132:135]
	v_mfma_f32_16x16x32_bf16 v[130:133], v[178:181], v[196:199], v[130:133]
	v_mfma_f32_16x16x32_bf16 v[112:115], v[184:187], v[192:195], v[112:115]
	v_mfma_f32_16x16x32_bf16 v[112:115], v[188:191], v[196:199], v[112:115]
	v_mfma_f32_16x16x32_bf16 v[96:99], v[184:187], v[200:203], v[96:99]
	v_mfma_f32_16x16x32_bf16 v[96:99], v[188:191], v[204:207], v[96:99]
	v_mfma_f32_16x16x32_bf16 v[100:103], v[174:177], v[200:203], v[100:103]
	v_mfma_f32_16x16x32_bf16 v[100:103], v[178:181], v[204:207], v[100:103]
	v_mfma_f32_16x16x32_bf16 v[84:87], v[174:177], v[208:211], v[84:87]
	v_mfma_f32_16x16x32_bf16 v[84:87], v[178:181], v[212:215], v[84:87]
	v_mfma_f32_16x16x32_bf16 v[80:83], v[184:187], v[208:211], v[80:83]
	v_mfma_f32_16x16x32_bf16 v[80:83], v[188:191], v[212:215], v[80:83]
	v_mfma_f32_16x16x32_bf16 v[64:67], v[184:187], v[216:219], v[64:67]
	v_mfma_f32_16x16x32_bf16 v[64:67], v[188:191], v[220:223], v[64:67]
	v_mfma_f32_16x16x32_bf16 v[68:71], v[174:177], v[216:219], v[68:71]
	v_mfma_f32_16x16x32_bf16 v[68:71], v[178:181], v[220:223], v[68:71]
	s_barrier
	s_add_i32 s14, s71, s55
	s_mov_b32 m0, s14
	ds_read_b128 v[192:195], v168 offset:16384
	ds_read_b128 v[196:199], v168 offset:17408
	ds_read_b128 v[200:203], v168 offset:18432
	ds_read_b128 v[204:207], v168 offset:19456
	ds_read_b128 v[208:211], v168 offset:20480
	ds_read_b128 v[212:215], v168 offset:21504
	ds_read_b128 v[216:219], v168 offset:22528
	ds_read_b128 v[220:223], v168 offset:23552
	global_load_lds_dwordx4 v148, s[50:51]
	s_add_i32 m0, s14, 0x2000
	s_add_u32 s76, s50, 0x40000
	v_lshl_add_u64 v[226:227], s[50:51], 0, v[144:145]
	s_addc_u32 s77, s51, 0
	s_add_i32 s14, s72, s55
	global_load_lds_dwordx4 v144, s[50:51]
	s_mov_b32 m0, s14
	v_lshl_add_u64 v[228:229], s[52:53], 0, v[150:151]
	global_load_lds_dwordx4 v148, s[76:77]
	s_add_i32 m0, s14, 0x2000
	v_lshl_add_u64 v[230:231], s[52:53], 0, v[146:147]
	global_load_lds_dwordx4 v144, s[76:77]
	s_mov_b32 m0, s58
	s_nop 0
	global_load_lds_dwordx4 v150, s[52:53]
	s_mov_b32 m0, s59
	s_nop 0
	global_load_lds_dwordx4 v146, s[52:53]
	s_waitcnt vmcnt(8)
	s_waitcnt lgkmcnt(0)
	s_barrier
	v_mfma_f32_16x16x32_bf16 v[60:63], v[118:121], v[192:195], v[60:63]
	v_mfma_f32_16x16x32_bf16 v[60:63], v[122:125], v[196:199], v[60:63]
	v_mfma_f32_16x16x32_bf16 v[56:59], v[126:129], v[192:195], v[56:59]
	v_mfma_f32_16x16x32_bf16 v[56:59], v[170:173], v[196:199], v[56:59]
	v_mfma_f32_16x16x32_bf16 v[40:43], v[126:129], v[200:203], v[40:43]
	v_mfma_f32_16x16x32_bf16 v[40:43], v[170:173], v[204:207], v[40:43]
	v_mfma_f32_16x16x32_bf16 v[44:47], v[118:121], v[200:203], v[44:47]
	v_mfma_f32_16x16x32_bf16 v[44:47], v[122:125], v[204:207], v[44:47]
	v_mfma_f32_16x16x32_bf16 v[28:31], v[118:121], v[208:211], v[28:31]
	v_mfma_f32_16x16x32_bf16 v[28:31], v[122:125], v[212:215], v[28:31]
	v_mfma_f32_16x16x32_bf16 v[24:27], v[126:129], v[208:211], v[24:27]
	v_mfma_f32_16x16x32_bf16 v[24:27], v[170:173], v[212:215], v[24:27]
	v_mfma_f32_16x16x32_bf16 v[8:11], v[126:129], v[216:219], v[8:11]
	v_mfma_f32_16x16x32_bf16 v[8:11], v[170:173], v[220:223], v[8:11]
	v_mfma_f32_16x16x32_bf16 v[12:15], v[118:121], v[216:219], v[12:15]
	v_mfma_f32_16x16x32_bf16 v[12:15], v[122:125], v[220:223], v[12:15]
	v_mfma_f32_16x16x32_bf16 v[52:55], v[174:177], v[192:195], v[52:55]
	v_mfma_f32_16x16x32_bf16 v[52:55], v[178:181], v[196:199], v[52:55]
	v_mfma_f32_16x16x32_bf16 v[48:51], v[184:187], v[192:195], v[48:51]
	v_mfma_f32_16x16x32_bf16 v[48:51], v[188:191], v[196:199], v[48:51]
	v_mfma_f32_16x16x32_bf16 v[32:35], v[184:187], v[200:203], v[32:35]
	v_mfma_f32_16x16x32_bf16 v[32:35], v[188:191], v[204:207], v[32:35]
	v_mfma_f32_16x16x32_bf16 v[36:39], v[174:177], v[200:203], v[36:39]
	v_mfma_f32_16x16x32_bf16 v[36:39], v[178:181], v[204:207], v[36:39]
	v_mfma_f32_16x16x32_bf16 v[20:23], v[174:177], v[208:211], v[20:23]
	v_mfma_f32_16x16x32_bf16 v[20:23], v[178:181], v[212:215], v[20:23]
	v_mfma_f32_16x16x32_bf16 v[16:19], v[184:187], v[208:211], v[16:19]
	v_mfma_f32_16x16x32_bf16 v[16:19], v[188:191], v[212:215], v[16:19]
	v_mfma_f32_16x16x32_bf16 v[0:3], v[184:187], v[216:219], v[0:3]
	v_mfma_f32_16x16x32_bf16 v[0:3], v[188:191], v[220:223], v[0:3]
	v_mfma_f32_16x16x32_bf16 v[4:7], v[174:177], v[216:219], v[4:7]
	v_mfma_f32_16x16x32_bf16 v[4:7], v[178:181], v[220:223], v[4:7]
	s_barrier
; #define PG8_STAGE(bufoff, gbase, voff) do { _Pragma("unroll") for (int _i = 0; _i < 2; ++_i) \
;         __builtin_amdgcn_global_load_lds((const unsigned*)((const char*)(gbase) + (voff)[_i]), (PG8_LAS unsigned*)(lds + (bufoff) + ldsw + _i * 8192), 16, 0, 0); } while (0)
; #define PG8_LDA(dst, b, h) do { _Pragma("unroll") for (int m = 0; m < 4; ++m) _Pragma("unroll") for (int k = 0; k < 2; ++k) dst[m][k] = *(const PG8_LAS bf16x8*)(lds + PG8_SA(b, h) + aoff + m * 2048 + k * 1024); } while (0)
; #define PG8_LDB(dst, b, h) do { _Pragma("unroll") for (int n = 0; n < 2; ++n) _Pragma("unroll") for (int k = 0; k < 2; ++k) dst[n][k] = *(const PG8_LAS bf16x8*)(lds + PG8_SB(b, h) + boff + n * 2048 + k * 1024); } while (0)
; #define PG8_MMA(ai, bj, At, Bt) do { __builtin_amdgcn_s_setprio(1); _Pragma("unroll") for (int m = 0; m < 4; ++m) _Pragma("unroll") for (int n = 0; n < 2; ++n) _Pragma("unroll") for (int k = 0; k < 2; ++k) \
;         acc[ai][bj][m][n] = __builtin_amdgcn_mfma_f32_16x16x32_bf16(Bt[n][k], At[m][k], acc[ai][bj][m][n], 0, 0, 0); __builtin_amdgcn_s_setprio(0); } while (0)
; #define PG8_WAIT_V(n) asm volatile("s_waitcnt vmcnt(" #n ")" ::: "memory")
; #define PG8_WAIT_L(n) asm volatile("s_waitcnt lgkmcnt(" #n ")" ::: "memory")
; #define PG8_BAR __builtin_amdgcn_s_barrier()
; #define PG8_SCHED __builtin_amdgcn_sched_barrier(0)
; template <class Epi, class Sched, bool ALIGN_EPI = false, bool SP2 = false>
; __device__ __forceinline__ void gemm_phase(PG8_LAS unsigned char* lds, const Gemm g, const Sched& S, const Epi& E) {
;     ...
;             PG8_LDB(B0, 1, 0); PG8_LDB(B1, 1, 1); PG8_SCHED; PG8_LDA(At, 1, 0); PG8_STAGE(PG8_SA(0, 1), a2 + hstep, voffA);
;             PG8_WAIT_V(8); PG8_WAIT_L(0); PG8_BAR; PG8_MMA(0, 0, At, B0); PG8_MMA(0, 1, At, B1); PG8_BAR; PG8_SCHED;
;             PG8_LDA(At, 1, 1); PG8_STAGE(PG8_SB(1, 0), b3, voffB); PG8_STAGE(PG8_SB(1, 1), b3 + hstep, voffB); PG8_STAGE(PG8_SA(1, 0), a3, voffA);
;             PG8_WAIT_V(8); PG8_WAIT_L(0); PG8_BAR; PG8_MMA(1, 0, At, B0); PG8_MMA(1, 1, At, B1); PG8_BAR; PG8_SCHED;
	s_add_i32 s14, 0, 0x18000
	v_add_u32_e32 v134, s14, v163
	s_add_i32 s15, 0, 0x1c000
	ds_read_b128 v[118:121], v134
	ds_read_b128 v[122:125], v134 offset:1024
	ds_read_b128 v[126:129], v134 offset:2048
	ds_read_b128 v[170:173], v134 offset:3072
	v_add_u32_e32 v134, s15, v163
	ds_read_b128 v[174:177], v134
	ds_read_b128 v[178:181], v134 offset:1024
	ds_read_b128 v[184:187], v134 offset:2048
	ds_read_b128 v[188:191], v134 offset:3072
	s_add_u32 s52, s52, 0x40000
	s_addc_u32 s53, s53, 0
	s_mov_b32 m0, s60
	ds_read_b128 v[192:195], v168 offset:32768
	ds_read_b128 v[196:199], v168 offset:33792
	ds_read_b128 v[200:203], v168 offset:34816
	ds_read_b128 v[204:207], v168 offset:35840
	ds_read_b128 v[208:211], v168 offset:36864
	ds_read_b128 v[212:215], v168 offset:37888
	ds_read_b128 v[216:219], v168 offset:38912
	ds_read_b128 v[220:223], v168 offset:39936
	global_load_lds_dwordx4 v150, s[52:53]
	s_mov_b32 m0, s61
	s_nop 0
	global_load_lds_dwordx4 v146, s[52:53]
	s_waitcnt vmcnt(8)
	s_waitcnt lgkmcnt(0)
	s_barrier
	v_mfma_f32_16x16x32_bf16 v[140:143], v[118:121], v[192:195], v[140:143]
	v_mfma_f32_16x16x32_bf16 v[140:143], v[122:125], v[196:199], v[140:143]
	v_mfma_f32_16x16x32_bf16 v[134:137], v[126:129], v[192:195], v[136:139]
	v_mfma_f32_16x16x32_bf16 v[136:139], v[170:173], v[196:199], v[134:137]
	v_mfma_f32_16x16x32_bf16 v[104:107], v[126:129], v[200:203], v[104:107]
	v_mfma_f32_16x16x32_bf16 v[104:107], v[170:173], v[204:207], v[104:107]
	v_mfma_f32_16x16x32_bf16 v[108:111], v[118:121], v[200:203], v[108:111]
	v_mfma_f32_16x16x32_bf16 v[108:111], v[122:125], v[204:207], v[108:111]
	v_mfma_f32_16x16x32_bf16 v[92:95], v[118:121], v[208:211], v[92:95]
	v_mfma_f32_16x16x32_bf16 v[92:95], v[122:125], v[212:215], v[92:95]
	v_mfma_f32_16x16x32_bf16 v[88:91], v[126:129], v[208:211], v[88:91]
	v_mfma_f32_16x16x32_bf16 v[88:91], v[170:173], v[212:215], v[88:91]
	v_mfma_f32_16x16x32_bf16 v[72:75], v[126:129], v[216:219], v[72:75]
	v_mfma_f32_16x16x32_bf16 v[72:75], v[170:173], v[220:223], v[72:75]
	v_mfma_f32_16x16x32_bf16 v[76:79], v[118:121], v[216:219], v[76:79]
	v_mfma_f32_16x16x32_bf16 v[76:79], v[122:125], v[220:223], v[76:79]
	v_mfma_f32_16x16x32_bf16 v[130:133], v[174:177], v[192:195], v[130:133]
	v_mfma_f32_16x16x32_bf16 v[132:135], v[178:181], v[196:199], v[130:133]
	v_mfma_f32_16x16x32_bf16 v[112:115], v[184:187], v[192:195], v[112:115]
	v_mfma_f32_16x16x32_bf16 v[112:115], v[188:191], v[196:199], v[112:115]
	v_mfma_f32_16x16x32_bf16 v[96:99], v[184:187], v[200:203], v[96:99]
	v_mfma_f32_16x16x32_bf16 v[96:99], v[188:191], v[204:207], v[96:99]
	v_mfma_f32_16x16x32_bf16 v[100:103], v[174:177], v[200:203], v[100:103]
	v_mfma_f32_16x16x32_bf16 v[100:103], v[178:181], v[204:207], v[100:103]
	v_mfma_f32_16x16x32_bf16 v[84:87], v[174:177], v[208:211], v[84:87]
	v_mfma_f32_16x16x32_bf16 v[84:87], v[178:181], v[212:215], v[84:87]
	v_mfma_f32_16x16x32_bf16 v[80:83], v[184:187], v[208:211], v[80:83]
	v_mfma_f32_16x16x32_bf16 v[80:83], v[188:191], v[212:215], v[80:83]
	v_mfma_f32_16x16x32_bf16 v[64:67], v[184:187], v[216:219], v[64:67]
	v_mfma_f32_16x16x32_bf16 v[64:67], v[188:191], v[220:223], v[64:67]
	v_mfma_f32_16x16x32_bf16 v[68:71], v[174:177], v[216:219], v[68:71]
	v_mfma_f32_16x16x32_bf16 v[68:71], v[178:181], v[220:223], v[68:71]
	s_barrier
	s_add_i32 s14, s14, s55
	s_add_u32 s98, s50, s18
	s_addc_u32 s99, s51, s19
	s_mov_b32 m0, s14
	ds_read_b128 v[192:195], v168 offset:49152
	ds_read_b128 v[196:199], v168 offset:50176
	ds_read_b128 v[200:203], v168 offset:51200
	ds_read_b128 v[204:207], v168 offset:52224
	ds_read_b128 v[208:211], v168 offset:53248
	ds_read_b128 v[212:215], v168 offset:54272
	ds_read_b128 v[216:219], v168 offset:55296
	ds_read_b128 v[220:223], v168 offset:56320
	global_load_lds_dwordx4 v148, s[98:99]
	s_add_i32 m0, s14, 0x2000
	s_add_u32 s50, s50, 0x40080
	v_lshl_add_u64 v[130:131], v[226:227], 0, s[18:19]
	s_addc_u32 s51, s51, 0
	s_add_i32 s14, s15, s55
	global_load_lds_dwordx4 v[130:131], off
	s_mov_b32 m0, s14
	s_nop 0
	global_load_lds_dwordx4 v148, s[50:51]
	s_add_i32 m0, s14, 0x2000
	s_nop 0
	global_load_lds_dwordx4 v144, s[50:51]
	v_lshl_add_u64 v[130:131], v[228:229], 0, s[18:19]
	s_mov_b32 m0, s64
	s_nop 0
	global_load_lds_dwordx4 v[130:131], off
	v_lshl_add_u64 v[130:131], v[230:231], 0, s[18:19]
	s_mov_b32 m0, s65
	s_nop 0
	global_load_lds_dwordx4 v[130:131], off
	s_waitcnt vmcnt(8)
	s_waitcnt lgkmcnt(0)
	s_barrier
	v_mfma_f32_16x16x32_bf16 v[60:63], v[118:121], v[192:195], v[60:63]
	v_mfma_f32_16x16x32_bf16 v[60:63], v[122:125], v[196:199], v[60:63]
	v_mfma_f32_16x16x32_bf16 v[56:59], v[126:129], v[192:195], v[56:59]
	v_mfma_f32_16x16x32_bf16 v[56:59], v[170:173], v[196:199], v[56:59]
	v_mfma_f32_16x16x32_bf16 v[40:43], v[126:129], v[200:203], v[40:43]
	v_mfma_f32_16x16x32_bf16 v[40:43], v[170:173], v[204:207], v[40:43]
	v_mfma_f32_16x16x32_bf16 v[44:47], v[118:121], v[200:203], v[44:47]
	v_mfma_f32_16x16x32_bf16 v[44:47], v[122:125], v[204:207], v[44:47]
	v_mfma_f32_16x16x32_bf16 v[28:31], v[118:121], v[208:211], v[28:31]
	v_mfma_f32_16x16x32_bf16 v[28:31], v[122:125], v[212:215], v[28:31]
	v_mfma_f32_16x16x32_bf16 v[24:27], v[126:129], v[208:211], v[24:27]
	v_mfma_f32_16x16x32_bf16 v[24:27], v[170:173], v[212:215], v[24:27]
	v_mfma_f32_16x16x32_bf16 v[8:11], v[126:129], v[216:219], v[8:11]
	v_mfma_f32_16x16x32_bf16 v[8:11], v[170:173], v[220:223], v[8:11]
	v_mfma_f32_16x16x32_bf16 v[12:15], v[118:121], v[216:219], v[12:15]
	v_mfma_f32_16x16x32_bf16 v[12:15], v[122:125], v[220:223], v[12:15]
	v_mfma_f32_16x16x32_bf16 v[52:55], v[174:177], v[192:195], v[52:55]
	v_mfma_f32_16x16x32_bf16 v[52:55], v[178:181], v[196:199], v[52:55]
	v_mfma_f32_16x16x32_bf16 v[48:51], v[184:187], v[192:195], v[48:51]
	v_mfma_f32_16x16x32_bf16 v[48:51], v[188:191], v[196:199], v[48:51]
	v_mfma_f32_16x16x32_bf16 v[32:35], v[184:187], v[200:203], v[32:35]
	v_mfma_f32_16x16x32_bf16 v[32:35], v[188:191], v[204:207], v[32:35]
	v_mfma_f32_16x16x32_bf16 v[36:39], v[174:177], v[200:203], v[36:39]
	v_mfma_f32_16x16x32_bf16 v[36:39], v[178:181], v[204:207], v[36:39]
	v_mfma_f32_16x16x32_bf16 v[20:23], v[174:177], v[208:211], v[20:23]
	v_mfma_f32_16x16x32_bf16 v[20:23], v[178:181], v[212:215], v[20:23]
	v_mfma_f32_16x16x32_bf16 v[16:19], v[184:187], v[208:211], v[16:19]
	v_mfma_f32_16x16x32_bf16 v[16:19], v[188:191], v[212:215], v[16:19]
	v_mfma_f32_16x16x32_bf16 v[0:3], v[184:187], v[216:219], v[0:3]
	v_mfma_f32_16x16x32_bf16 v[0:3], v[188:191], v[220:223], v[0:3]
	v_mfma_f32_16x16x32_bf16 v[4:7], v[174:177], v[216:219], v[4:7]
	v_mfma_f32_16x16x32_bf16 v[4:7], v[178:181], v[220:223], v[4:7]
	s_barrier
	s_add_i32 s75, s75, 2
	s_add_u32 s45, s45, 0x100
	s_addc_u32 s47, s47, 0
	s_add_u32 s48, s48, 0x100
	s_addc_u32 s49, s49, 0
	s_cmp_gt_u32 s75, 13
	s_cbranch_scc1 .LBB0_1361

; #define PG8_STAGE(bufoff, gbase, voff) do { _Pragma("unroll") for (int _i = 0; _i < 2; ++_i) \
;         __builtin_amdgcn_global_load_lds((const unsigned*)((const char*)(gbase) + (voff)[_i]), (PG8_LAS unsigned*)(lds + (bufoff) + ldsw + _i * 8192), 16, 0, 0); } while (0)
; #define PG8_LDA(dst, b, h) do { _Pragma("unroll") for (int m = 0; m < 4; ++m) _Pragma("unroll") for (int k = 0; k < 2; ++k) dst[m][k] = *(const PG8_LAS bf16x8*)(lds + PG8_SA(b, h) + aoff + m * 2048 + k * 1024); } while (0)
; #define PG8_LDB(dst, b, h) do { _Pragma("unroll") for (int n = 0; n < 2; ++n) _Pragma("unroll") for (int k = 0; k < 2; ++k) dst[n][k] = *(const PG8_LAS bf16x8*)(lds + PG8_SB(b, h) + boff + n * 2048 + k * 1024); } while (0)
; #define PG8_MMA(ai, bj, At, Bt) do { __builtin_amdgcn_s_setprio(1); _Pragma("unroll") for (int m = 0; m < 4; ++m) _Pragma("unroll") for (int n = 0; n < 2; ++n) _Pragma("unroll") for (int k = 0; k < 2; ++k) \
;         acc[ai][bj][m][n] = __builtin_amdgcn_mfma_f32_16x16x32_bf16(Bt[n][k], At[m][k], acc[ai][bj][m][n], 0, 0, 0); __builtin_amdgcn_s_setprio(0); } while (0)
; #define PG8_WAIT_V(n) asm volatile("s_waitcnt vmcnt(" #n ")" ::: "memory")
; #define PG8_BAR __builtin_amdgcn_s_barrier()
; template <class Epi, class Sched, bool ALIGN_EPI = false, bool SP2 = false>
; __device__ __forceinline__ void gemm_phase(PG8_LAS unsigned char* lds, const Gemm g, const Sched& S, const Epi& E) {
;     ...
;             const bool last = (t == nt - 2);
;             const char* a1 = cA + (size_t)(t + 1) * kstep;
;             const char* a2 = last ? nA : cA + (size_t)(t + 2) * kstep; const char* b2 = last ? nB : cB + (size_t)(t + 2) * kstep;
;             const char* a3 = a2 + kstep; const char* b3 = b2 + kstep;
;             if (last && has_next) S.a_ready(nxt);
;             if (last) E.prefetch(lds + 139264, cur, wid, lane);
;             if constexpr (SP2) {
;             PG8_LDB(B0, 0, 0); PG8_LDB(B1, 0, 1); PG8_SCHED; PG8_LDA(At, 0, 0); PG8_STAGE(PG8_SA(1, 1), a1 + hstep, voffA);
;             PG8_WAIT_V(8); PG8_WAIT_L(0); PG8_BAR; PG8_MMA(0, 0, At, B0); PG8_MMA(0, 1, At, B1); PG8_BAR; PG8_SCHED;
;             PG8_LDA(At, 0, 1); PG8_STAGE(PG8_SB(0, 0), b2, voffB); PG8_STAGE(PG8_SB(0, 1), b2 + hstep, voffB); PG8_STAGE(PG8_SA(0, 0), a2, voffA);
;             PG8_WAIT_V(8); PG8_WAIT_L(0); PG8_BAR; PG8_MMA(1, 0, At, B0); PG8_MMA(1, 1, At, B1); PG8_BAR; PG8_SCHED;
.LBB0_1432:
	ds_read_b128 v[128:131], v167
	ds_read_b128 v[132:135], v167 offset:1024
	ds_read_b128 v[136:139], v167 offset:2048
	ds_read_b128 v[140:143], v167 offset:3072
	ds_read_b128 v[160:163], v168
	ds_read_b128 v[170:173], v168 offset:1024
	ds_read_b128 v[174:177], v168 offset:2048
	ds_read_b128 v[178:181], v168 offset:3072
	s_add_u32 s20, s18, 0x100
	s_addc_u32 s21, s19, 0
	s_cmp_eq_u32 s52, 40
	s_cselect_b32 s27, s5, s21
	s_cselect_b32 s26, s4, s20
	s_cselect_b32 s23, s17, s51
	s_cselect_b32 s22, s16, s50
	v_lshl_add_u64 v[214:215], s[18:19], 0, v[154:155]
	s_add_i32 m0, s36, 0xc000
	ds_read_b128 v[182:185], v169
	ds_read_b128 v[186:189], v169 offset:1024
	ds_read_b128 v[190:193], v169 offset:2048
	ds_read_b128 v[194:197], v169 offset:3072
	ds_read_b128 v[198:201], v169 offset:4096
	ds_read_b128 v[202:205], v169 offset:5120
	ds_read_b128 v[206:209], v169 offset:6144
	ds_read_b128 v[210:213], v169 offset:7168
	global_load_lds_dwordx4 v[214:215], off
	v_lshl_add_u64 v[214:215], s[18:19], 0, v[152:153]
	s_add_i32 m0, s36, 0xe000
	s_nop 0
	global_load_lds_dwordx4 v[214:215], off
	s_waitcnt vmcnt(8)
	s_waitcnt lgkmcnt(0)
	s_barrier
	v_mfma_f32_16x16x32_bf16 v[124:127], v[128:131], v[182:185], v[124:127]
	v_mfma_f32_16x16x32_bf16 v[124:127], v[132:135], v[186:189], v[124:127]
	v_mfma_f32_16x16x32_bf16 v[120:123], v[136:139], v[182:185], v[120:123]
	v_mfma_f32_16x16x32_bf16 v[120:123], v[140:143], v[186:189], v[120:123]
	v_mfma_f32_16x16x32_bf16 v[108:111], v[136:139], v[190:193], v[108:111]
	v_mfma_f32_16x16x32_bf16 v[108:111], v[140:143], v[194:197], v[108:111]
	v_mfma_f32_16x16x32_bf16 v[116:119], v[128:131], v[190:193], v[116:119]
	v_mfma_f32_16x16x32_bf16 v[116:119], v[132:135], v[194:197], v[116:119]
	v_mfma_f32_16x16x32_bf16 v[100:103], v[128:131], v[198:201], v[100:103]
	v_mfma_f32_16x16x32_bf16 v[100:103], v[132:135], v[202:205], v[100:103]
	v_mfma_f32_16x16x32_bf16 v[92:95], v[136:139], v[198:201], v[92:95]
	v_mfma_f32_16x16x32_bf16 v[92:95], v[140:143], v[202:205], v[92:95]
	v_mfma_f32_16x16x32_bf16 v[76:79], v[136:139], v[206:209], v[76:79]
	v_mfma_f32_16x16x32_bf16 v[76:79], v[140:143], v[210:213], v[76:79]
	v_mfma_f32_16x16x32_bf16 v[84:87], v[128:131], v[206:209], v[84:87]
	v_mfma_f32_16x16x32_bf16 v[84:87], v[132:135], v[210:213], v[84:87]
	v_mfma_f32_16x16x32_bf16 v[112:115], v[160:163], v[182:185], v[112:115]
	v_mfma_f32_16x16x32_bf16 v[112:115], v[170:173], v[186:189], v[112:115]
	v_mfma_f32_16x16x32_bf16 v[104:107], v[174:177], v[182:185], v[104:107]
	v_mfma_f32_16x16x32_bf16 v[104:107], v[178:181], v[186:189], v[104:107]
	v_mfma_f32_16x16x32_bf16 v[88:91], v[174:177], v[190:193], v[88:91]
	v_mfma_f32_16x16x32_bf16 v[88:91], v[178:181], v[194:197], v[88:91]
	v_mfma_f32_16x16x32_bf16 v[96:99], v[160:163], v[190:193], v[96:99]
	v_mfma_f32_16x16x32_bf16 v[96:99], v[170:173], v[194:197], v[96:99]
	v_mfma_f32_16x16x32_bf16 v[80:83], v[160:163], v[198:201], v[80:83]
	v_mfma_f32_16x16x32_bf16 v[80:83], v[170:173], v[202:205], v[80:83]
	v_mfma_f32_16x16x32_bf16 v[72:75], v[174:177], v[198:201], v[72:75]
	v_mfma_f32_16x16x32_bf16 v[72:75], v[178:181], v[202:205], v[72:75]
	v_mfma_f32_16x16x32_bf16 v[64:67], v[174:177], v[206:209], v[64:67]
	v_mfma_f32_16x16x32_bf16 v[64:67], v[178:181], v[210:213], v[64:67]
	v_mfma_f32_16x16x32_bf16 v[68:71], v[160:163], v[206:209], v[68:71]
	v_mfma_f32_16x16x32_bf16 v[68:71], v[170:173], v[210:213], v[68:71]
	s_barrier
	s_add_i32 s18, s44, s33
	s_mov_b32 m0, s18
	ds_read_b128 v[182:185], v169 offset:16384
	ds_read_b128 v[186:189], v169 offset:17408
	ds_read_b128 v[190:193], v169 offset:18432
	ds_read_b128 v[194:197], v169 offset:19456
	ds_read_b128 v[198:201], v169 offset:20480
	ds_read_b128 v[202:205], v169 offset:21504
	ds_read_b128 v[206:209], v169 offset:22528
	ds_read_b128 v[210:213], v169 offset:23552
	global_load_lds_dwordx4 v148, s[22:23]
	s_add_i32 m0, s18, 0x2000
	s_add_u32 s18, s22, 0xb0000
	v_lshl_add_u64 v[216:217], s[22:23], 0, v[144:145]
	s_addc_u32 s19, s23, 0
	s_add_i32 s53, s45, s33
	global_load_lds_dwordx4 v144, s[22:23]
	s_mov_b32 m0, s53
	s_nop 0
	global_load_lds_dwordx4 v148, s[18:19]
	s_add_i32 m0, s53, 0x2000
	s_nop 0
	global_load_lds_dwordx4 v144, s[18:19]
	s_mov_b32 m0, s36
	s_nop 0
	global_load_lds_dwordx4 v150, s[26:27]
	s_mov_b32 m0, s37
	s_nop 0
	global_load_lds_dwordx4 v146, s[26:27]
	s_waitcnt vmcnt(8)
	s_waitcnt lgkmcnt(0)
	s_barrier
	v_mfma_f32_16x16x32_bf16 v[60:63], v[128:131], v[182:185], v[60:63]
	v_mfma_f32_16x16x32_bf16 v[60:63], v[132:135], v[186:189], v[60:63]
	v_mfma_f32_16x16x32_bf16 v[56:59], v[136:139], v[182:185], v[56:59]
	v_mfma_f32_16x16x32_bf16 v[56:59], v[140:143], v[186:189], v[56:59]
	v_mfma_f32_16x16x32_bf16 v[44:47], v[136:139], v[190:193], v[44:47]
	v_mfma_f32_16x16x32_bf16 v[44:47], v[140:143], v[194:197], v[44:47]
	v_mfma_f32_16x16x32_bf16 v[48:51], v[128:131], v[190:193], v[48:51]
	v_mfma_f32_16x16x32_bf16 v[48:51], v[132:135], v[194:197], v[48:51]
	v_mfma_f32_16x16x32_bf16 v[36:39], v[128:131], v[198:201], v[36:39]
	v_mfma_f32_16x16x32_bf16 v[36:39], v[132:135], v[202:205], v[36:39]
	v_mfma_f32_16x16x32_bf16 v[28:31], v[136:139], v[198:201], v[28:31]
	v_mfma_f32_16x16x32_bf16 v[28:31], v[140:143], v[202:205], v[28:31]
	v_mfma_f32_16x16x32_bf16 v[12:15], v[136:139], v[206:209], v[12:15]
	v_mfma_f32_16x16x32_bf16 v[12:15], v[140:143], v[210:213], v[12:15]
	v_mfma_f32_16x16x32_bf16 v[20:23], v[128:131], v[206:209], v[20:23]
	v_mfma_f32_16x16x32_bf16 v[20:23], v[132:135], v[210:213], v[20:23]
	v_mfma_f32_16x16x32_bf16 v[52:55], v[160:163], v[182:185], v[52:55]
	v_mfma_f32_16x16x32_bf16 v[52:55], v[170:173], v[186:189], v[52:55]
	v_mfma_f32_16x16x32_bf16 v[40:43], v[174:177], v[182:185], v[40:43]
	v_mfma_f32_16x16x32_bf16 v[40:43], v[178:181], v[186:189], v[40:43]
	v_mfma_f32_16x16x32_bf16 v[24:27], v[174:177], v[190:193], v[24:27]
	v_mfma_f32_16x16x32_bf16 v[24:27], v[178:181], v[194:197], v[24:27]
	v_mfma_f32_16x16x32_bf16 v[32:35], v[160:163], v[190:193], v[32:35]
	v_mfma_f32_16x16x32_bf16 v[32:35], v[170:173], v[194:197], v[32:35]
	v_mfma_f32_16x16x32_bf16 v[16:19], v[160:163], v[198:201], v[16:19]
	v_mfma_f32_16x16x32_bf16 v[16:19], v[170:173], v[202:205], v[16:19]
	v_mfma_f32_16x16x32_bf16 v[8:11], v[174:177], v[198:201], v[8:11]
	v_mfma_f32_16x16x32_bf16 v[8:11], v[178:181], v[202:205], v[8:11]
	v_mfma_f32_16x16x32_bf16 v[0:3], v[174:177], v[206:209], v[0:3]
	v_mfma_f32_16x16x32_bf16 v[0:3], v[178:181], v[210:213], v[0:3]
	v_mfma_f32_16x16x32_bf16 v[4:7], v[160:163], v[206:209], v[4:7]
	v_mfma_f32_16x16x32_bf16 v[4:7], v[170:173], v[210:213], v[4:7]
	s_barrier
; #define PG8_STAGE(bufoff, gbase, voff) do { _Pragma("unroll") for (int _i = 0; _i < 2; ++_i) \
;         __builtin_amdgcn_global_load_lds((const unsigned*)((const char*)(gbase) + (voff)[_i]), (PG8_LAS unsigned*)(lds + (bufoff) + ldsw + _i * 8192), 16, 0, 0); } while (0)
; #define PG8_LDA(dst, b, h) do { _Pragma("unroll") for (int m = 0; m < 4; ++m) _Pragma("unroll") for (int k = 0; k < 2; ++k) dst[m][k] = *(const PG8_LAS bf16x8*)(lds + PG8_SA(b, h) + aoff + m * 2048 + k * 1024); } while (0)
; #define PG8_LDB(dst, b, h) do { _Pragma("unroll") for (int n = 0; n < 2; ++n) _Pragma("unroll") for (int k = 0; k < 2; ++k) dst[n][k] = *(const PG8_LAS bf16x8*)(lds + PG8_SB(b, h) + boff + n * 2048 + k * 1024); } while (0)
; #define PG8_MMA(ai, bj, At, Bt) do { __builtin_amdgcn_s_setprio(1); _Pragma("unroll") for (int m = 0; m < 4; ++m) _Pragma("unroll") for (int n = 0; n < 2; ++n) _Pragma("unroll") for (int k = 0; k < 2; ++k) \
;         acc[ai][bj][m][n] = __builtin_amdgcn_mfma_f32_16x16x32_bf16(Bt[n][k], At[m][k], acc[ai][bj][m][n], 0, 0, 0); __builtin_amdgcn_s_setprio(0); } while (0)
; #define PG8_WAIT_V(n) asm volatile("s_waitcnt vmcnt(" #n ")" ::: "memory")
; #define PG8_WAIT_L(n) asm volatile("s_waitcnt lgkmcnt(" #n ")" ::: "memory")
; #define PG8_BAR __builtin_amdgcn_s_barrier()
; #define PG8_SCHED __builtin_amdgcn_sched_barrier(0)
; template <class Epi, class Sched, bool ALIGN_EPI = false, bool SP2 = false>
; __device__ __forceinline__ void gemm_phase(PG8_LAS unsigned char* lds, const Gemm g, const Sched& S, const Epi& E) {
;     ...
;             PG8_LDB(B0, 1, 0); PG8_LDB(B1, 1, 1); PG8_SCHED; PG8_LDA(At, 1, 0); PG8_STAGE(PG8_SA(0, 1), a2 + hstep, voffA);
;             PG8_WAIT_V(8); PG8_WAIT_L(0); PG8_BAR; PG8_MMA(0, 0, At, B0); PG8_MMA(0, 1, At, B1); PG8_BAR; PG8_SCHED;
;             PG8_LDA(At, 1, 1); PG8_STAGE(PG8_SB(1, 0), b3, voffB); PG8_STAGE(PG8_SB(1, 1), b3 + hstep, voffB); PG8_STAGE(PG8_SA(1, 0), a3, voffA);
;             PG8_WAIT_V(8); PG8_WAIT_L(0); PG8_BAR; PG8_MMA(1, 0, At, B0); PG8_MMA(1, 1, At, B1); PG8_BAR; PG8_SCHED;
	s_add_i32 s53, 0, 0x18000
	s_add_i32 s54, 0, 0x1c000
	v_add_u32_e32 v140, s53, v165
	v_add_u32_e32 v178, s54, v165
	ds_read_b128 v[128:131], v140
	ds_read_b128 v[132:135], v140 offset:1024
	ds_read_b128 v[136:139], v140 offset:2048
	ds_read_b128 v[140:143], v140 offset:3072
	ds_read_b128 v[160:163], v178
	ds_read_b128 v[170:173], v178 offset:1024
	ds_read_b128 v[174:177], v178 offset:2048
	ds_read_b128 v[178:181], v178 offset:3072
	s_add_u32 s18, s26, 0xb0000
	s_addc_u32 s19, s27, 0
	s_mov_b32 m0, s38
	ds_read_b128 v[182:185], v169 offset:32768
	ds_read_b128 v[186:189], v169 offset:33792
	ds_read_b128 v[190:193], v169 offset:34816
	ds_read_b128 v[194:197], v169 offset:35840
	ds_read_b128 v[198:201], v169 offset:36864
	ds_read_b128 v[202:205], v169 offset:37888
	ds_read_b128 v[206:209], v169 offset:38912
	ds_read_b128 v[210:213], v169 offset:39936
	global_load_lds_dwordx4 v150, s[18:19]
	s_mov_b32 m0, s39
	s_nop 0
	global_load_lds_dwordx4 v146, s[18:19]
	s_waitcnt vmcnt(8)
	s_waitcnt lgkmcnt(0)
	s_barrier
	v_mfma_f32_16x16x32_bf16 v[124:127], v[128:131], v[182:185], v[124:127]
	v_mfma_f32_16x16x32_bf16 v[124:127], v[132:135], v[186:189], v[124:127]
	v_mfma_f32_16x16x32_bf16 v[120:123], v[136:139], v[182:185], v[120:123]
	v_mfma_f32_16x16x32_bf16 v[120:123], v[140:143], v[186:189], v[120:123]
	v_mfma_f32_16x16x32_bf16 v[108:111], v[136:139], v[190:193], v[108:111]
	v_mfma_f32_16x16x32_bf16 v[108:111], v[140:143], v[194:197], v[108:111]
	v_mfma_f32_16x16x32_bf16 v[116:119], v[128:131], v[190:193], v[116:119]
	v_mfma_f32_16x16x32_bf16 v[116:119], v[132:135], v[194:197], v[116:119]
	v_mfma_f32_16x16x32_bf16 v[100:103], v[128:131], v[198:201], v[100:103]
	v_mfma_f32_16x16x32_bf16 v[100:103], v[132:135], v[202:205], v[100:103]
	v_mfma_f32_16x16x32_bf16 v[92:95], v[136:139], v[198:201], v[92:95]
	v_mfma_f32_16x16x32_bf16 v[92:95], v[140:143], v[202:205], v[92:95]
	v_mfma_f32_16x16x32_bf16 v[76:79], v[136:139], v[206:209], v[76:79]
	v_mfma_f32_16x16x32_bf16 v[76:79], v[140:143], v[210:213], v[76:79]
	v_mfma_f32_16x16x32_bf16 v[84:87], v[128:131], v[206:209], v[84:87]
	v_mfma_f32_16x16x32_bf16 v[84:87], v[132:135], v[210:213], v[84:87]
	v_mfma_f32_16x16x32_bf16 v[112:115], v[160:163], v[182:185], v[112:115]
	v_mfma_f32_16x16x32_bf16 v[112:115], v[170:173], v[186:189], v[112:115]
	v_mfma_f32_16x16x32_bf16 v[104:107], v[174:177], v[182:185], v[104:107]
	v_mfma_f32_16x16x32_bf16 v[104:107], v[178:181], v[186:189], v[104:107]
	v_mfma_f32_16x16x32_bf16 v[88:91], v[174:177], v[190:193], v[88:91]
	v_mfma_f32_16x16x32_bf16 v[88:91], v[178:181], v[194:197], v[88:91]
	v_mfma_f32_16x16x32_bf16 v[96:99], v[160:163], v[190:193], v[96:99]
	v_mfma_f32_16x16x32_bf16 v[96:99], v[170:173], v[194:197], v[96:99]
	v_mfma_f32_16x16x32_bf16 v[80:83], v[160:163], v[198:201], v[80:83]
	v_mfma_f32_16x16x32_bf16 v[80:83], v[170:173], v[202:205], v[80:83]
	v_mfma_f32_16x16x32_bf16 v[72:75], v[174:177], v[198:201], v[72:75]
	v_mfma_f32_16x16x32_bf16 v[72:75], v[178:181], v[202:205], v[72:75]
	v_mfma_f32_16x16x32_bf16 v[64:67], v[174:177], v[206:209], v[64:67]
	v_mfma_f32_16x16x32_bf16 v[64:67], v[178:181], v[210:213], v[64:67]
	v_mfma_f32_16x16x32_bf16 v[68:71], v[160:163], v[206:209], v[68:71]
	v_mfma_f32_16x16x32_bf16 v[68:71], v[170:173], v[210:213], v[68:71]
	s_barrier
	s_add_i32 s18, s53, s33
	s_add_u32 s98, s22, s12
	s_addc_u32 s99, s23, s13
	s_add_u32 s100, s26, s12
	s_addc_u32 s101, s27, s13
	s_mov_b32 m0, s18
	ds_read_b128 v[182:185], v169 offset:49152
	ds_read_b128 v[186:189], v169 offset:50176
	ds_read_b128 v[190:193], v169 offset:51200
	ds_read_b128 v[194:197], v169 offset:52224
	ds_read_b128 v[198:201], v169 offset:53248
	ds_read_b128 v[202:205], v169 offset:54272
	ds_read_b128 v[206:209], v169 offset:55296
	ds_read_b128 v[210:213], v169 offset:56320
	global_load_lds_dwordx4 v148, s[98:99]
	s_add_i32 m0, s18, 0x2000
	s_add_u32 s18, s22, 0xb0080
	v_lshl_add_u64 v[214:215], v[216:217], 0, s[12:13]
	s_addc_u32 s19, s23, 0
	s_add_i32 s22, s54, s33
	global_load_lds_dwordx4 v[214:215], off
	s_mov_b32 m0, s22
	s_nop 0
	global_load_lds_dwordx4 v148, s[18:19]
	s_add_i32 m0, s22, 0x2000
	s_nop 0
	global_load_lds_dwordx4 v144, s[18:19]
	s_mov_b32 m0, s41
	s_nop 0
	global_load_lds_dwordx4 v150, s[100:101]
	s_mov_b32 m0, s42
	s_nop 0
	global_load_lds_dwordx4 v146, s[100:101]
	s_waitcnt vmcnt(8)
	s_waitcnt lgkmcnt(0)
	s_barrier
	v_mfma_f32_16x16x32_bf16 v[60:63], v[128:131], v[182:185], v[60:63]
	v_mfma_f32_16x16x32_bf16 v[60:63], v[132:135], v[186:189], v[60:63]
	v_mfma_f32_16x16x32_bf16 v[56:59], v[136:139], v[182:185], v[56:59]
	v_mfma_f32_16x16x32_bf16 v[56:59], v[140:143], v[186:189], v[56:59]
	v_mfma_f32_16x16x32_bf16 v[44:47], v[136:139], v[190:193], v[44:47]
	v_mfma_f32_16x16x32_bf16 v[44:47], v[140:143], v[194:197], v[44:47]
	v_mfma_f32_16x16x32_bf16 v[48:51], v[128:131], v[190:193], v[48:51]
	v_mfma_f32_16x16x32_bf16 v[48:51], v[132:135], v[194:197], v[48:51]
	v_mfma_f32_16x16x32_bf16 v[36:39], v[128:131], v[198:201], v[36:39]
	v_mfma_f32_16x16x32_bf16 v[36:39], v[132:135], v[202:205], v[36:39]
	v_mfma_f32_16x16x32_bf16 v[28:31], v[136:139], v[198:201], v[28:31]
	v_mfma_f32_16x16x32_bf16 v[28:31], v[140:143], v[202:205], v[28:31]
	v_mfma_f32_16x16x32_bf16 v[12:15], v[136:139], v[206:209], v[12:15]
	v_mfma_f32_16x16x32_bf16 v[12:15], v[140:143], v[210:213], v[12:15]
	v_mfma_f32_16x16x32_bf16 v[20:23], v[128:131], v[206:209], v[20:23]
	v_mfma_f32_16x16x32_bf16 v[20:23], v[132:135], v[210:213], v[20:23]
	v_mfma_f32_16x16x32_bf16 v[52:55], v[160:163], v[182:185], v[52:55]
	v_mfma_f32_16x16x32_bf16 v[52:55], v[170:173], v[186:189], v[52:55]
	v_mfma_f32_16x16x32_bf16 v[40:43], v[174:177], v[182:185], v[40:43]
	v_mfma_f32_16x16x32_bf16 v[40:43], v[178:181], v[186:189], v[40:43]
	v_mfma_f32_16x16x32_bf16 v[24:27], v[174:177], v[190:193], v[24:27]
	v_mfma_f32_16x16x32_bf16 v[24:27], v[178:181], v[194:197], v[24:27]
	v_mfma_f32_16x16x32_bf16 v[32:35], v[160:163], v[190:193], v[32:35]
	v_mfma_f32_16x16x32_bf16 v[32:35], v[170:173], v[194:197], v[32:35]
	v_mfma_f32_16x16x32_bf16 v[16:19], v[160:163], v[198:201], v[16:19]
	v_mfma_f32_16x16x32_bf16 v[16:19], v[170:173], v[202:205], v[16:19]
	v_mfma_f32_16x16x32_bf16 v[8:11], v[174:177], v[198:201], v[8:11]
	v_mfma_f32_16x16x32_bf16 v[8:11], v[178:181], v[202:205], v[8:11]
	v_mfma_f32_16x16x32_bf16 v[0:3], v[174:177], v[206:209], v[0:3]
	v_mfma_f32_16x16x32_bf16 v[0:3], v[178:181], v[210:213], v[0:3]
	v_mfma_f32_16x16x32_bf16 v[4:7], v[160:163], v[206:209], v[4:7]
	v_mfma_f32_16x16x32_bf16 v[4:7], v[170:173], v[210:213], v[4:7]
	s_barrier
	s_add_i32 s52, s52, 2
	s_add_u32 s50, s50, 0x100
	s_addc_u32 s51, s51, 0
	s_cmp_gt_u32 s52, 41
	s_mov_b64 s[18:19], s[20:21]
	s_cbranch_scc0 .LBB0_1432
	s_and_b64 vcc, exec, s[14:15]
	s_cbranch_vccz .LBB0_1435
	s_barrier
